# v46
# speedup vs baseline: 1.0610x; 1.0035x over previous
; #define WAIT_V(n) asm volatile("s_waitcnt vmcnt(" #n ")" ::: "memory")
; #define WAIT_L(n) asm volatile("s_waitcnt lgkmcnt(" #n ")" ::: "memory")
; #define BAR __builtin_amdgcn_s_barrier()
; #define SCHED __builtin_amdgcn_sched_barrier(0)
; template <int EPI>
; __device__ __forceinline__ void gemm_tile(const Params& p, const bf16* __restrict__ A, const bf16* __restrict__ Bt, const int K,
;                                           const int nt, const int brow, const int bcol, int pm, int pn) {
;     ...
;   for (int t = 0; t < nt - 2; t += 2) {
;     LDB(B0, 0, 0); SCHED; LDA(At, 0, 0); STAGE(SA(1, 1), A, brow + HALF, t + 1);
;     WAIT_L(8); BAR; WAIT_L(0); MMA(0, 0, At, B0); BAR; SCHED;
;     LDB(B1, 0, 1); STAGE(SB(0, 0), Bt, bcol, t + 2);
;     BAR; WAIT_L(0); MMA(0, 1, At, B1); BAR;
;     LDA(At, 0, 1); STAGE(SA(0, 0), A, brow, t + 2);
;     BAR; WAIT_L(0); MMA(1, 0, At, B0); BAR; SCHED;
;     STAGE(SB(0, 1), Bt, bcol + HALF, t + 2);
;     WAIT_V(6); BAR; MMA(1, 1, At, B1); BAR;
;     LDB(B0, 1, 0); SCHED; LDA(At, 1, 0); STAGE(SA(0, 1), A, brow + HALF, t + 2);
;     WAIT_L(8); BAR; WAIT_L(0); MMA(0, 0, At, B0); BAR; SCHED;
;     LDB(B1, 1, 1); STAGE(SB(1, 0), Bt, bcol, t + 3);
;     BAR; WAIT_L(0); MMA(0, 1, At, B1); BAR;
;     LDA(At, 1, 1); STAGE(SA(1, 0), A, brow, t + 3);
;     BAR; WAIT_L(0); MMA(1, 0, At, B0); BAR; SCHED;
;     STAGE(SB(1, 1), Bt, bcol + HALF, t + 3);
;     WAIT_V(6); BAR; MMA(1, 1, At, B1); BAR;
;   }
.LBB0_415:
	ds_read_b128 v[162:165], v160
	ds_read_b128 v[166:169], v160 offset:1024
	ds_read_b128 v[170:173], v160 offset:2048
	ds_read_b128 v[174:177], v160 offset:3072
	s_mov_b32 m0, s99
	ds_read_b128 v[178:181], v136
	ds_read_b128 v[182:185], v136 offset:1024
	ds_read_b128 v[186:189], v135
	ds_read_b128 v[190:193], v135 offset:1024
	ds_read_b128 v[194:197], v131
	ds_read_b128 v[198:201], v131 offset:1024
	ds_read_b128 v[202:205], v130
	ds_read_b128 v[208:211], v130 offset:1024
	global_load_lds_dwordx4 v[246:247], off
	s_mov_b32 m0, s98
	s_nop 0
	global_load_lds_dwordx4 v[244:245], off
	s_waitcnt lgkmcnt(8)
	s_setprio 1
	s_barrier
	s_waitcnt lgkmcnt(0)
	v_mfma_f32_16x16x32_bf16 v[124:127], v[178:181], v[162:165], v[124:127]
	v_mfma_f32_16x16x32_bf16 v[120:123], v[178:181], v[170:173], v[120:123]
	v_mfma_f32_16x16x32_bf16 v[116:119], v[186:189], v[162:165], v[116:119]
	v_mfma_f32_16x16x32_bf16 v[112:115], v[186:189], v[170:173], v[112:115]
	v_mfma_f32_16x16x32_bf16 v[108:111], v[194:197], v[162:165], v[108:111]
	v_mfma_f32_16x16x32_bf16 v[104:107], v[194:197], v[170:173], v[104:107]
	v_mfma_f32_16x16x32_bf16 v[100:103], v[202:205], v[162:165], v[100:103]
	v_mfma_f32_16x16x32_bf16 v[96:99], v[202:205], v[170:173], v[96:99]
	v_mfma_f32_16x16x32_bf16 v[124:127], v[182:185], v[166:169], v[124:127]
	v_mfma_f32_16x16x32_bf16 v[120:123], v[182:185], v[174:177], v[120:123]
	v_mfma_f32_16x16x32_bf16 v[116:119], v[190:193], v[166:169], v[116:119]
	v_mfma_f32_16x16x32_bf16 v[112:115], v[190:193], v[174:177], v[112:115]
	v_mfma_f32_16x16x32_bf16 v[108:111], v[198:201], v[166:169], v[108:111]
	v_mfma_f32_16x16x32_bf16 v[104:107], v[198:201], v[174:177], v[104:107]
	v_mfma_f32_16x16x32_bf16 v[100:103], v[208:211], v[166:169], v[100:103]
	v_mfma_f32_16x16x32_bf16 v[96:99], v[208:211], v[174:177], v[96:99]
	s_barrier
	s_setprio 0
	v_lshl_add_u64 v[230:231], s[36:37], 0, v[128:129]
	s_mov_b64 s[40:41], 0x100
	v_readfirstlane_b32 s31, v134
	v_lshl_add_u64 v[232:233], v[230:231], 0, s[40:41]
	s_mov_b32 m0, s31
	s_mov_b64 s[40:41], 0x40100
	v_readfirstlane_b32 s31, v137
	ds_read_b128 v[212:215], v156
	ds_read_b128 v[216:219], v156 offset:1024
	ds_read_b128 v[220:223], v156 offset:2048
	ds_read_b128 v[224:227], v156 offset:3072
	global_load_lds_dwordx4 v[232:233], off
	v_lshl_add_u64 v[232:233], v[230:231], 0, s[40:41]
	s_mov_b32 m0, s31
	s_nop 0
	global_load_lds_dwordx4 v[232:233], off
	s_mov_b64 s[40:41], 0x6202100
	v_lshl_add_u64 v[252:253], v[228:229], 0, s[40:41]
	s_mov_b64 s[40:41], 0x6242100
	v_lshl_add_u64 v[254:255], v[228:229], 0, s[40:41]
	v_lshl_add_u64 v[232:233], v[228:229], 0, s[40:41]
	v_readfirstlane_b32 s31, v138
	s_mov_b32 m0, s31
	s_setprio 1
	s_barrier
	s_waitcnt lgkmcnt(0)
	v_mfma_f32_16x16x32_bf16 v[92:95], v[178:181], v[212:215], v[92:95]
	v_mfma_f32_16x16x32_bf16 v[88:91], v[178:181], v[220:223], v[88:91]
	v_mfma_f32_16x16x32_bf16 v[84:87], v[186:189], v[212:215], v[84:87]
	v_mfma_f32_16x16x32_bf16 v[80:83], v[186:189], v[220:223], v[80:83]
	v_mfma_f32_16x16x32_bf16 v[76:79], v[194:197], v[212:215], v[76:79]
	v_mfma_f32_16x16x32_bf16 v[72:75], v[194:197], v[220:223], v[72:75]
	v_mfma_f32_16x16x32_bf16 v[68:71], v[202:205], v[212:215], v[68:71]
	v_mfma_f32_16x16x32_bf16 v[64:67], v[202:205], v[220:223], v[64:67]
	v_mfma_f32_16x16x32_bf16 v[92:95], v[182:185], v[216:219], v[92:95]
	v_mfma_f32_16x16x32_bf16 v[88:91], v[182:185], v[224:227], v[88:91]
	v_mfma_f32_16x16x32_bf16 v[84:87], v[190:193], v[216:219], v[84:87]
	v_mfma_f32_16x16x32_bf16 v[80:83], v[190:193], v[224:227], v[80:83]
	v_mfma_f32_16x16x32_bf16 v[76:79], v[198:201], v[216:219], v[76:79]
	v_mfma_f32_16x16x32_bf16 v[72:75], v[198:201], v[224:227], v[72:75]
	v_mfma_f32_16x16x32_bf16 v[68:71], v[208:211], v[216:219], v[68:71]
	v_mfma_f32_16x16x32_bf16 v[64:67], v[208:211], v[224:227], v[64:67]
	s_barrier
	s_setprio 0
	ds_read_b128 v[178:181], v136 offset:16384
	ds_read_b128 v[182:185], v136 offset:17408
	ds_read_b128 v[186:189], v135 offset:16384
	ds_read_b128 v[190:193], v135 offset:17408
	ds_read_b128 v[194:197], v131 offset:16384
	ds_read_b128 v[198:201], v131 offset:17408
	ds_read_b128 v[202:205], v130 offset:16384
	ds_read_b128 v[208:211], v130 offset:17408
	global_load_lds_dwordx4 v[252:253], off
	v_readfirstlane_b32 s31, v140
	s_mov_b32 m0, s31
	s_nop 0
	global_load_lds_dwordx4 v[254:255], off
	s_setprio 1
	s_barrier
	s_waitcnt lgkmcnt(0)
	v_mfma_f32_16x16x32_bf16 v[60:63], v[178:181], v[162:165], v[60:63]
	v_mfma_f32_16x16x32_bf16 v[56:59], v[178:181], v[170:173], v[56:59]
	v_mfma_f32_16x16x32_bf16 v[52:55], v[186:189], v[162:165], v[52:55]
	v_mfma_f32_16x16x32_bf16 v[48:51], v[186:189], v[170:173], v[48:51]
	v_mfma_f32_16x16x32_bf16 v[44:47], v[194:197], v[162:165], v[44:47]
	v_mfma_f32_16x16x32_bf16 v[40:43], v[194:197], v[170:173], v[40:43]
	v_mfma_f32_16x16x32_bf16 v[36:39], v[202:205], v[162:165], v[36:39]
	v_mfma_f32_16x16x32_bf16 v[32:35], v[202:205], v[170:173], v[32:35]
	v_mfma_f32_16x16x32_bf16 v[60:63], v[182:185], v[166:169], v[60:63]
	v_mfma_f32_16x16x32_bf16 v[56:59], v[182:185], v[174:177], v[56:59]
	v_mfma_f32_16x16x32_bf16 v[52:55], v[190:193], v[166:169], v[52:55]
	v_mfma_f32_16x16x32_bf16 v[48:51], v[190:193], v[174:177], v[48:51]
	v_mfma_f32_16x16x32_bf16 v[44:47], v[198:201], v[166:169], v[44:47]
	v_mfma_f32_16x16x32_bf16 v[40:43], v[198:201], v[174:177], v[40:43]
	v_mfma_f32_16x16x32_bf16 v[36:39], v[208:211], v[166:169], v[36:39]
	v_mfma_f32_16x16x32_bf16 v[32:35], v[208:211], v[174:177], v[32:35]
	s_barrier
; #define WAIT_V(n) asm volatile("s_waitcnt vmcnt(" #n ")" ::: "memory")
; #define WAIT_L(n) asm volatile("s_waitcnt lgkmcnt(" #n ")" ::: "memory")
; #define BAR __builtin_amdgcn_s_barrier()
; #define SCHED __builtin_amdgcn_sched_barrier(0)
; template <int EPI>
; __device__ __forceinline__ void gemm_tile(const Params& p, const bf16* __restrict__ A, const bf16* __restrict__ Bt, const int K,
;                                           const int nt, const int brow, const int bcol, int pm, int pn) {
;     ...
;   for (int t = 0; t < nt - 2; t += 2) {
;     LDB(B0, 0, 0); SCHED; LDA(At, 0, 0); STAGE(SA(1, 1), A, brow + HALF, t + 1);
;     WAIT_L(8); BAR; WAIT_L(0); MMA(0, 0, At, B0); BAR; SCHED;
;     LDB(B1, 0, 1); STAGE(SB(0, 0), Bt, bcol, t + 2);
;     BAR; WAIT_L(0); MMA(0, 1, At, B1); BAR;
;     LDA(At, 0, 1); STAGE(SA(0, 0), A, brow, t + 2);
;     BAR; WAIT_L(0); MMA(1, 0, At, B0); BAR; SCHED;
;     STAGE(SB(0, 1), Bt, bcol + HALF, t + 2);
;     WAIT_V(6); BAR; MMA(1, 1, At, B1); BAR;
;     LDB(B0, 1, 0); SCHED; LDA(At, 1, 0); STAGE(SA(0, 1), A, brow + HALF, t + 2);
;     WAIT_L(8); BAR; WAIT_L(0); MMA(0, 0, At, B0); BAR; SCHED;
;     LDB(B1, 1, 1); STAGE(SB(1, 0), Bt, bcol, t + 3);
;     BAR; WAIT_L(0); MMA(0, 1, At, B1); BAR;
;     LDA(At, 1, 1); STAGE(SA(1, 0), A, brow, t + 3);
;     BAR; WAIT_L(0); MMA(1, 0, At, B0); BAR; SCHED;
;     STAGE(SB(1, 1), Bt, bcol + HALF, t + 3);
;     WAIT_V(6); BAR; MMA(1, 1, At, B1); BAR;
;   }
	s_setprio 0
	s_add_i32 s9, s9, 2
	s_add_u32 s38, s38, 0x100
	s_addc_u32 s39, s39, 0
	s_add_u32 s36, s36, 0x100
	s_addc_u32 s37, s37, 0
	s_mov_b64 s[40:41], 0x80100
	v_readfirstlane_b32 s31, v141
	v_lshl_add_u64 v[162:163], v[230:231], 0, s[40:41]
	s_mov_b32 m0, s31
	s_mov_b64 s[40:41], 0xc0100
	v_readfirstlane_b32 s31, v147
	global_load_lds_dwordx4 v[162:163], off
	v_lshl_add_u64 v[162:163], v[230:231], 0, s[40:41]
	s_mov_b32 m0, s31
	s_nop 0
	global_load_lds_dwordx4 v[162:163], off
	s_mov_b64 s[40:41], 0x6282100
	v_lshl_add_u64 v[248:249], v[228:229], 0, s[40:41]
	s_mov_b64 s[40:41], 0x62c2100
	v_lshl_add_u64 v[250:251], v[228:229], 0, s[40:41]
	s_waitcnt vmcnt(6)
	s_setprio 1
	s_barrier
	v_mfma_f32_16x16x32_bf16 v[28:31], v[178:181], v[212:215], v[28:31]
	v_mfma_f32_16x16x32_bf16 v[24:27], v[178:181], v[220:223], v[24:27]
	v_mfma_f32_16x16x32_bf16 v[20:23], v[186:189], v[212:215], v[20:23]
	v_mfma_f32_16x16x32_bf16 v[16:19], v[186:189], v[220:223], v[16:19]
	v_mfma_f32_16x16x32_bf16 v[12:15], v[194:197], v[212:215], v[12:15]
	v_mfma_f32_16x16x32_bf16 v[8:11], v[194:197], v[220:223], v[8:11]
	v_mfma_f32_16x16x32_bf16 v[4:7], v[202:205], v[212:215], v[4:7]
	v_mfma_f32_16x16x32_bf16 v[0:3], v[202:205], v[220:223], v[0:3]
	v_mfma_f32_16x16x32_bf16 v[28:31], v[182:185], v[216:219], v[28:31]
	v_mfma_f32_16x16x32_bf16 v[24:27], v[182:185], v[224:227], v[24:27]
	v_mfma_f32_16x16x32_bf16 v[20:23], v[190:193], v[216:219], v[20:23]
	v_mfma_f32_16x16x32_bf16 v[16:19], v[190:193], v[224:227], v[16:19]
	v_mfma_f32_16x16x32_bf16 v[12:15], v[198:201], v[216:219], v[12:15]
	v_mfma_f32_16x16x32_bf16 v[8:11], v[198:201], v[224:227], v[8:11]
	v_mfma_f32_16x16x32_bf16 v[4:7], v[208:211], v[216:219], v[4:7]
	v_mfma_f32_16x16x32_bf16 v[0:3], v[208:211], v[224:227], v[0:3]
	s_barrier
	s_setprio 0
	ds_read_b128 v[162:165], v149
	ds_read_b128 v[166:169], v149 offset:1024
	ds_read_b128 v[170:173], v149 offset:2048
	ds_read_b128 v[174:177], v149 offset:3072
	s_mov_b32 m0, s100
	ds_read_b128 v[178:181], v136 offset:32768
	ds_read_b128 v[182:185], v136 offset:33792
	ds_read_b128 v[186:189], v135 offset:32768
	ds_read_b128 v[190:193], v135 offset:33792
	ds_read_b128 v[194:197], v131 offset:32768
	ds_read_b128 v[198:201], v131 offset:33792
	ds_read_b128 v[202:205], v130 offset:32768
	ds_read_b128 v[208:211], v130 offset:33792
	global_load_lds_dwordx4 v[248:249], off
	s_mov_b32 m0, s101
	s_nop 0
	global_load_lds_dwordx4 v[250:251], off
	s_waitcnt lgkmcnt(8)
	s_setprio 1
	s_barrier
	s_waitcnt lgkmcnt(0)
	v_mfma_f32_16x16x32_bf16 v[124:127], v[178:181], v[162:165], v[124:127]
	v_mfma_f32_16x16x32_bf16 v[120:123], v[178:181], v[170:173], v[120:123]
	v_mfma_f32_16x16x32_bf16 v[116:119], v[186:189], v[162:165], v[116:119]
	v_mfma_f32_16x16x32_bf16 v[112:115], v[186:189], v[170:173], v[112:115]
	v_mfma_f32_16x16x32_bf16 v[108:111], v[194:197], v[162:165], v[108:111]
	v_mfma_f32_16x16x32_bf16 v[104:107], v[194:197], v[170:173], v[104:107]
	v_mfma_f32_16x16x32_bf16 v[100:103], v[202:205], v[162:165], v[100:103]
	v_mfma_f32_16x16x32_bf16 v[96:99], v[202:205], v[170:173], v[96:99]
	v_mfma_f32_16x16x32_bf16 v[124:127], v[182:185], v[166:169], v[124:127]
	v_mfma_f32_16x16x32_bf16 v[120:123], v[182:185], v[174:177], v[120:123]
	v_mfma_f32_16x16x32_bf16 v[116:119], v[190:193], v[166:169], v[116:119]
	v_mfma_f32_16x16x32_bf16 v[112:115], v[190:193], v[174:177], v[112:115]
	v_mfma_f32_16x16x32_bf16 v[108:111], v[198:201], v[166:169], v[108:111]
	v_mfma_f32_16x16x32_bf16 v[104:107], v[198:201], v[174:177], v[104:107]
	v_mfma_f32_16x16x32_bf16 v[100:103], v[208:211], v[166:169], v[100:103]
	v_mfma_f32_16x16x32_bf16 v[96:99], v[208:211], v[174:177], v[96:99]
	s_barrier
	s_setprio 0
	s_mov_b64 s[40:41], 0x180
	v_readfirstlane_b32 s31, v151
	v_lshl_add_u64 v[232:233], v[230:231], 0, s[40:41]
	s_mov_b32 m0, s31
	s_mov_b64 s[40:41], 0x40180
	v_readfirstlane_b32 s31, v152
	ds_read_b128 v[212:215], v139
	ds_read_b128 v[216:219], v139 offset:1024
	ds_read_b128 v[220:223], v139 offset:2048
	ds_read_b128 v[224:227], v139 offset:3072
	global_load_lds_dwordx4 v[232:233], off
	v_lshl_add_u64 v[232:233], v[230:231], 0, s[40:41]
	s_mov_b32 m0, s31
	s_nop 0
	global_load_lds_dwordx4 v[232:233], off
	s_mov_b64 s[40:41], 0x6202180
	v_lshl_add_u64 v[252:253], v[228:229], 0, s[40:41]
	v_lshl_add_u64 v[232:233], v[228:229], 0, s[40:41]
	s_mov_b64 s[40:41], 0x6242180
	v_lshl_add_u64 v[254:255], v[228:229], 0, s[40:41]
	v_lshl_add_u64 v[228:229], v[228:229], 0, s[40:41]
	v_readfirstlane_b32 s31, v153
	s_mov_b32 m0, s31
	s_setprio 1
	s_barrier
	s_waitcnt lgkmcnt(0)
	v_mfma_f32_16x16x32_bf16 v[92:95], v[178:181], v[212:215], v[92:95]
	v_mfma_f32_16x16x32_bf16 v[88:91], v[178:181], v[220:223], v[88:91]
	v_mfma_f32_16x16x32_bf16 v[84:87], v[186:189], v[212:215], v[84:87]
	v_mfma_f32_16x16x32_bf16 v[80:83], v[186:189], v[220:223], v[80:83]
	v_mfma_f32_16x16x32_bf16 v[76:79], v[194:197], v[212:215], v[76:79]
	v_mfma_f32_16x16x32_bf16 v[72:75], v[194:197], v[220:223], v[72:75]
	v_mfma_f32_16x16x32_bf16 v[68:71], v[202:205], v[212:215], v[68:71]
	v_mfma_f32_16x16x32_bf16 v[64:67], v[202:205], v[220:223], v[64:67]
	v_mfma_f32_16x16x32_bf16 v[92:95], v[182:185], v[216:219], v[92:95]
	v_mfma_f32_16x16x32_bf16 v[88:91], v[182:185], v[224:227], v[88:91]
	v_mfma_f32_16x16x32_bf16 v[84:87], v[190:193], v[216:219], v[84:87]
	v_mfma_f32_16x16x32_bf16 v[80:83], v[190:193], v[224:227], v[80:83]
	v_mfma_f32_16x16x32_bf16 v[76:79], v[198:201], v[216:219], v[76:79]
	v_mfma_f32_16x16x32_bf16 v[72:75], v[198:201], v[224:227], v[72:75]
	v_mfma_f32_16x16x32_bf16 v[68:71], v[208:211], v[216:219], v[68:71]
	v_mfma_f32_16x16x32_bf16 v[64:67], v[208:211], v[224:227], v[64:67]
	s_barrier
; #define WAIT_V(n) asm volatile("s_waitcnt vmcnt(" #n ")" ::: "memory")
; #define WAIT_L(n) asm volatile("s_waitcnt lgkmcnt(" #n ")" ::: "memory")
; #define BAR __builtin_amdgcn_s_barrier()
; #define SCHED __builtin_amdgcn_sched_barrier(0)
; template <int EPI>
; __device__ __forceinline__ void gemm_tile(const Params& p, const bf16* __restrict__ A, const bf16* __restrict__ Bt, const int K,
;                                           const int nt, const int brow, const int bcol, int pm, int pn) {
;     ...
;   for (int t = 0; t < nt - 2; t += 2) {
;     LDB(B0, 0, 0); SCHED; LDA(At, 0, 0); STAGE(SA(1, 1), A, brow + HALF, t + 1);
;     WAIT_L(8); BAR; WAIT_L(0); MMA(0, 0, At, B0); BAR; SCHED;
;     LDB(B1, 0, 1); STAGE(SB(0, 0), Bt, bcol, t + 2);
;     BAR; WAIT_L(0); MMA(0, 1, At, B1); BAR;
;     LDA(At, 0, 1); STAGE(SA(0, 0), A, brow, t + 2);
;     BAR; WAIT_L(0); MMA(1, 0, At, B0); BAR; SCHED;
;     STAGE(SB(0, 1), Bt, bcol + HALF, t + 2);
;     WAIT_V(6); BAR; MMA(1, 1, At, B1); BAR;
;     LDB(B0, 1, 0); SCHED; LDA(At, 1, 0); STAGE(SA(0, 1), A, brow + HALF, t + 2);
;     WAIT_L(8); BAR; WAIT_L(0); MMA(0, 0, At, B0); BAR; SCHED;
;     LDB(B1, 1, 1); STAGE(SB(1, 0), Bt, bcol, t + 3);
;     BAR; WAIT_L(0); MMA(0, 1, At, B1); BAR;
;     LDA(At, 1, 1); STAGE(SA(1, 0), A, brow, t + 3);
;     BAR; WAIT_L(0); MMA(1, 0, At, B0); BAR; SCHED;
;     STAGE(SB(1, 1), Bt, bcol + HALF, t + 3);
;     WAIT_V(6); BAR; MMA(1, 1, At, B1); BAR;
;   }
;   { LDB(B0, 0, 0); LDA(At, 0, 0); STAGE(SA(1, 1), A, brow + HALF, nt - 1);
;     BAR; WAIT_L(0); MMA(0, 0, At, B0); BAR;
;     LDB(B1, 0, 1); BAR; WAIT_L(0); MMA(0, 1, At, B1); BAR;
;     LDA(At, 0, 1); WAIT_V(4); BAR; WAIT_L(0); MMA(1, 0, At, B0); MMA(1, 1, At, B1); BAR; }
	s_setprio 0
	ds_read_b128 v[178:181], v136 offset:49152
	ds_read_b128 v[182:185], v136 offset:50176
	ds_read_b128 v[186:189], v135 offset:49152
	ds_read_b128 v[190:193], v135 offset:50176
	ds_read_b128 v[194:197], v131 offset:49152
	ds_read_b128 v[198:201], v131 offset:50176
	ds_read_b128 v[202:205], v130 offset:49152
	ds_read_b128 v[208:211], v130 offset:50176
	global_load_lds_dwordx4 v[252:253], off
	v_readfirstlane_b32 s31, v154
	s_mov_b32 m0, s31
	s_nop 0
	global_load_lds_dwordx4 v[254:255], off
	s_setprio 1
	s_barrier
	s_waitcnt lgkmcnt(0)
	v_mfma_f32_16x16x32_bf16 v[60:63], v[178:181], v[162:165], v[60:63]
	v_mfma_f32_16x16x32_bf16 v[56:59], v[178:181], v[170:173], v[56:59]
	v_mfma_f32_16x16x32_bf16 v[52:55], v[186:189], v[162:165], v[52:55]
	v_mfma_f32_16x16x32_bf16 v[48:51], v[186:189], v[170:173], v[48:51]
	v_mfma_f32_16x16x32_bf16 v[44:47], v[194:197], v[162:165], v[44:47]
	v_mfma_f32_16x16x32_bf16 v[40:43], v[194:197], v[170:173], v[40:43]
	v_mfma_f32_16x16x32_bf16 v[36:39], v[202:205], v[162:165], v[36:39]
	v_mfma_f32_16x16x32_bf16 v[32:35], v[202:205], v[170:173], v[32:35]
	v_mfma_f32_16x16x32_bf16 v[60:63], v[182:185], v[166:169], v[60:63]
	v_mfma_f32_16x16x32_bf16 v[56:59], v[182:185], v[174:177], v[56:59]
	v_mfma_f32_16x16x32_bf16 v[52:55], v[190:193], v[166:169], v[52:55]
	v_mfma_f32_16x16x32_bf16 v[48:51], v[190:193], v[174:177], v[48:51]
	v_mfma_f32_16x16x32_bf16 v[44:47], v[198:201], v[166:169], v[44:47]
	v_mfma_f32_16x16x32_bf16 v[40:43], v[198:201], v[174:177], v[40:43]
	v_mfma_f32_16x16x32_bf16 v[36:39], v[208:211], v[166:169], v[36:39]
	v_mfma_f32_16x16x32_bf16 v[32:35], v[208:211], v[174:177], v[32:35]
	s_barrier
	s_setprio 0
	s_mov_b64 s[40:41], 0x80180
	v_readfirstlane_b32 s31, v155
	v_lshl_add_u64 v[162:163], v[230:231], 0, s[40:41]
	s_mov_b32 m0, s31
	s_mov_b64 s[40:41], 0xc0180
	v_readfirstlane_b32 s31, v157
	global_load_lds_dwordx4 v[162:163], off
	v_lshl_add_u64 v[162:163], v[230:231], 0, s[40:41]
	s_mov_b32 m0, s31
	s_nop 0
	global_load_lds_dwordx4 v[162:163], off
	v_lshl_add_u64 v[228:229], s[38:39], 0, v[128:129]
	s_mov_b64 s[40:41], 0x6282080
	v_lshl_add_u64 v[246:247], v[228:229], 0, s[40:41]
	s_mov_b64 s[40:41], 0x62c2080
	v_lshl_add_u64 v[244:245], v[228:229], 0, s[40:41]
	s_waitcnt vmcnt(6)
	s_setprio 1
	s_barrier
	v_mfma_f32_16x16x32_bf16 v[28:31], v[178:181], v[212:215], v[28:31]
	v_mfma_f32_16x16x32_bf16 v[24:27], v[178:181], v[220:223], v[24:27]
	v_mfma_f32_16x16x32_bf16 v[20:23], v[186:189], v[212:215], v[20:23]
	v_mfma_f32_16x16x32_bf16 v[16:19], v[186:189], v[220:223], v[16:19]
	v_mfma_f32_16x16x32_bf16 v[12:15], v[194:197], v[212:215], v[12:15]
	v_mfma_f32_16x16x32_bf16 v[8:11], v[194:197], v[220:223], v[8:11]
	v_mfma_f32_16x16x32_bf16 v[4:7], v[202:205], v[212:215], v[4:7]
	v_mfma_f32_16x16x32_bf16 v[0:3], v[202:205], v[220:223], v[0:3]
	v_mfma_f32_16x16x32_bf16 v[28:31], v[182:185], v[216:219], v[28:31]
	v_mfma_f32_16x16x32_bf16 v[24:27], v[182:185], v[224:227], v[24:27]
	v_mfma_f32_16x16x32_bf16 v[20:23], v[190:193], v[216:219], v[20:23]
	v_mfma_f32_16x16x32_bf16 v[16:19], v[190:193], v[224:227], v[16:19]
	v_mfma_f32_16x16x32_bf16 v[12:15], v[198:201], v[216:219], v[12:15]
	v_mfma_f32_16x16x32_bf16 v[8:11], v[198:201], v[224:227], v[8:11]
	v_mfma_f32_16x16x32_bf16 v[4:7], v[208:211], v[216:219], v[4:7]
	v_mfma_f32_16x16x32_bf16 v[0:3], v[208:211], v[224:227], v[0:3]
	s_barrier
	s_setprio 0
	s_cmp_lt_u32 s9, 28
	s_cbranch_scc1 .LBB0_415
	s_add_u32 s6, s60, s6
	s_addc_u32 s7, s61, s7
	v_lshl_add_u64 v[128:129], s[6:7], 0, v[132:133]
	v_readfirstlane_b32 s6, v159
	s_mov_b32 m0, s6
	s_add_u32 s6, s60, s34
	v_lshl_add_u64 v[128:129], v[128:129], 0, s[28:29]
	s_addc_u32 s7, s61, s35
	ds_read_b128 v[150:153], v160
	ds_read_b128 v[162:165], v160 offset:1024
	ds_read_b128 v[166:169], v160 offset:2048
	ds_read_b128 v[170:173], v160 offset:3072
	ds_read_b128 v[174:177], v136
	ds_read_b128 v[178:181], v136 offset:1024
	ds_read_b128 v[182:185], v135
	ds_read_b128 v[186:189], v135 offset:1024
	ds_read_b128 v[190:193], v131
	ds_read_b128 v[194:197], v131 offset:1024
	ds_read_b128 v[198:201], v130
	ds_read_b128 v[202:205], v130 offset:1024
	global_load_lds_dwordx4 v[128:129], off
	v_lshl_add_u64 v[128:129], s[6:7], 0, v[132:133]
	v_readfirstlane_b32 s6, v158
	v_lshl_add_u64 v[128:129], v[128:129], 0, s[28:29]
	s_mov_b32 m0, s6
	s_nop 0
	global_load_lds_dwordx4 v[128:129], off
	s_setprio 1
	s_barrier
	s_waitcnt lgkmcnt(0)
	v_mfma_f32_16x16x32_bf16 v[124:127], v[174:177], v[150:153], v[124:127]
	v_mfma_f32_16x16x32_bf16 v[120:123], v[174:177], v[166:169], v[120:123]
	v_mfma_f32_16x16x32_bf16 v[116:119], v[182:185], v[150:153], v[116:119]
	v_mfma_f32_16x16x32_bf16 v[108:111], v[190:193], v[150:153], v[108:111]
	v_mfma_f32_16x16x32_bf16 v[124:127], v[178:181], v[162:165], v[124:127]
	v_mfma_f32_16x16x32_bf16 v[120:123], v[178:181], v[170:173], v[120:123]
	v_mfma_f32_16x16x32_bf16 v[116:119], v[186:189], v[162:165], v[116:119]
	v_mfma_f32_16x16x32_bf16 v[112:115], v[182:185], v[166:169], v[112:115]
	v_mfma_f32_16x16x32_bf16 v[108:111], v[194:197], v[162:165], v[108:111]
	v_mfma_f32_16x16x32_bf16 v[104:107], v[190:193], v[166:169], v[104:107]
	v_mfma_f32_16x16x32_bf16 v[100:103], v[198:201], v[150:153], v[100:103]
	v_mfma_f32_16x16x32_bf16 v[96:99], v[198:201], v[166:169], v[96:99]
	v_mfma_f32_16x16x32_bf16 v[158:161], v[186:189], v[170:173], v[112:115]
	v_mfma_f32_16x16x32_bf16 v[208:211], v[194:197], v[170:173], v[104:107]
	v_mfma_f32_16x16x32_bf16 v[212:215], v[202:205], v[162:165], v[100:103]
	v_mfma_f32_16x16x32_bf16 v[216:219], v[202:205], v[170:173], v[96:99]
	s_barrier
; #define WAIT_V(n) asm volatile("s_waitcnt vmcnt(" #n ")" ::: "memory")
; #define WAIT_L(n) asm volatile("s_waitcnt lgkmcnt(" #n ")" ::: "memory")
; #define BAR __builtin_amdgcn_s_barrier()
; template <int EPI>
; __device__ __forceinline__ void gemm_tile(const Params& p, const bf16* __restrict__ A, const bf16* __restrict__ Bt, const int K,
;                                           const int nt, const int brow, const int bcol, int pm, int pn) {
;     ...
;   { LDB(B0, 0, 0); LDA(At, 0, 0); STAGE(SA(1, 1), A, brow + HALF, nt - 1);
;     BAR; WAIT_L(0); MMA(0, 0, At, B0); BAR;
;     LDB(B1, 0, 1); BAR; WAIT_L(0); MMA(0, 1, At, B1); BAR;
;     LDA(At, 0, 1); WAIT_V(4); BAR; WAIT_L(0); MMA(1, 0, At, B0); MMA(1, 1, At, B1); BAR; }
;   { LDB(B0, 1, 0); LDA(At, 1, 0); WAIT_V(2); BAR; WAIT_L(0); MMA(0, 0, At, B0); BAR;
;     LDB(B1, 1, 1); WAIT_V(0); BAR; WAIT_L(0); MMA(0, 1, At, B1); BAR;
;     LDA(At, 1, 1); BAR; WAIT_L(0); MMA(1, 0, At, B0); MMA(1, 1, At, B1); BAR; }
	s_setprio 0
	s_nop 1
	ds_read_b128 v[96:99], v156
	ds_read_b128 v[100:103], v156 offset:1024
	ds_read_b128 v[104:107], v156 offset:2048
	ds_read_b128 v[112:115], v156 offset:3072
	s_setprio 1
	s_barrier
	s_waitcnt lgkmcnt(0)
	v_mfma_f32_16x16x32_bf16 v[92:95], v[174:177], v[96:99], v[92:95]
	v_mfma_f32_16x16x32_bf16 v[88:91], v[174:177], v[104:107], v[88:91]
	v_mfma_f32_16x16x32_bf16 v[84:87], v[182:185], v[96:99], v[84:87]
	v_mfma_f32_16x16x32_bf16 v[76:79], v[190:193], v[96:99], v[76:79]
	v_mfma_f32_16x16x32_bf16 v[92:95], v[178:181], v[100:103], v[92:95]
	v_mfma_f32_16x16x32_bf16 v[88:91], v[178:181], v[112:115], v[88:91]
	v_mfma_f32_16x16x32_bf16 v[84:87], v[186:189], v[100:103], v[84:87]
	v_mfma_f32_16x16x32_bf16 v[80:83], v[182:185], v[104:107], v[80:83]
	v_mfma_f32_16x16x32_bf16 v[76:79], v[194:197], v[100:103], v[76:79]
	v_mfma_f32_16x16x32_bf16 v[72:75], v[190:193], v[104:107], v[72:75]
	v_mfma_f32_16x16x32_bf16 v[68:71], v[198:201], v[96:99], v[68:71]
	v_mfma_f32_16x16x32_bf16 v[64:67], v[198:201], v[104:107], v[64:67]
	v_mfma_f32_16x16x32_bf16 v[154:157], v[186:189], v[112:115], v[80:83]
	v_mfma_f32_16x16x32_bf16 v[174:177], v[194:197], v[112:115], v[72:75]
	v_mfma_f32_16x16x32_bf16 v[178:181], v[202:205], v[100:103], v[68:71]
	v_mfma_f32_16x16x32_bf16 v[182:185], v[202:205], v[112:115], v[64:67]
	s_barrier
	s_setprio 0
	s_nop 1
	ds_read_b128 v[64:67], v136 offset:16384
	ds_read_b128 v[68:71], v136 offset:17408
	ds_read_b128 v[72:75], v135 offset:16384
	ds_read_b128 v[80:83], v135 offset:17408
	ds_read_b128 v[186:189], v131 offset:16384
	ds_read_b128 v[190:193], v131 offset:17408
	ds_read_b128 v[194:197], v130 offset:16384
	ds_read_b128 v[198:201], v130 offset:17408
	s_waitcnt vmcnt(4)
	s_setprio 1
	s_barrier
	s_waitcnt lgkmcnt(0)
	v_mfma_f32_16x16x32_bf16 v[60:63], v[64:67], v[150:153], v[60:63]
	v_mfma_f32_16x16x32_bf16 v[56:59], v[64:67], v[166:169], v[56:59]
	v_mfma_f32_16x16x32_bf16 v[52:55], v[72:75], v[150:153], v[52:55]
	v_mfma_f32_16x16x32_bf16 v[44:47], v[186:189], v[150:153], v[44:47]
	v_mfma_f32_16x16x32_bf16 v[60:63], v[68:71], v[162:165], v[60:63]
	v_mfma_f32_16x16x32_bf16 v[56:59], v[68:71], v[170:173], v[56:59]
	v_mfma_f32_16x16x32_bf16 v[52:55], v[80:83], v[162:165], v[52:55]
	v_mfma_f32_16x16x32_bf16 v[48:51], v[72:75], v[166:169], v[48:51]
	v_mfma_f32_16x16x32_bf16 v[44:47], v[190:193], v[162:165], v[44:47]
	v_mfma_f32_16x16x32_bf16 v[40:43], v[186:189], v[166:169], v[40:43]
	v_mfma_f32_16x16x32_bf16 v[36:39], v[194:197], v[150:153], v[36:39]
	v_mfma_f32_16x16x32_bf16 v[32:35], v[194:197], v[166:169], v[32:35]
	v_mfma_f32_16x16x32_bf16 v[202:205], v[80:83], v[170:173], v[48:51]
	v_mfma_f32_16x16x32_bf16 v[220:223], v[190:193], v[170:173], v[40:43]
	v_mfma_f32_16x16x32_bf16 v[150:153], v[198:201], v[162:165], v[36:39]
	v_mfma_f32_16x16x32_bf16 v[162:165], v[198:201], v[170:173], v[32:35]
	s_setprio 0
	s_setprio 1
	v_mfma_f32_16x16x32_bf16 v[28:31], v[64:67], v[96:99], v[28:31]
	v_mfma_f32_16x16x32_bf16 v[24:27], v[64:67], v[104:107], v[24:27]
	v_mfma_f32_16x16x32_bf16 v[20:23], v[72:75], v[96:99], v[20:23]
	v_mfma_f32_16x16x32_bf16 v[12:15], v[186:189], v[96:99], v[12:15]
	v_mfma_f32_16x16x32_bf16 v[28:31], v[68:71], v[100:103], v[28:31]
	v_mfma_f32_16x16x32_bf16 v[24:27], v[68:71], v[112:115], v[24:27]
	v_mfma_f32_16x16x32_bf16 v[20:23], v[80:83], v[100:103], v[20:23]
	v_mfma_f32_16x16x32_bf16 v[16:19], v[72:75], v[104:107], v[16:19]
	v_mfma_f32_16x16x32_bf16 v[12:15], v[190:193], v[100:103], v[12:15]
	v_mfma_f32_16x16x32_bf16 v[8:11], v[186:189], v[104:107], v[8:11]
	v_mfma_f32_16x16x32_bf16 v[4:7], v[194:197], v[96:99], v[4:7]
	v_mfma_f32_16x16x32_bf16 v[0:3], v[194:197], v[104:107], v[0:3]
	v_mfma_f32_16x16x32_bf16 v[166:169], v[80:83], v[112:115], v[16:19]
	v_mfma_f32_16x16x32_bf16 v[170:173], v[190:193], v[112:115], v[8:11]
	v_mfma_f32_16x16x32_bf16 v[186:189], v[198:201], v[100:103], v[4:7]
	v_mfma_f32_16x16x32_bf16 v[190:193], v[198:201], v[112:115], v[0:3]
	s_barrier
	s_setprio 0
	s_nop 1
	ds_read_b128 v[0:3], v149
	ds_read_b128 v[4:7], v149 offset:1024
	ds_read_b128 v[8:11], v149 offset:2048
	ds_read_b128 v[16:19], v149 offset:3072
	ds_read_b128 v[32:35], v136 offset:32768
	ds_read_b128 v[36:39], v136 offset:33792
	ds_read_b128 v[40:43], v135 offset:32768
	ds_read_b128 v[48:51], v135 offset:33792
	ds_read_b128 v[194:197], v131 offset:32768
	ds_read_b128 v[198:201], v131 offset:33792
	ds_read_b128 v[224:227], v130 offset:32768
	ds_read_b128 v[228:231], v130 offset:33792
	s_waitcnt vmcnt(2)
	s_setprio 1
	s_barrier
; #define WAIT_V(n) asm volatile("s_waitcnt vmcnt(" #n ")" ::: "memory")
; #define WAIT_L(n) asm volatile("s_waitcnt lgkmcnt(" #n ")" ::: "memory")
; #define BAR __builtin_amdgcn_s_barrier()
; template <int EPI>
; __device__ __forceinline__ void gemm_tile(const Params& p, const bf16* __restrict__ A, const bf16* __restrict__ Bt, const int K,
;                                           const int nt, const int brow, const int bcol, int pm, int pn) {
;     ...
;     LDA(At, 0, 1); WAIT_V(4); BAR; WAIT_L(0); MMA(1, 0, At, B0); MMA(1, 1, At, B1); BAR; }
;   { LDB(B0, 1, 0); LDA(At, 1, 0); WAIT_V(2); BAR; WAIT_L(0); MMA(0, 0, At, B0); BAR;
;     LDB(B1, 1, 1); WAIT_V(0); BAR; WAIT_L(0); MMA(0, 1, At, B1); BAR;
;     LDA(At, 1, 1); BAR; WAIT_L(0); MMA(1, 0, At, B0); MMA(1, 1, At, B1); BAR; }
;   if (wr == 0) BAR;
	s_waitcnt lgkmcnt(0)
	v_mfma_f32_16x16x32_bf16 v[64:67], v[32:35], v[0:3], v[124:127]
	v_mfma_f32_16x16x32_bf16 v[96:99], v[36:39], v[4:7], v[64:67]
	v_mfma_f32_16x16x32_bf16 v[64:67], v[32:35], v[8:11], v[120:123]
	v_mfma_f32_16x16x32_bf16 v[112:115], v[36:39], v[16:19], v[64:67]
	v_mfma_f32_16x16x32_bf16 v[64:67], v[40:43], v[0:3], v[116:119]
	v_mfma_f32_16x16x32_bf16 v[100:103], v[48:51], v[4:7], v[64:67]
	v_mfma_f32_16x16x32_bf16 v[64:67], v[40:43], v[8:11], v[158:161]
	v_mfma_f32_16x16x32_bf16 v[116:119], v[48:51], v[16:19], v[64:67]
	v_mfma_f32_16x16x32_bf16 v[64:67], v[194:197], v[0:3], v[108:111]
	v_mfma_f32_16x16x32_bf16 v[104:107], v[198:201], v[4:7], v[64:67]
	v_mfma_f32_16x16x32_bf16 v[64:67], v[194:197], v[8:11], v[208:211]
	v_mfma_f32_16x16x32_bf16 v[120:123], v[198:201], v[16:19], v[64:67]
	v_mfma_f32_16x16x32_bf16 v[64:67], v[224:227], v[0:3], v[212:215]
	v_mfma_f32_16x16x32_bf16 v[108:111], v[228:231], v[4:7], v[64:67]
	v_mfma_f32_16x16x32_bf16 v[64:67], v[224:227], v[8:11], v[216:219]
	v_mfma_f32_16x16x32_bf16 v[124:127], v[228:231], v[16:19], v[64:67]
	s_barrier
	s_setprio 0
	ds_read_b128 v[158:161], v139
	ds_read_b128 v[208:211], v139 offset:1024
	ds_read_b128 v[212:215], v139 offset:2048
	ds_read_b128 v[138:141], v139 offset:3072
	s_waitcnt vmcnt(0)
	s_setprio 1
	s_barrier
	s_waitcnt lgkmcnt(0)
	v_mfma_f32_16x16x32_bf16 v[64:67], v[32:35], v[158:161], v[92:95]
	v_mfma_f32_16x16x32_bf16 v[32:35], v[32:35], v[212:215], v[88:91]
	v_mfma_f32_16x16x32_bf16 v[80:83], v[36:39], v[138:141], v[32:35]
	v_mfma_f32_16x16x32_bf16 v[32:35], v[40:43], v[158:161], v[84:87]
	v_mfma_f32_16x16x32_bf16 v[68:71], v[48:51], v[208:211], v[32:35]
	v_mfma_f32_16x16x32_bf16 v[32:35], v[40:43], v[212:215], v[154:157]
	v_mfma_f32_16x16x32_bf16 v[84:87], v[48:51], v[138:141], v[32:35]
	v_mfma_f32_16x16x32_bf16 v[32:35], v[194:197], v[158:161], v[76:79]
	v_mfma_f32_16x16x32_bf16 v[72:75], v[198:201], v[208:211], v[32:35]
	v_mfma_f32_16x16x32_bf16 v[32:35], v[194:197], v[212:215], v[174:177]
	v_mfma_f32_16x16x32_bf16 v[88:91], v[198:201], v[138:141], v[32:35]
	v_mfma_f32_16x16x32_bf16 v[32:35], v[224:227], v[158:161], v[178:181]
	v_mfma_f32_16x16x32_bf16 v[76:79], v[228:231], v[208:211], v[32:35]
	v_mfma_f32_16x16x32_bf16 v[32:35], v[224:227], v[212:215], v[182:185]
	v_mfma_f32_16x16x32_bf16 v[64:67], v[36:39], v[208:211], v[64:67]
	v_mfma_f32_16x16x32_bf16 v[92:95], v[228:231], v[138:141], v[32:35]
	s_barrier
	s_setprio 0
	ds_read_b128 v[154:157], v136 offset:49152
	ds_read_b128 v[174:177], v136 offset:50176
	ds_read_b128 v[178:181], v135 offset:49152
	ds_read_b128 v[134:137], v135 offset:50176
	ds_read_b128 v[182:185], v131 offset:49152
	ds_read_b128 v[194:197], v131 offset:50176
	ds_read_b128 v[198:201], v130 offset:49152
	ds_read_b128 v[128:131], v130 offset:50176
	s_setprio 1
	s_barrier
	s_waitcnt lgkmcnt(0)
	v_mfma_f32_16x16x32_bf16 v[36:39], v[154:157], v[8:11], v[56:59]
	v_mfma_f32_16x16x32_bf16 v[40:43], v[178:181], v[8:11], v[202:205]
	v_mfma_f32_16x16x32_bf16 v[32:35], v[154:157], v[0:3], v[60:63]
	v_mfma_f32_16x16x32_bf16 v[48:51], v[174:177], v[16:19], v[36:39]
	v_mfma_f32_16x16x32_bf16 v[36:39], v[178:181], v[0:3], v[52:55]
	v_mfma_f32_16x16x32_bf16 v[52:55], v[134:137], v[16:19], v[40:43]
	v_mfma_f32_16x16x32_bf16 v[40:43], v[182:185], v[0:3], v[44:47]
	v_mfma_f32_16x16x32_bf16 v[44:47], v[182:185], v[8:11], v[220:223]
	v_mfma_f32_16x16x32_bf16 v[0:3], v[198:201], v[0:3], v[150:153]
	v_mfma_f32_16x16x32_bf16 v[56:59], v[194:197], v[16:19], v[44:47]
	v_mfma_f32_16x16x32_bf16 v[44:47], v[128:131], v[4:7], v[0:3]
	v_mfma_f32_16x16x32_bf16 v[0:3], v[198:201], v[8:11], v[162:165]
	v_mfma_f32_16x16x32_bf16 v[32:35], v[174:177], v[4:7], v[32:35]
	v_mfma_f32_16x16x32_bf16 v[36:39], v[134:137], v[4:7], v[36:39]
	v_mfma_f32_16x16x32_bf16 v[40:43], v[194:197], v[4:7], v[40:43]
	v_mfma_f32_16x16x32_bf16 v[60:63], v[128:131], v[16:19], v[0:3]
	s_setprio 0
	s_setprio 1
	v_mfma_f32_16x16x32_bf16 v[4:7], v[154:157], v[212:215], v[24:27]
	v_mfma_f32_16x16x32_bf16 v[8:11], v[178:181], v[212:215], v[166:169]
	v_mfma_f32_16x16x32_bf16 v[16:19], v[174:177], v[138:141], v[4:7]
	v_mfma_f32_16x16x32_bf16 v[4:7], v[178:181], v[158:161], v[20:23]
	v_mfma_f32_16x16x32_bf16 v[20:23], v[134:137], v[138:141], v[8:11]
	v_mfma_f32_16x16x32_bf16 v[8:11], v[182:185], v[158:161], v[12:15]
	v_mfma_f32_16x16x32_bf16 v[12:15], v[182:185], v[212:215], v[170:173]
	v_mfma_f32_16x16x32_bf16 v[0:3], v[154:157], v[158:161], v[28:31]
	v_mfma_f32_16x16x32_bf16 v[24:27], v[194:197], v[138:141], v[12:15]
	v_mfma_f32_16x16x32_bf16 v[12:15], v[198:201], v[158:161], v[186:189]
	v_mfma_f32_16x16x32_bf16 v[28:31], v[198:201], v[212:215], v[190:193]
	v_mfma_f32_16x16x32_bf16 v[0:3], v[174:177], v[208:211], v[0:3]
	v_mfma_f32_16x16x32_bf16 v[4:7], v[134:137], v[208:211], v[4:7]
	v_mfma_f32_16x16x32_bf16 v[8:11], v[194:197], v[208:211], v[8:11]
	v_mfma_f32_16x16x32_bf16 v[12:15], v[128:131], v[208:211], v[12:15]
	v_mfma_f32_16x16x32_bf16 v[28:31], v[128:131], v[138:141], v[28:31]
	s_barrier
	s_setprio 0
	s_cmpk_gt_u32 s5, 0xff
	s_cbranch_scc1 .LBB0_418
	s_barrier

; #define WAIT_V(n) asm volatile("s_waitcnt vmcnt(" #n ")" ::: "memory")
; #define BAR __builtin_amdgcn_s_barrier()
; template <int EPI>
; __device__ __forceinline__ void gemm_tile(const Params& p, const bf16* __restrict__ A, const bf16* __restrict__ Bt, const int K,
;                                           const int nt, const int brow, const int bcol, int pm, int pn) {
;     ...
;   int tid;
;   asm volatile("v_mov_b32 %0, %1" : "=v"(tid) : "v"(threadIdx.x));
;   const int wid = __builtin_amdgcn_readfirstlane(tid >> 6), lane = tid & 63, wr = wid >> 2, wc = wid & 3, fr = lane & 15, fq = lane >> 4;
;   unsigned toff;
;   { int _r, _c; stage_rc(tid * 16, _r, _c); toff = (unsigned)(_r * K + _c) * 2u; }
;   f32x4 acc[2][2][4][2] = {};
;   float pre0 = 0.f, pre1 = 0.f, pre2 = 0.f;
;   if constexpr (EPI == EPI_GU) {
;     const int base = (pm == 65) ? SEQ : 254 * pm - 2;
;     if (tid < 256) pre0 = P_SSQ(p)[max(base + tid, 0)];
;     else if (tid < 384) { const int c = pn * 128 + tid - 256; pre0 = p.w_ffn_conv[c]; pre1 = p.w_ffn_conv[DFF + c]; pre2 = p.w_ffn_conv[2 * DFF + c]; }
;   }
;   bf16x8 At[4][2], B0[2][2], B1[2][2];
;   STAGE(SB(0, 0), Bt, bcol, 0); STAGE(SA(0, 0), A, brow, 0);
;   STAGE(SB(0, 1), Bt, bcol + HALF, 0); STAGE(SA(0, 1), A, brow + HALF, 0);
;   if (wr == 1) BAR;
;   WAIT_V(4); BAR;
;   STAGE(SB(1, 0), Bt, bcol, 1); STAGE(SA(1, 0), A, brow, 1); STAGE(SB(1, 1), Bt, bcol + HALF, 1);
;   WAIT_V(6); BAR;
.LBB0_1377:
	s_add_u32 s94, s8, s54
	v_add_u32_e32 v139, s74, v4
	s_addc_u32 s95, s9, s55
	v_lshl_add_u64 v[6:7], s[94:95], 0, v[156:157]
	v_readfirstlane_b32 s85, v139
	s_add_u32 s52, s8, s52
	v_lshl_add_u64 v[6:7], v[6:7], 0, s[12:13]
	s_mov_b32 m0, s85
	s_addc_u32 s53, s9, s53
	v_add_u32_e32 v140, 0x2000, v139
	s_waitcnt vmcnt(4)
	s_barrier
	global_load_lds_dwordx4 v[6:7], off
	v_lshl_add_u64 v[6:7], s[52:53], 0, v[156:157]
	v_readfirstlane_b32 s52, v140
	s_mov_b32 m0, s52
	s_add_u32 s52, s64, s66
	v_lshl_add_u64 v[6:7], v[6:7], 0, s[12:13]
	s_addc_u32 s53, s65, s67
	v_add_u32_e32 v141, 0x8000, v132
	global_load_lds_dwordx4 v[6:7], off
	v_lshl_add_u64 v[6:7], s[52:53], 0, v[156:157]
	v_readfirstlane_b32 s52, v141
	s_mov_b32 m0, s52
	s_add_u32 s52, s64, s56
	v_lshl_add_u64 v[6:7], v[6:7], 0, s[12:13]
	s_addc_u32 s53, s65, s57
	v_add_u32_e32 v142, 0xa000, v132
	global_load_lds_dwordx4 v[6:7], off
	v_lshl_add_u64 v[6:7], s[52:53], 0, v[156:157]
	v_readfirstlane_b32 s52, v142
	s_mov_b32 m0, s52
	s_add_u32 s52, s8, s68
	v_add_u32_e32 v143, s75, v4
	s_addc_u32 s53, s9, s69
	v_lshl_add_u64 v[6:7], v[6:7], 0, s[12:13]
	v_lshl_add_u64 v[4:5], s[52:53], 0, v[156:157]
	v_readfirstlane_b32 s52, v143
	global_load_lds_dwordx4 v[6:7], off
	s_mov_b32 m0, s52
	s_add_u32 s52, s8, s70
	v_lshl_add_u64 v[4:5], v[4:5], 0, s[12:13]
	s_addc_u32 s53, s9, s71
	v_add_u32_e32 v148, 0x2000, v143
	global_load_lds_dwordx4 v[4:5], off
	v_lshl_add_u64 v[4:5], s[52:53], 0, v[156:157]
	v_readfirstlane_b32 s52, v148
	v_lshl_add_u64 v[4:5], v[4:5], 0, s[12:13]
	s_mov_b32 m0, s52
	s_sub_i32 s53, s90, s92
	global_load_lds_dwordx4 v[4:5], off
	s_lshl_b32 s56, s91, 6
	s_lshl_b32 s52, s89, 6
	s_sub_i32 s53, s53, s56
	v_and_b32_e32 v8, 15, v1
	v_and_b32_e32 v9, 48, v1
	v_lshlrev_b32_e32 v5, 2, v1
	s_and_b32 s57, s52, 0x3000
	v_lshlrev_b32_e32 v1, 6, v1
	s_movk_i32 s52, 0x3c0
	s_sext_i32_i8 s53, s53
	v_and_or_b32 v1, v1, s52, v9
	s_lshl_b32 s52, s91, 11
	s_lshl_b32 s53, s53, 8
	v_lshlrev_b32_e32 v4, 6, v8
	v_and_b32_e32 v5, 32, v5
	s_add_i32 s52, s52, s53
	v_bitop3_b32 v4, v4, v5, v9 bitop3:0x36
	s_lshl_b32 s66, s84, 13
	v_xad_u32 v1, v1, v5, 16
	v_lshlrev_b32_e32 v5, 15, v0
	s_ashr_i32 s53, s52, 31
	s_or_b32 s67, s66, 0x800
	s_or_b32 s68, s66, 0x1000
	s_or_b32 s69, s66, 0x1800
	v_and_b32_e32 v5, 0xffff0000, v5
	s_lshl_b64 s[52:53], s[52:53], 12
	v_lshl_add_u32 v2, v2, 12, v5
	v_and_b32_e32 v0, 1, v0
	s_add_u32 s52, s46, s52
	s_waitcnt vmcnt(6)
	v_lshl_or_b32 v0, v0, 6, v2
	s_addc_u32 s53, s47, s53
	v_add_u32_e32 v6, s72, v4
	v_add_u32_e32 v7, s73, v4
	v_add_u32_e32 v8, s74, v4
	v_add_u32_e32 v10, s75, v4
	v_add_u32_e32 v4, 16, v4
	v_lshl_add_u32 v128, v3, 1, v0
	s_add_u32 s54, s46, s54
	v_mov_b32_e32 v0, 0
	v_mov_b32_e32 v129, v157
	s_addc_u32 s55, s47, s55
	s_mov_b32 s56, -2
	v_add_u32_e32 v153, s57, v6
	v_add_u32_e32 v147, s66, v4
	v_add_u32_e32 v146, s67, v1
	v_add_u32_e32 v145, s68, v1
	v_add_u32_e32 v144, s69, v1
	v_add_u32_e32 v151, 0xc000, v132
	v_add_u32_e32 v150, 0xe000, v132
	v_add_u32_e32 v149, s57, v7
	v_add_u32_e32 v138, s57, v8
	v_add_u32_e32 v152, s57, v10
	v_mov_b32_e32 v1, v0
	v_mov_b32_e32 v2, v0
	v_mov_b32_e32 v3, v0
	v_mov_b32_e32 v4, v0
	v_mov_b32_e32 v5, v0
	v_mov_b32_e32 v6, v0
	v_mov_b32_e32 v7, v0
	v_mov_b32_e32 v8, v0
	v_mov_b32_e32 v9, v0
	v_mov_b32_e32 v10, v0
	v_mov_b32_e32 v11, v0
	v_mov_b32_e32 v12, v0
	v_mov_b32_e32 v13, v0
	v_mov_b32_e32 v14, v0
	v_mov_b32_e32 v15, v0
	v_mov_b32_e32 v16, v0
	v_mov_b32_e32 v17, v0
	v_mov_b32_e32 v18, v0
	v_mov_b32_e32 v19, v0
	v_mov_b32_e32 v20, v0
	v_mov_b32_e32 v21, v0
	v_mov_b32_e32 v22, v0
	v_mov_b32_e32 v23, v0
	v_mov_b32_e32 v24, v0
	v_mov_b32_e32 v25, v0
	v_mov_b32_e32 v26, v0
	v_mov_b32_e32 v27, v0
	v_mov_b32_e32 v28, v0
	v_mov_b32_e32 v29, v0
	v_mov_b32_e32 v30, v0
	v_mov_b32_e32 v31, v0
	v_mov_b32_e32 v32, v0
	v_mov_b32_e32 v33, v0
	v_mov_b32_e32 v34, v0
	v_mov_b32_e32 v35, v0
	v_mov_b32_e32 v36, v0
	v_mov_b32_e32 v37, v0
	v_mov_b32_e32 v38, v0
	v_mov_b32_e32 v39, v0
	v_mov_b32_e32 v40, v0
	v_mov_b32_e32 v41, v0
	v_mov_b32_e32 v42, v0
	v_mov_b32_e32 v43, v0
	v_mov_b32_e32 v44, v0
	v_mov_b32_e32 v45, v0
	v_mov_b32_e32 v46, v0
	v_mov_b32_e32 v47, v0
	v_mov_b32_e32 v48, v0
	v_mov_b32_e32 v49, v0
	v_mov_b32_e32 v50, v0
	v_mov_b32_e32 v51, v0
	v_mov_b32_e32 v52, v0
	v_mov_b32_e32 v53, v0
	v_mov_b32_e32 v54, v0
	v_mov_b32_e32 v55, v0
	v_mov_b32_e32 v56, v0
	v_mov_b32_e32 v57, v0
	v_mov_b32_e32 v58, v0
	v_mov_b32_e32 v59, v0
	v_mov_b32_e32 v60, v0
	v_mov_b32_e32 v61, v0
	v_mov_b32_e32 v62, v0
	v_mov_b32_e32 v63, v0
	v_mov_b32_e32 v64, v0
	v_mov_b32_e32 v65, v0
	v_mov_b32_e32 v66, v0
	v_mov_b32_e32 v67, v0
	v_mov_b32_e32 v68, v0
	v_mov_b32_e32 v69, v0
	v_mov_b32_e32 v70, v0
	v_mov_b32_e32 v71, v0
	v_mov_b32_e32 v72, v0
	v_mov_b32_e32 v73, v0
	v_mov_b32_e32 v74, v0
	v_mov_b32_e32 v75, v0
	v_mov_b32_e32 v76, v0
	v_mov_b32_e32 v77, v0
	v_mov_b32_e32 v78, v0
	v_mov_b32_e32 v79, v0
	v_mov_b32_e32 v80, v0
	v_mov_b32_e32 v81, v0
	v_mov_b32_e32 v82, v0
	v_mov_b32_e32 v83, v0
	v_mov_b32_e32 v84, v0
	v_mov_b32_e32 v85, v0
	v_mov_b32_e32 v86, v0
	v_mov_b32_e32 v87, v0
	v_mov_b32_e32 v88, v0
	v_mov_b32_e32 v89, v0
	v_mov_b32_e32 v90, v0
	v_mov_b32_e32 v91, v0
	v_mov_b32_e32 v92, v0
	v_mov_b32_e32 v93, v0
	v_mov_b32_e32 v94, v0
	v_mov_b32_e32 v95, v0
	v_mov_b32_e32 v96, v0
	v_mov_b32_e32 v97, v0
	v_mov_b32_e32 v98, v0
	v_mov_b32_e32 v99, v0
	v_mov_b32_e32 v100, v0
	v_mov_b32_e32 v101, v0
	v_mov_b32_e32 v102, v0
	v_mov_b32_e32 v103, v0
	v_mov_b32_e32 v104, v0
	v_mov_b32_e32 v105, v0
	v_mov_b32_e32 v106, v0
	v_mov_b32_e32 v107, v0
	v_mov_b32_e32 v108, v0
	v_mov_b32_e32 v109, v0
	v_mov_b32_e32 v110, v0
	v_mov_b32_e32 v111, v0
	v_mov_b32_e32 v112, v0
	v_mov_b32_e32 v113, v0
	v_mov_b32_e32 v114, v0
	v_mov_b32_e32 v115, v0
	v_mov_b32_e32 v116, v0
	v_mov_b32_e32 v117, v0
	v_mov_b32_e32 v118, v0
	v_mov_b32_e32 v119, v0
	v_mov_b32_e32 v120, v0
	v_mov_b32_e32 v121, v0
	v_mov_b32_e32 v122, v0
	v_mov_b32_e32 v123, v0
	v_mov_b32_e32 v124, v0
	v_mov_b32_e32 v125, v0
	v_mov_b32_e32 v126, v0
	v_mov_b32_e32 v127, v0
	s_barrier
	v_lshl_add_u64 v[154:155], s[52:53], 0, v[128:129]
	s_mov_b64 s[66:67], 0x14602080
	v_lshl_add_u64 v[246:247], v[154:155], 0, s[66:67]
	s_mov_b64 s[66:67], 0x14642080
	v_lshl_add_u64 v[244:245], v[154:155], 0, s[66:67]
	v_readfirstlane_b32 s99, v151
	v_readfirstlane_b32 s98, v150
	v_readfirstlane_b32 s100, v136
	v_readfirstlane_b32 s101, v137
	v_readfirstlane_b32 s97, v141
	v_readfirstlane_b32 s32, v142
	v_readfirstlane_b32 s93, v132
	v_readfirstlane_b32 s96, v133
; #define WAIT_V(n) asm volatile("s_waitcnt vmcnt(" #n ")" ::: "memory")
; #define WAIT_L(n) asm volatile("s_waitcnt lgkmcnt(" #n ")" ::: "memory")
; #define BAR __builtin_amdgcn_s_barrier()
; #define SCHED __builtin_amdgcn_sched_barrier(0)
; template <int EPI>
; __device__ __forceinline__ void gemm_tile(const Params& p, const bf16* __restrict__ A, const bf16* __restrict__ Bt, const int K,
;                                           const int nt, const int brow, const int bcol, int pm, int pn) {
;     ...
;   for (int t = 0; t < nt - 2; t += 2) {
;     LDB(B0, 0, 0); SCHED; LDA(At, 0, 0); STAGE(SA(1, 1), A, brow + HALF, t + 1);
;     WAIT_L(8); BAR; WAIT_L(0); MMA(0, 0, At, B0); BAR; SCHED;
;     LDB(B1, 0, 1); STAGE(SB(0, 0), Bt, bcol, t + 2);
;     BAR; WAIT_L(0); MMA(0, 1, At, B1); BAR;
;     LDA(At, 0, 1); STAGE(SA(0, 0), A, brow, t + 2);
;     BAR; WAIT_L(0); MMA(1, 0, At, B0); BAR; SCHED;
;     STAGE(SB(0, 1), Bt, bcol + HALF, t + 2);
;     WAIT_V(6); BAR; MMA(1, 1, At, B1); BAR;
;     LDB(B0, 1, 0); SCHED; LDA(At, 1, 0); STAGE(SA(0, 1), A, brow + HALF, t + 2);
;     WAIT_L(8); BAR; WAIT_L(0); MMA(0, 0, At, B0); BAR; SCHED;
;     LDB(B1, 1, 1); STAGE(SB(1, 0), Bt, bcol, t + 3);
;     BAR; WAIT_L(0); MMA(0, 1, At, B1); BAR;
;     LDA(At, 1, 1); STAGE(SA(1, 0), A, brow, t + 3);
;     BAR; WAIT_L(0); MMA(1, 0, At, B0); BAR; SCHED;
;     STAGE(SB(1, 1), Bt, bcol + HALF, t + 3);
;     WAIT_V(6); BAR; MMA(1, 1, At, B1); BAR;
;   }
.LBB0_1378:
	ds_read_b128 v[158:161], v153
	ds_read_b128 v[162:165], v153 offset:1024
	ds_read_b128 v[166:169], v153 offset:2048
	ds_read_b128 v[170:173], v153 offset:3072
	s_mov_b32 m0, s99
	ds_read_b128 v[174:177], v147
	ds_read_b128 v[178:181], v147 offset:1024
	ds_read_b128 v[182:185], v146
	ds_read_b128 v[186:189], v146 offset:1024
	ds_read_b128 v[190:193], v145
	ds_read_b128 v[196:199], v145 offset:1024
	ds_read_b128 v[200:203], v144
	ds_read_b128 v[208:211], v144 offset:1024
	global_load_lds_dwordx4 v[246:247], off
	s_mov_b32 m0, s98
	s_nop 0
	global_load_lds_dwordx4 v[244:245], off
	s_waitcnt lgkmcnt(8)
	s_setprio 1
	s_barrier
	s_waitcnt lgkmcnt(0)
	v_mfma_f32_16x16x32_bf16 v[124:127], v[174:177], v[158:161], v[124:127]
	v_mfma_f32_16x16x32_bf16 v[120:123], v[174:177], v[166:169], v[120:123]
	v_mfma_f32_16x16x32_bf16 v[116:119], v[182:185], v[158:161], v[116:119]
	v_mfma_f32_16x16x32_bf16 v[112:115], v[182:185], v[166:169], v[112:115]
	v_mfma_f32_16x16x32_bf16 v[108:111], v[190:193], v[158:161], v[108:111]
	v_mfma_f32_16x16x32_bf16 v[104:107], v[190:193], v[166:169], v[104:107]
	v_mfma_f32_16x16x32_bf16 v[100:103], v[200:203], v[158:161], v[100:103]
	v_mfma_f32_16x16x32_bf16 v[96:99], v[200:203], v[166:169], v[96:99]
	v_mfma_f32_16x16x32_bf16 v[124:127], v[178:181], v[162:165], v[124:127]
	v_mfma_f32_16x16x32_bf16 v[120:123], v[178:181], v[170:173], v[120:123]
	v_mfma_f32_16x16x32_bf16 v[116:119], v[186:189], v[162:165], v[116:119]
	v_mfma_f32_16x16x32_bf16 v[112:115], v[186:189], v[170:173], v[112:115]
	v_mfma_f32_16x16x32_bf16 v[108:111], v[196:199], v[162:165], v[108:111]
	v_mfma_f32_16x16x32_bf16 v[104:107], v[196:199], v[170:173], v[104:107]
	v_mfma_f32_16x16x32_bf16 v[100:103], v[208:211], v[162:165], v[100:103]
	v_mfma_f32_16x16x32_bf16 v[96:99], v[208:211], v[170:173], v[96:99]
	s_barrier
	s_setprio 0
	v_lshl_add_u64 v[204:205], s[54:55], 0, v[128:129]
	s_mov_b64 s[66:67], 0x1800100
	v_readfirstlane_b32 s57, v130
	v_lshl_add_u64 v[228:229], v[204:205], 0, s[66:67]
	s_mov_b32 m0, s57
	s_mov_b64 s[66:67], 0x1840100
	v_readfirstlane_b32 s57, v131
	ds_read_b128 v[212:215], v149
	ds_read_b128 v[216:219], v149 offset:1024
	ds_read_b128 v[220:223], v149 offset:2048
	ds_read_b128 v[224:227], v149 offset:3072
	global_load_lds_dwordx4 v[228:229], off
	v_lshl_add_u64 v[228:229], v[204:205], 0, s[66:67]
	s_mov_b32 m0, s57
	s_nop 0
	global_load_lds_dwordx4 v[228:229], off
	s_mov_b64 s[66:67], 0x14582100
	v_lshl_add_u64 v[252:253], v[154:155], 0, s[66:67]
	v_lshl_add_u64 v[254:255], v[154:155], 0, s[14:15]
	v_lshl_add_u64 v[228:229], v[154:155], 0, s[14:15]
	s_setprio 1
	s_barrier
	s_waitcnt lgkmcnt(0)
	v_mfma_f32_16x16x32_bf16 v[92:95], v[174:177], v[212:215], v[92:95]
	v_mfma_f32_16x16x32_bf16 v[88:91], v[174:177], v[220:223], v[88:91]
	v_mfma_f32_16x16x32_bf16 v[84:87], v[182:185], v[212:215], v[84:87]
	v_mfma_f32_16x16x32_bf16 v[80:83], v[182:185], v[220:223], v[80:83]
	v_mfma_f32_16x16x32_bf16 v[76:79], v[190:193], v[212:215], v[76:79]
	v_mfma_f32_16x16x32_bf16 v[72:75], v[190:193], v[220:223], v[72:75]
	v_mfma_f32_16x16x32_bf16 v[68:71], v[200:203], v[212:215], v[68:71]
	v_mfma_f32_16x16x32_bf16 v[64:67], v[200:203], v[220:223], v[64:67]
	v_mfma_f32_16x16x32_bf16 v[92:95], v[178:181], v[216:219], v[92:95]
	v_mfma_f32_16x16x32_bf16 v[88:91], v[178:181], v[224:227], v[88:91]
	v_mfma_f32_16x16x32_bf16 v[84:87], v[186:189], v[216:219], v[84:87]
	v_mfma_f32_16x16x32_bf16 v[80:83], v[186:189], v[224:227], v[80:83]
	v_mfma_f32_16x16x32_bf16 v[76:79], v[196:199], v[216:219], v[76:79]
	v_mfma_f32_16x16x32_bf16 v[72:75], v[196:199], v[224:227], v[72:75]
	v_mfma_f32_16x16x32_bf16 v[68:71], v[208:211], v[216:219], v[68:71]
	v_mfma_f32_16x16x32_bf16 v[64:67], v[208:211], v[224:227], v[64:67]
	s_barrier
	s_setprio 0
	s_mov_b32 m0, s93
	ds_read_b128 v[174:177], v147 offset:16384
	ds_read_b128 v[178:181], v147 offset:17408
	ds_read_b128 v[182:185], v146 offset:16384
	ds_read_b128 v[186:189], v146 offset:17408
	ds_read_b128 v[190:193], v145 offset:16384
	ds_read_b128 v[196:199], v145 offset:17408
	ds_read_b128 v[200:203], v144 offset:16384
	ds_read_b128 v[208:211], v144 offset:17408
	global_load_lds_dwordx4 v[252:253], off
	s_mov_b32 m0, s96
	s_nop 0
	global_load_lds_dwordx4 v[254:255], off
	s_setprio 1
	s_barrier
	s_waitcnt lgkmcnt(0)
	v_mfma_f32_16x16x32_bf16 v[60:63], v[174:177], v[158:161], v[60:63]
	v_mfma_f32_16x16x32_bf16 v[56:59], v[174:177], v[166:169], v[56:59]
	v_mfma_f32_16x16x32_bf16 v[52:55], v[182:185], v[158:161], v[52:55]
	v_mfma_f32_16x16x32_bf16 v[48:51], v[182:185], v[166:169], v[48:51]
	v_mfma_f32_16x16x32_bf16 v[44:47], v[190:193], v[158:161], v[44:47]
	v_mfma_f32_16x16x32_bf16 v[40:43], v[190:193], v[166:169], v[40:43]
	v_mfma_f32_16x16x32_bf16 v[36:39], v[200:203], v[158:161], v[36:39]
	v_mfma_f32_16x16x32_bf16 v[32:35], v[200:203], v[166:169], v[32:35]
	v_mfma_f32_16x16x32_bf16 v[60:63], v[178:181], v[162:165], v[60:63]
	v_mfma_f32_16x16x32_bf16 v[56:59], v[178:181], v[170:173], v[56:59]
	v_mfma_f32_16x16x32_bf16 v[52:55], v[186:189], v[162:165], v[52:55]
	v_mfma_f32_16x16x32_bf16 v[48:51], v[186:189], v[170:173], v[48:51]
	v_mfma_f32_16x16x32_bf16 v[44:47], v[196:199], v[162:165], v[44:47]
	v_mfma_f32_16x16x32_bf16 v[40:43], v[196:199], v[170:173], v[40:43]
	v_mfma_f32_16x16x32_bf16 v[36:39], v[208:211], v[162:165], v[36:39]
	v_mfma_f32_16x16x32_bf16 v[32:35], v[208:211], v[170:173], v[32:35]
	s_barrier
; #define WAIT_V(n) asm volatile("s_waitcnt vmcnt(" #n ")" ::: "memory")
; #define WAIT_L(n) asm volatile("s_waitcnt lgkmcnt(" #n ")" ::: "memory")
; #define BAR __builtin_amdgcn_s_barrier()
; #define SCHED __builtin_amdgcn_sched_barrier(0)
; template <int EPI>
; __device__ __forceinline__ void gemm_tile(const Params& p, const bf16* __restrict__ A, const bf16* __restrict__ Bt, const int K,
;                                           const int nt, const int brow, const int bcol, int pm, int pn) {
;     ...
;   for (int t = 0; t < nt - 2; t += 2) {
;     LDB(B0, 0, 0); SCHED; LDA(At, 0, 0); STAGE(SA(1, 1), A, brow + HALF, t + 1);
;     WAIT_L(8); BAR; WAIT_L(0); MMA(0, 0, At, B0); BAR; SCHED;
;     LDB(B1, 0, 1); STAGE(SB(0, 0), Bt, bcol, t + 2);
;     BAR; WAIT_L(0); MMA(0, 1, At, B1); BAR;
;     LDA(At, 0, 1); STAGE(SA(0, 0), A, brow, t + 2);
;     BAR; WAIT_L(0); MMA(1, 0, At, B0); BAR; SCHED;
;     STAGE(SB(0, 1), Bt, bcol + HALF, t + 2);
;     WAIT_V(6); BAR; MMA(1, 1, At, B1); BAR;
;     LDB(B0, 1, 0); SCHED; LDA(At, 1, 0); STAGE(SA(0, 1), A, brow + HALF, t + 2);
;     WAIT_L(8); BAR; WAIT_L(0); MMA(0, 0, At, B0); BAR; SCHED;
;     LDB(B1, 1, 1); STAGE(SB(1, 0), Bt, bcol, t + 3);
;     BAR; WAIT_L(0); MMA(0, 1, At, B1); BAR;
;     LDA(At, 1, 1); STAGE(SA(1, 0), A, brow, t + 3);
;     BAR; WAIT_L(0); MMA(1, 0, At, B0); BAR; SCHED;
;     STAGE(SB(1, 1), Bt, bcol + HALF, t + 3);
;     WAIT_V(6); BAR; MMA(1, 1, At, B1); BAR;
;   }
	s_setprio 0
	s_add_i32 s56, s56, 2
	s_add_u32 s52, s52, 0x100
	s_addc_u32 s53, s53, 0
	s_add_u32 s54, s54, 0x100
	s_addc_u32 s55, s55, 0
	v_readfirstlane_b32 s57, v134
	v_lshl_add_u64 v[158:159], v[204:205], 0, s[16:17]
	s_mov_b32 m0, s57
	v_readfirstlane_b32 s57, v135
	global_load_lds_dwordx4 v[158:159], off
	v_lshl_add_u64 v[158:159], v[204:205], 0, s[18:19]
	s_mov_b32 m0, s57
	s_nop 0
	global_load_lds_dwordx4 v[158:159], off
	v_lshl_add_u64 v[248:249], v[154:155], 0, s[20:21]
	v_lshl_add_u64 v[250:251], v[154:155], 0, s[22:23]
	s_waitcnt vmcnt(6)
	s_setprio 1
	s_barrier
	v_mfma_f32_16x16x32_bf16 v[28:31], v[174:177], v[212:215], v[28:31]
	v_mfma_f32_16x16x32_bf16 v[24:27], v[174:177], v[220:223], v[24:27]
	v_mfma_f32_16x16x32_bf16 v[20:23], v[182:185], v[212:215], v[20:23]
	v_mfma_f32_16x16x32_bf16 v[16:19], v[182:185], v[220:223], v[16:19]
	v_mfma_f32_16x16x32_bf16 v[12:15], v[190:193], v[212:215], v[12:15]
	v_mfma_f32_16x16x32_bf16 v[8:11], v[190:193], v[220:223], v[8:11]
	v_mfma_f32_16x16x32_bf16 v[4:7], v[200:203], v[212:215], v[4:7]
	v_mfma_f32_16x16x32_bf16 v[0:3], v[200:203], v[220:223], v[0:3]
	v_mfma_f32_16x16x32_bf16 v[28:31], v[178:181], v[216:219], v[28:31]
	v_mfma_f32_16x16x32_bf16 v[24:27], v[178:181], v[224:227], v[24:27]
	v_mfma_f32_16x16x32_bf16 v[20:23], v[186:189], v[216:219], v[20:23]
	v_mfma_f32_16x16x32_bf16 v[16:19], v[186:189], v[224:227], v[16:19]
	v_mfma_f32_16x16x32_bf16 v[12:15], v[196:199], v[216:219], v[12:15]
	v_mfma_f32_16x16x32_bf16 v[8:11], v[196:199], v[224:227], v[8:11]
	v_mfma_f32_16x16x32_bf16 v[4:7], v[208:211], v[216:219], v[4:7]
	v_mfma_f32_16x16x32_bf16 v[0:3], v[208:211], v[224:227], v[0:3]
	s_barrier
	s_setprio 0
	ds_read_b128 v[158:161], v138
	ds_read_b128 v[162:165], v138 offset:1024
	ds_read_b128 v[166:169], v138 offset:2048
	ds_read_b128 v[170:173], v138 offset:3072
	s_mov_b32 m0, s100
	ds_read_b128 v[174:177], v147 offset:32768
	ds_read_b128 v[178:181], v147 offset:33792
	ds_read_b128 v[182:185], v146 offset:32768
	ds_read_b128 v[186:189], v146 offset:33792
	ds_read_b128 v[190:193], v145 offset:32768
	ds_read_b128 v[196:199], v145 offset:33792
	ds_read_b128 v[200:203], v144 offset:32768
	ds_read_b128 v[208:211], v144 offset:33792
	global_load_lds_dwordx4 v[248:249], off
	s_mov_b32 m0, s101
	s_nop 0
	global_load_lds_dwordx4 v[250:251], off
	s_waitcnt lgkmcnt(8)
	s_setprio 1
	s_barrier
	s_waitcnt lgkmcnt(0)
	v_mfma_f32_16x16x32_bf16 v[124:127], v[174:177], v[158:161], v[124:127]
	v_mfma_f32_16x16x32_bf16 v[120:123], v[174:177], v[166:169], v[120:123]
	v_mfma_f32_16x16x32_bf16 v[116:119], v[182:185], v[158:161], v[116:119]
	v_mfma_f32_16x16x32_bf16 v[112:115], v[182:185], v[166:169], v[112:115]
	v_mfma_f32_16x16x32_bf16 v[108:111], v[190:193], v[158:161], v[108:111]
	v_mfma_f32_16x16x32_bf16 v[104:107], v[190:193], v[166:169], v[104:107]
	v_mfma_f32_16x16x32_bf16 v[100:103], v[200:203], v[158:161], v[100:103]
	v_mfma_f32_16x16x32_bf16 v[96:99], v[200:203], v[166:169], v[96:99]
	v_mfma_f32_16x16x32_bf16 v[124:127], v[178:181], v[162:165], v[124:127]
	v_mfma_f32_16x16x32_bf16 v[120:123], v[178:181], v[170:173], v[120:123]
	v_mfma_f32_16x16x32_bf16 v[116:119], v[186:189], v[162:165], v[116:119]
	v_mfma_f32_16x16x32_bf16 v[112:115], v[186:189], v[170:173], v[112:115]
	v_mfma_f32_16x16x32_bf16 v[108:111], v[196:199], v[162:165], v[108:111]
	v_mfma_f32_16x16x32_bf16 v[104:107], v[196:199], v[170:173], v[104:107]
	v_mfma_f32_16x16x32_bf16 v[100:103], v[208:211], v[162:165], v[100:103]
	v_mfma_f32_16x16x32_bf16 v[96:99], v[208:211], v[170:173], v[96:99]
	s_barrier
	s_setprio 0
	v_readfirstlane_b32 s57, v139
	v_lshl_add_u64 v[228:229], v[204:205], 0, s[24:25]
	s_mov_b32 m0, s57
	v_readfirstlane_b32 s57, v140
	ds_read_b128 v[212:215], v152
	ds_read_b128 v[216:219], v152 offset:1024
	ds_read_b128 v[220:223], v152 offset:2048
	ds_read_b128 v[224:227], v152 offset:3072
	global_load_lds_dwordx4 v[228:229], off
	v_lshl_add_u64 v[228:229], v[204:205], 0, s[26:27]
	s_mov_b32 m0, s57
	s_nop 0
	global_load_lds_dwordx4 v[228:229], off
	v_lshl_add_u64 v[252:253], v[154:155], 0, s[28:29]
	v_lshl_add_u64 v[228:229], v[154:155], 0, s[28:29]
	v_lshl_add_u64 v[254:255], v[154:155], 0, s[30:31]
	v_lshl_add_u64 v[154:155], v[154:155], 0, s[30:31]
	s_setprio 1
	s_barrier
	s_waitcnt lgkmcnt(0)
	v_mfma_f32_16x16x32_bf16 v[92:95], v[174:177], v[212:215], v[92:95]
	v_mfma_f32_16x16x32_bf16 v[88:91], v[174:177], v[220:223], v[88:91]
	v_mfma_f32_16x16x32_bf16 v[84:87], v[182:185], v[212:215], v[84:87]
	v_mfma_f32_16x16x32_bf16 v[80:83], v[182:185], v[220:223], v[80:83]
	v_mfma_f32_16x16x32_bf16 v[76:79], v[190:193], v[212:215], v[76:79]
	v_mfma_f32_16x16x32_bf16 v[72:75], v[190:193], v[220:223], v[72:75]
	v_mfma_f32_16x16x32_bf16 v[68:71], v[200:203], v[212:215], v[68:71]
	v_mfma_f32_16x16x32_bf16 v[64:67], v[200:203], v[220:223], v[64:67]
	v_mfma_f32_16x16x32_bf16 v[92:95], v[178:181], v[216:219], v[92:95]
	v_mfma_f32_16x16x32_bf16 v[88:91], v[178:181], v[224:227], v[88:91]
	v_mfma_f32_16x16x32_bf16 v[84:87], v[186:189], v[216:219], v[84:87]
	v_mfma_f32_16x16x32_bf16 v[80:83], v[186:189], v[224:227], v[80:83]
	v_mfma_f32_16x16x32_bf16 v[76:79], v[196:199], v[216:219], v[76:79]
	v_mfma_f32_16x16x32_bf16 v[72:75], v[196:199], v[224:227], v[72:75]
	v_mfma_f32_16x16x32_bf16 v[68:71], v[208:211], v[216:219], v[68:71]
	v_mfma_f32_16x16x32_bf16 v[64:67], v[208:211], v[224:227], v[64:67]
	s_barrier
; #define WAIT_V(n) asm volatile("s_waitcnt vmcnt(" #n ")" ::: "memory")
; #define WAIT_L(n) asm volatile("s_waitcnt lgkmcnt(" #n ")" ::: "memory")
; #define BAR __builtin_amdgcn_s_barrier()
; #define SCHED __builtin_amdgcn_sched_barrier(0)
; template <int EPI>
; __device__ __forceinline__ void gemm_tile(const Params& p, const bf16* __restrict__ A, const bf16* __restrict__ Bt, const int K,
;                                           const int nt, const int brow, const int bcol, int pm, int pn) {
;     ...
;   for (int t = 0; t < nt - 2; t += 2) {
;     LDB(B0, 0, 0); SCHED; LDA(At, 0, 0); STAGE(SA(1, 1), A, brow + HALF, t + 1);
;     WAIT_L(8); BAR; WAIT_L(0); MMA(0, 0, At, B0); BAR; SCHED;
;     LDB(B1, 0, 1); STAGE(SB(0, 0), Bt, bcol, t + 2);
;     BAR; WAIT_L(0); MMA(0, 1, At, B1); BAR;
;     LDA(At, 0, 1); STAGE(SA(0, 0), A, brow, t + 2);
;     BAR; WAIT_L(0); MMA(1, 0, At, B0); BAR; SCHED;
;     STAGE(SB(0, 1), Bt, bcol + HALF, t + 2);
;     WAIT_V(6); BAR; MMA(1, 1, At, B1); BAR;
;     LDB(B0, 1, 0); SCHED; LDA(At, 1, 0); STAGE(SA(0, 1), A, brow + HALF, t + 2);
;     WAIT_L(8); BAR; WAIT_L(0); MMA(0, 0, At, B0); BAR; SCHED;
;     LDB(B1, 1, 1); STAGE(SB(1, 0), Bt, bcol, t + 3);
;     BAR; WAIT_L(0); MMA(0, 1, At, B1); BAR;
;     LDA(At, 1, 1); STAGE(SA(1, 0), A, brow, t + 3);
;     BAR; WAIT_L(0); MMA(1, 0, At, B0); BAR; SCHED;
;     STAGE(SB(1, 1), Bt, bcol + HALF, t + 3);
;     WAIT_V(6); BAR; MMA(1, 1, At, B1); BAR;
;   }
;   { LDB(B0, 0, 0); LDA(At, 0, 0); STAGE(SA(1, 1), A, brow + HALF, nt - 1);
;     BAR; WAIT_L(0); MMA(0, 0, At, B0); BAR;
;     LDB(B1, 0, 1); BAR; WAIT_L(0); MMA(0, 1, At, B1); BAR;
;     LDA(At, 0, 1); WAIT_V(4); BAR; WAIT_L(0); MMA(1, 0, At, B0); MMA(1, 1, At, B1); BAR; }
	s_setprio 0
	s_mov_b32 m0, s97
	ds_read_b128 v[174:177], v147 offset:49152
	ds_read_b128 v[178:181], v147 offset:50176
	ds_read_b128 v[182:185], v146 offset:49152
	ds_read_b128 v[186:189], v146 offset:50176
	ds_read_b128 v[190:193], v145 offset:49152
	ds_read_b128 v[196:199], v145 offset:50176
	ds_read_b128 v[200:203], v144 offset:49152
	ds_read_b128 v[208:211], v144 offset:50176
	global_load_lds_dwordx4 v[252:253], off
	s_mov_b32 m0, s32
	s_nop 0
	global_load_lds_dwordx4 v[254:255], off
	s_setprio 1
	s_barrier
	s_waitcnt lgkmcnt(0)
	v_mfma_f32_16x16x32_bf16 v[60:63], v[174:177], v[158:161], v[60:63]
	v_mfma_f32_16x16x32_bf16 v[56:59], v[174:177], v[166:169], v[56:59]
	v_mfma_f32_16x16x32_bf16 v[52:55], v[182:185], v[158:161], v[52:55]
	v_mfma_f32_16x16x32_bf16 v[48:51], v[182:185], v[166:169], v[48:51]
	v_mfma_f32_16x16x32_bf16 v[44:47], v[190:193], v[158:161], v[44:47]
	v_mfma_f32_16x16x32_bf16 v[40:43], v[190:193], v[166:169], v[40:43]
	v_mfma_f32_16x16x32_bf16 v[36:39], v[200:203], v[158:161], v[36:39]
	v_mfma_f32_16x16x32_bf16 v[32:35], v[200:203], v[166:169], v[32:35]
	v_mfma_f32_16x16x32_bf16 v[60:63], v[178:181], v[162:165], v[60:63]
	v_mfma_f32_16x16x32_bf16 v[56:59], v[178:181], v[170:173], v[56:59]
	v_mfma_f32_16x16x32_bf16 v[52:55], v[186:189], v[162:165], v[52:55]
	v_mfma_f32_16x16x32_bf16 v[48:51], v[186:189], v[170:173], v[48:51]
	v_mfma_f32_16x16x32_bf16 v[44:47], v[196:199], v[162:165], v[44:47]
	v_mfma_f32_16x16x32_bf16 v[40:43], v[196:199], v[170:173], v[40:43]
	v_mfma_f32_16x16x32_bf16 v[36:39], v[208:211], v[162:165], v[36:39]
	v_mfma_f32_16x16x32_bf16 v[32:35], v[208:211], v[170:173], v[32:35]
	s_barrier
	s_setprio 0
	v_readfirstlane_b32 s57, v143
	v_lshl_add_u64 v[154:155], v[204:205], 0, s[34:35]
	s_mov_b32 m0, s57
	v_readfirstlane_b32 s57, v148
	global_load_lds_dwordx4 v[154:155], off
	v_lshl_add_u64 v[154:155], v[204:205], 0, s[36:37]
	s_mov_b32 m0, s57
	s_nop 0
	global_load_lds_dwordx4 v[154:155], off
	v_lshl_add_u64 v[154:155], s[52:53], 0, v[128:129]
	s_mov_b64 s[66:67], 0x14602080
	v_lshl_add_u64 v[246:247], v[154:155], 0, s[66:67]
	s_mov_b64 s[66:67], 0x14642080
	v_lshl_add_u64 v[244:245], v[154:155], 0, s[66:67]
	s_waitcnt vmcnt(6)
	s_setprio 1
	s_barrier
	v_mfma_f32_16x16x32_bf16 v[28:31], v[174:177], v[212:215], v[28:31]
	v_mfma_f32_16x16x32_bf16 v[24:27], v[174:177], v[220:223], v[24:27]
	v_mfma_f32_16x16x32_bf16 v[20:23], v[182:185], v[212:215], v[20:23]
	v_mfma_f32_16x16x32_bf16 v[16:19], v[182:185], v[220:223], v[16:19]
	v_mfma_f32_16x16x32_bf16 v[12:15], v[190:193], v[212:215], v[12:15]
	v_mfma_f32_16x16x32_bf16 v[8:11], v[190:193], v[220:223], v[8:11]
	v_mfma_f32_16x16x32_bf16 v[4:7], v[200:203], v[212:215], v[4:7]
	v_mfma_f32_16x16x32_bf16 v[0:3], v[200:203], v[220:223], v[0:3]
	v_mfma_f32_16x16x32_bf16 v[28:31], v[178:181], v[216:219], v[28:31]
	v_mfma_f32_16x16x32_bf16 v[24:27], v[178:181], v[224:227], v[24:27]
	v_mfma_f32_16x16x32_bf16 v[20:23], v[186:189], v[216:219], v[20:23]
	v_mfma_f32_16x16x32_bf16 v[16:19], v[186:189], v[224:227], v[16:19]
	v_mfma_f32_16x16x32_bf16 v[12:15], v[196:199], v[216:219], v[12:15]
	v_mfma_f32_16x16x32_bf16 v[8:11], v[196:199], v[224:227], v[8:11]
	v_mfma_f32_16x16x32_bf16 v[4:7], v[208:211], v[216:219], v[4:7]
	v_mfma_f32_16x16x32_bf16 v[0:3], v[208:211], v[224:227], v[0:3]
	s_barrier
	s_setprio 0
	s_cmp_lt_u32 s56, 28
	s_cbranch_scc1 .LBB0_1378
	s_add_u32 s6, s64, s6
	s_addc_u32 s7, s65, s7
	v_lshl_add_u64 v[136:137], s[6:7], 0, v[156:157]
	v_readfirstlane_b32 s6, v151
	s_mov_b32 m0, s6
	s_add_u32 s6, s64, s42
	v_lshl_add_u64 v[136:137], v[136:137], 0, s[38:39]
	s_addc_u32 s7, s65, s43
	ds_read_b128 v[128:131], v153
	ds_read_b128 v[132:135], v153 offset:1024
	ds_read_b128 v[140:143], v153 offset:2048
	ds_read_b128 v[158:161], v153 offset:3072
	ds_read_b128 v[162:165], v147
	ds_read_b128 v[166:169], v147 offset:1024
	ds_read_b128 v[170:173], v146
	ds_read_b128 v[174:177], v146 offset:1024
	ds_read_b128 v[178:181], v145
	ds_read_b128 v[182:185], v145 offset:1024
	ds_read_b128 v[186:189], v144
	ds_read_b128 v[190:193], v144 offset:1024
	global_load_lds_dwordx4 v[136:137], off
	v_lshl_add_u64 v[136:137], s[6:7], 0, v[156:157]
	v_readfirstlane_b32 s6, v150
	v_lshl_add_u64 v[136:137], v[136:137], 0, s[38:39]
	s_mov_b32 m0, s6
	s_nop 0
	global_load_lds_dwordx4 v[136:137], off
	s_setprio 1
	s_barrier
	s_waitcnt lgkmcnt(0)
	v_mfma_f32_16x16x32_bf16 v[124:127], v[162:165], v[128:131], v[124:127]
	v_mfma_f32_16x16x32_bf16 v[120:123], v[162:165], v[140:143], v[120:123]
	v_mfma_f32_16x16x32_bf16 v[116:119], v[170:173], v[128:131], v[116:119]
	v_mfma_f32_16x16x32_bf16 v[124:127], v[166:169], v[132:135], v[124:127]
	v_mfma_f32_16x16x32_bf16 v[120:123], v[166:169], v[158:161], v[120:123]
	v_mfma_f32_16x16x32_bf16 v[116:119], v[174:177], v[132:135], v[116:119]
	v_mfma_f32_16x16x32_bf16 v[112:115], v[170:173], v[140:143], v[112:115]
	v_mfma_f32_16x16x32_bf16 v[108:111], v[178:181], v[128:131], v[108:111]
	v_mfma_f32_16x16x32_bf16 v[104:107], v[178:181], v[140:143], v[104:107]
	v_mfma_f32_16x16x32_bf16 v[100:103], v[186:189], v[128:131], v[100:103]
	v_mfma_f32_16x16x32_bf16 v[96:99], v[186:189], v[140:143], v[96:99]
	v_mfma_f32_16x16x32_bf16 v[112:115], v[174:177], v[158:161], v[112:115]
	v_mfma_f32_16x16x32_bf16 v[108:111], v[182:185], v[132:135], v[108:111]
	v_mfma_f32_16x16x32_bf16 v[104:107], v[182:185], v[158:161], v[104:107]
	v_mfma_f32_16x16x32_bf16 v[100:103], v[190:193], v[132:135], v[100:103]
	v_mfma_f32_16x16x32_bf16 v[96:99], v[190:193], v[158:161], v[96:99]
	s_barrier
; #define WAIT_V(n) asm volatile("s_waitcnt vmcnt(" #n ")" ::: "memory")
; #define WAIT_L(n) asm volatile("s_waitcnt lgkmcnt(" #n ")" ::: "memory")
; #define BAR __builtin_amdgcn_s_barrier()
; template <int EPI>
; __device__ __forceinline__ void gemm_tile(const Params& p, const bf16* __restrict__ A, const bf16* __restrict__ Bt, const int K,
;                                           const int nt, const int brow, const int bcol, int pm, int pn) {
;     ...
;   { LDB(B0, 0, 0); LDA(At, 0, 0); STAGE(SA(1, 1), A, brow + HALF, nt - 1);
;     BAR; WAIT_L(0); MMA(0, 0, At, B0); BAR;
;     LDB(B1, 0, 1); BAR; WAIT_L(0); MMA(0, 1, At, B1); BAR;
;     LDA(At, 0, 1); WAIT_V(4); BAR; WAIT_L(0); MMA(1, 0, At, B0); MMA(1, 1, At, B1); BAR; }
;   { LDB(B0, 1, 0); LDA(At, 1, 0); WAIT_V(2); BAR; WAIT_L(0); MMA(0, 0, At, B0); BAR;
;     LDB(B1, 1, 1); WAIT_V(0); BAR; WAIT_L(0); MMA(0, 1, At, B1); BAR;
;     LDA(At, 1, 1); BAR; WAIT_L(0); MMA(1, 0, At, B0); MMA(1, 1, At, B1); BAR; }
	s_setprio 0
	ds_read_b128 v[196:199], v149
	ds_read_b128 v[200:203], v149 offset:1024
	ds_read_b128 v[208:211], v149 offset:2048
	ds_read_b128 v[148:151], v149 offset:3072
	s_setprio 1
	s_barrier
	s_waitcnt lgkmcnt(0)
	v_mfma_f32_16x16x32_bf16 v[92:95], v[162:165], v[196:199], v[92:95]
	v_mfma_f32_16x16x32_bf16 v[88:91], v[162:165], v[208:211], v[88:91]
	v_mfma_f32_16x16x32_bf16 v[84:87], v[170:173], v[196:199], v[84:87]
	v_mfma_f32_16x16x32_bf16 v[76:79], v[178:181], v[196:199], v[76:79]
	v_mfma_f32_16x16x32_bf16 v[92:95], v[166:169], v[200:203], v[92:95]
	v_mfma_f32_16x16x32_bf16 v[88:91], v[166:169], v[148:151], v[88:91]
	v_mfma_f32_16x16x32_bf16 v[84:87], v[174:177], v[200:203], v[84:87]
	v_mfma_f32_16x16x32_bf16 v[80:83], v[170:173], v[208:211], v[80:83]
	v_mfma_f32_16x16x32_bf16 v[76:79], v[182:185], v[200:203], v[76:79]
	v_mfma_f32_16x16x32_bf16 v[72:75], v[178:181], v[208:211], v[72:75]
	v_mfma_f32_16x16x32_bf16 v[68:71], v[186:189], v[196:199], v[68:71]
	v_mfma_f32_16x16x32_bf16 v[64:67], v[186:189], v[208:211], v[64:67]
	v_mfma_f32_16x16x32_bf16 v[162:165], v[174:177], v[148:151], v[80:83]
	v_mfma_f32_16x16x32_bf16 v[166:169], v[182:185], v[148:151], v[72:75]
	v_mfma_f32_16x16x32_bf16 v[170:173], v[190:193], v[200:203], v[68:71]
	v_mfma_f32_16x16x32_bf16 v[174:177], v[190:193], v[148:151], v[64:67]
	s_barrier
	s_setprio 0
	s_nop 1
	ds_read_b128 v[64:67], v147 offset:16384
	ds_read_b128 v[68:71], v147 offset:17408
	ds_read_b128 v[72:75], v146 offset:16384
	ds_read_b128 v[80:83], v146 offset:17408
	ds_read_b128 v[178:181], v145 offset:16384
	ds_read_b128 v[182:185], v145 offset:17408
	ds_read_b128 v[186:189], v144 offset:16384
	ds_read_b128 v[190:193], v144 offset:17408
	s_waitcnt vmcnt(4)
	s_setprio 1
	s_barrier
	s_waitcnt lgkmcnt(0)
	v_mfma_f32_16x16x32_bf16 v[60:63], v[64:67], v[128:131], v[60:63]
	v_mfma_f32_16x16x32_bf16 v[56:59], v[64:67], v[140:143], v[56:59]
	v_mfma_f32_16x16x32_bf16 v[52:55], v[72:75], v[128:131], v[52:55]
	v_mfma_f32_16x16x32_bf16 v[44:47], v[178:181], v[128:131], v[44:47]
	v_mfma_f32_16x16x32_bf16 v[60:63], v[68:71], v[132:135], v[60:63]
	v_mfma_f32_16x16x32_bf16 v[56:59], v[68:71], v[158:161], v[56:59]
	v_mfma_f32_16x16x32_bf16 v[52:55], v[80:83], v[132:135], v[52:55]
	v_mfma_f32_16x16x32_bf16 v[48:51], v[72:75], v[140:143], v[48:51]
	v_mfma_f32_16x16x32_bf16 v[44:47], v[182:185], v[132:135], v[44:47]
	v_mfma_f32_16x16x32_bf16 v[40:43], v[178:181], v[140:143], v[40:43]
	v_mfma_f32_16x16x32_bf16 v[36:39], v[186:189], v[128:131], v[36:39]
	v_mfma_f32_16x16x32_bf16 v[32:35], v[186:189], v[140:143], v[32:35]
	v_mfma_f32_16x16x32_bf16 v[212:215], v[80:83], v[158:161], v[48:51]
	v_mfma_f32_16x16x32_bf16 v[216:219], v[182:185], v[158:161], v[40:43]
	v_mfma_f32_16x16x32_bf16 v[220:223], v[190:193], v[132:135], v[36:39]
	v_mfma_f32_16x16x32_bf16 v[158:161], v[190:193], v[158:161], v[32:35]
	s_setprio 0
	s_setprio 1
	v_mfma_f32_16x16x32_bf16 v[28:31], v[64:67], v[196:199], v[28:31]
	v_mfma_f32_16x16x32_bf16 v[24:27], v[64:67], v[208:211], v[24:27]
	v_mfma_f32_16x16x32_bf16 v[20:23], v[72:75], v[196:199], v[20:23]
	v_mfma_f32_16x16x32_bf16 v[12:15], v[178:181], v[196:199], v[12:15]
	v_mfma_f32_16x16x32_bf16 v[28:31], v[68:71], v[200:203], v[28:31]
	v_mfma_f32_16x16x32_bf16 v[24:27], v[68:71], v[148:151], v[24:27]
	v_mfma_f32_16x16x32_bf16 v[20:23], v[80:83], v[200:203], v[20:23]
	v_mfma_f32_16x16x32_bf16 v[16:19], v[72:75], v[208:211], v[16:19]
	v_mfma_f32_16x16x32_bf16 v[12:15], v[182:185], v[200:203], v[12:15]
	v_mfma_f32_16x16x32_bf16 v[8:11], v[178:181], v[208:211], v[8:11]
	v_mfma_f32_16x16x32_bf16 v[4:7], v[186:189], v[196:199], v[4:7]
	v_mfma_f32_16x16x32_bf16 v[0:3], v[186:189], v[208:211], v[0:3]
	v_mfma_f32_16x16x32_bf16 v[224:227], v[80:83], v[148:151], v[16:19]
	v_mfma_f32_16x16x32_bf16 v[178:181], v[182:185], v[148:151], v[8:11]
	v_mfma_f32_16x16x32_bf16 v[182:185], v[190:193], v[200:203], v[4:7]
	v_mfma_f32_16x16x32_bf16 v[186:189], v[190:193], v[148:151], v[0:3]
	s_barrier
	s_setprio 0
	s_nop 1
	ds_read_b128 v[0:3], v138
	ds_read_b128 v[4:7], v138 offset:1024
	ds_read_b128 v[8:11], v138 offset:2048
	ds_read_b128 v[16:19], v138 offset:3072
	ds_read_b128 v[32:35], v147 offset:32768
	ds_read_b128 v[36:39], v147 offset:33792
	ds_read_b128 v[40:43], v146 offset:32768
	ds_read_b128 v[48:51], v146 offset:33792
	ds_read_b128 v[190:193], v145 offset:32768
	ds_read_b128 v[196:199], v145 offset:33792
	ds_read_b128 v[200:203], v144 offset:32768
	ds_read_b128 v[208:211], v144 offset:33792
	s_waitcnt vmcnt(2)
	s_setprio 1
	s_barrier
; #define WAIT_V(n) asm volatile("s_waitcnt vmcnt(" #n ")" ::: "memory")
; #define WAIT_L(n) asm volatile("s_waitcnt lgkmcnt(" #n ")" ::: "memory")
; #define BAR __builtin_amdgcn_s_barrier()
; template <int EPI>
; __device__ __forceinline__ void gemm_tile(const Params& p, const bf16* __restrict__ A, const bf16* __restrict__ Bt, const int K,
;                                           const int nt, const int brow, const int bcol, int pm, int pn) {
;     ...
;     LDA(At, 0, 1); WAIT_V(4); BAR; WAIT_L(0); MMA(1, 0, At, B0); MMA(1, 1, At, B1); BAR; }
;   { LDB(B0, 1, 0); LDA(At, 1, 0); WAIT_V(2); BAR; WAIT_L(0); MMA(0, 0, At, B0); BAR;
;     LDB(B1, 1, 1); WAIT_V(0); BAR; WAIT_L(0); MMA(0, 1, At, B1); BAR;
;     LDA(At, 1, 1); BAR; WAIT_L(0); MMA(1, 0, At, B0); MMA(1, 1, At, B1); BAR; }
;   if (wr == 0) BAR;
	s_waitcnt lgkmcnt(0)
	v_mfma_f32_16x16x32_bf16 v[64:67], v[32:35], v[0:3], v[124:127]
	v_mfma_f32_16x16x32_bf16 v[136:139], v[36:39], v[4:7], v[64:67]
	v_mfma_f32_16x16x32_bf16 v[64:67], v[32:35], v[8:11], v[120:123]
	v_mfma_f32_16x16x32_bf16 v[148:151], v[36:39], v[16:19], v[64:67]
	v_mfma_f32_16x16x32_bf16 v[64:67], v[40:43], v[0:3], v[116:119]
	v_mfma_f32_16x16x32_bf16 v[132:135], v[48:51], v[4:7], v[64:67]
	v_mfma_f32_16x16x32_bf16 v[64:67], v[40:43], v[8:11], v[112:115]
	v_mfma_f32_16x16x32_bf16 v[140:143], v[48:51], v[16:19], v[64:67]
	v_mfma_f32_16x16x32_bf16 v[64:67], v[190:193], v[0:3], v[108:111]
	v_mfma_f32_16x16x32_bf16 v[124:127], v[196:199], v[4:7], v[64:67]
	v_mfma_f32_16x16x32_bf16 v[64:67], v[190:193], v[8:11], v[104:107]
	v_mfma_f32_16x16x32_bf16 v[128:131], v[196:199], v[16:19], v[64:67]
	v_mfma_f32_16x16x32_bf16 v[64:67], v[200:203], v[0:3], v[100:103]
	v_mfma_f32_16x16x32_bf16 v[116:119], v[208:211], v[4:7], v[64:67]
	v_mfma_f32_16x16x32_bf16 v[64:67], v[200:203], v[8:11], v[96:99]
	v_mfma_f32_16x16x32_bf16 v[120:123], v[208:211], v[16:19], v[64:67]
	s_barrier
	s_setprio 0
	ds_read_b128 v[96:99], v152
	ds_read_b128 v[100:103], v152 offset:1024
	ds_read_b128 v[104:107], v152 offset:2048
	ds_read_b128 v[108:111], v152 offset:3072
	s_waitcnt vmcnt(0)
	s_setprio 1
	s_barrier
	s_waitcnt lgkmcnt(0)
	v_mfma_f32_16x16x32_bf16 v[64:67], v[32:35], v[96:99], v[92:95]
	v_mfma_f32_16x16x32_bf16 v[32:35], v[32:35], v[104:107], v[88:91]
	v_mfma_f32_16x16x32_bf16 v[80:83], v[36:39], v[108:111], v[32:35]
	v_mfma_f32_16x16x32_bf16 v[32:35], v[40:43], v[96:99], v[84:87]
	v_mfma_f32_16x16x32_bf16 v[68:71], v[48:51], v[100:103], v[32:35]
	v_mfma_f32_16x16x32_bf16 v[32:35], v[40:43], v[104:107], v[162:165]
	v_mfma_f32_16x16x32_bf16 v[84:87], v[48:51], v[108:111], v[32:35]
	v_mfma_f32_16x16x32_bf16 v[32:35], v[190:193], v[96:99], v[76:79]
	v_mfma_f32_16x16x32_bf16 v[72:75], v[196:199], v[100:103], v[32:35]
	v_mfma_f32_16x16x32_bf16 v[32:35], v[190:193], v[104:107], v[166:169]
	v_mfma_f32_16x16x32_bf16 v[88:91], v[196:199], v[108:111], v[32:35]
	v_mfma_f32_16x16x32_bf16 v[32:35], v[200:203], v[96:99], v[170:173]
	v_mfma_f32_16x16x32_bf16 v[76:79], v[208:211], v[100:103], v[32:35]
	v_mfma_f32_16x16x32_bf16 v[32:35], v[200:203], v[104:107], v[174:177]
	v_mfma_f32_16x16x32_bf16 v[64:67], v[36:39], v[100:103], v[64:67]
	v_mfma_f32_16x16x32_bf16 v[92:95], v[208:211], v[108:111], v[32:35]
	s_barrier
	s_setprio 0
	ds_read_b128 v[112:115], v147 offset:49152
	ds_read_b128 v[152:155], v147 offset:50176
	ds_read_b128 v[162:165], v146 offset:49152
	ds_read_b128 v[166:169], v146 offset:50176
	ds_read_b128 v[170:173], v145 offset:49152
	ds_read_b128 v[174:177], v145 offset:50176
	ds_read_b128 v[190:193], v144 offset:49152
	ds_read_b128 v[144:147], v144 offset:50176
	s_setprio 1
	s_barrier
	s_waitcnt lgkmcnt(0)
	v_mfma_f32_16x16x32_bf16 v[36:39], v[112:115], v[8:11], v[56:59]
	v_mfma_f32_16x16x32_bf16 v[40:43], v[162:165], v[8:11], v[212:215]
	v_mfma_f32_16x16x32_bf16 v[32:35], v[112:115], v[0:3], v[60:63]
	v_mfma_f32_16x16x32_bf16 v[48:51], v[152:155], v[16:19], v[36:39]
	v_mfma_f32_16x16x32_bf16 v[36:39], v[162:165], v[0:3], v[52:55]
	v_mfma_f32_16x16x32_bf16 v[52:55], v[166:169], v[16:19], v[40:43]
	v_mfma_f32_16x16x32_bf16 v[40:43], v[170:173], v[0:3], v[44:47]
	v_mfma_f32_16x16x32_bf16 v[44:47], v[170:173], v[8:11], v[216:219]
	v_mfma_f32_16x16x32_bf16 v[0:3], v[190:193], v[0:3], v[220:223]
	v_mfma_f32_16x16x32_bf16 v[56:59], v[174:177], v[16:19], v[44:47]
	v_mfma_f32_16x16x32_bf16 v[44:47], v[144:147], v[4:7], v[0:3]
	v_mfma_f32_16x16x32_bf16 v[0:3], v[190:193], v[8:11], v[158:161]
	v_mfma_f32_16x16x32_bf16 v[32:35], v[152:155], v[4:7], v[32:35]
	v_mfma_f32_16x16x32_bf16 v[36:39], v[166:169], v[4:7], v[36:39]
	v_mfma_f32_16x16x32_bf16 v[40:43], v[174:177], v[4:7], v[40:43]
	v_mfma_f32_16x16x32_bf16 v[60:63], v[144:147], v[16:19], v[0:3]
	s_setprio 0
	s_setprio 1
	v_mfma_f32_16x16x32_bf16 v[4:7], v[112:115], v[104:107], v[24:27]
	v_mfma_f32_16x16x32_bf16 v[8:11], v[162:165], v[104:107], v[224:227]
	v_mfma_f32_16x16x32_bf16 v[16:19], v[152:155], v[108:111], v[4:7]
	v_mfma_f32_16x16x32_bf16 v[4:7], v[162:165], v[96:99], v[20:23]
	v_mfma_f32_16x16x32_bf16 v[20:23], v[166:169], v[108:111], v[8:11]
	v_mfma_f32_16x16x32_bf16 v[8:11], v[170:173], v[96:99], v[12:15]
	v_mfma_f32_16x16x32_bf16 v[12:15], v[170:173], v[104:107], v[178:181]
	v_mfma_f32_16x16x32_bf16 v[0:3], v[112:115], v[96:99], v[28:31]
	v_mfma_f32_16x16x32_bf16 v[24:27], v[174:177], v[108:111], v[12:15]
	v_mfma_f32_16x16x32_bf16 v[12:15], v[190:193], v[96:99], v[182:185]
	v_mfma_f32_16x16x32_bf16 v[28:31], v[190:193], v[104:107], v[186:189]
	v_mfma_f32_16x16x32_bf16 v[0:3], v[152:155], v[100:103], v[0:3]
	v_mfma_f32_16x16x32_bf16 v[4:7], v[166:169], v[100:103], v[4:7]
	v_mfma_f32_16x16x32_bf16 v[8:11], v[174:177], v[100:103], v[8:11]
	v_mfma_f32_16x16x32_bf16 v[12:15], v[144:147], v[100:103], v[12:15]
	v_mfma_f32_16x16x32_bf16 v[28:31], v[144:147], v[108:111], v[28:31]
	s_barrier
	s_setprio 0
	s_cmpk_gt_u32 s89, 0xff
	s_cbranch_scc1 .LBB0_1381
	s_barrier

; #define WAIT_V(n) asm volatile("s_waitcnt vmcnt(" #n ")" ::: "memory")
; #define BAR __builtin_amdgcn_s_barrier()
; template <int EPI>
; __device__ __forceinline__ void gemm_tile(const Params& p, const bf16* __restrict__ A, const bf16* __restrict__ Bt, const int K,
;                                           const int nt, const int brow, const int bcol, int pm, int pn) {
;     ...
;   int tid;
;   asm volatile("v_mov_b32 %0, %1" : "=v"(tid) : "v"(threadIdx.x));
;   const int wid = __builtin_amdgcn_readfirstlane(tid >> 6), lane = tid & 63, wr = wid >> 2, wc = wid & 3, fr = lane & 15, fq = lane >> 4;
;   unsigned toff;
;   { int _r, _c; stage_rc(tid * 16, _r, _c); toff = (unsigned)(_r * K + _c) * 2u; }
;   f32x4 acc[2][2][4][2] = {};
;   float pre0 = 0.f, pre1 = 0.f, pre2 = 0.f;
;   if constexpr (EPI == EPI_GU) {
;     const int base = (pm == 65) ? SEQ : 254 * pm - 2;
;     if (tid < 256) pre0 = P_SSQ(p)[max(base + tid, 0)];
;     else if (tid < 384) { const int c = pn * 128 + tid - 256; pre0 = p.w_ffn_conv[c]; pre1 = p.w_ffn_conv[DFF + c]; pre2 = p.w_ffn_conv[2 * DFF + c]; }
;   }
;   bf16x8 At[4][2], B0[2][2], B1[2][2];
;   STAGE(SB(0, 0), Bt, bcol, 0); STAGE(SA(0, 0), A, brow, 0);
;   STAGE(SB(0, 1), Bt, bcol + HALF, 0); STAGE(SA(0, 1), A, brow + HALF, 0);
;   if (wr == 1) BAR;
;   WAIT_V(4); BAR;
;   STAGE(SB(1, 0), Bt, bcol, 1); STAGE(SA(1, 0), A, brow, 1); STAGE(SB(1, 1), Bt, bcol + HALF, 1);
;   WAIT_V(6); BAR;
.LBB0_1561:
	s_add_u32 s84, s10, s54
	v_add_u32_e32 v146, s67, v4
	s_addc_u32 s85, s11, s55
	v_lshl_add_u64 v[6:7], s[84:85], 0, v[136:137]
	v_readfirstlane_b32 s39, v146
	s_add_u32 s42, s10, s42
	v_lshl_add_u64 v[6:7], v[6:7], 0, s[18:19]
	s_mov_b32 m0, s39
	s_addc_u32 s43, s11, s43
	v_add_u32_e32 v147, 0x2000, v146
	s_waitcnt vmcnt(4)
	s_barrier
	global_load_lds_dwordx4 v[6:7], off
	v_lshl_add_u64 v[6:7], s[42:43], 0, v[136:137]
	v_readfirstlane_b32 s39, v147
	s_add_u32 s42, s60, s50
	v_lshl_add_u64 v[6:7], v[6:7], 0, s[18:19]
	s_mov_b32 m0, s39
	s_addc_u32 s43, s61, s51
	v_add_u32_e32 v148, 0x8000, v132
	global_load_lds_dwordx4 v[6:7], off
	v_lshl_add_u64 v[6:7], s[42:43], 0, v[136:137]
	v_readfirstlane_b32 s39, v148
	s_add_u32 s42, s60, s52
	v_lshl_add_u64 v[6:7], v[6:7], 0, s[18:19]
	s_mov_b32 m0, s39
	s_addc_u32 s43, s61, s53
	global_load_lds_dwordx4 v[6:7], off
	v_lshl_add_u64 v[6:7], s[42:43], 0, v[136:137]
	v_add_u32_e32 v149, 0xa000, v132
	s_add_u32 s42, s10, s48
	v_readfirstlane_b32 s39, v149
	v_add_u32_e32 v150, s68, v4
	s_addc_u32 s43, s11, s49
	v_lshl_add_u64 v[6:7], v[6:7], 0, s[18:19]
	s_mov_b32 m0, s39
	v_lshl_add_u64 v[4:5], s[42:43], 0, v[136:137]
	v_readfirstlane_b32 s39, v150
	s_add_u32 s42, s10, s56
	global_load_lds_dwordx4 v[6:7], off
	v_lshl_add_u64 v[4:5], v[4:5], 0, s[18:19]
	s_mov_b32 m0, s39
	s_addc_u32 s43, s11, s57
	v_add_u32_e32 v151, 0x2000, v150
	global_load_lds_dwordx4 v[4:5], off
	v_lshl_add_u64 v[4:5], s[42:43], 0, v[136:137]
	v_readfirstlane_b32 s39, v151
	v_lshl_add_u64 v[4:5], v[4:5], 0, s[18:19]
	s_mov_b32 m0, s39
	v_and_b32_e32 v8, 15, v0
	global_load_lds_dwordx4 v[4:5], off
	v_and_b32_e32 v9, 48, v0
	v_lshlrev_b32_e32 v5, 2, v0
	s_lshl_b32 s39, s94, 6
	s_lshl_b32 s84, s37, 13
	v_lshlrev_b32_e32 v0, 6, v0
	s_movk_i32 s37, 0x3c0
	s_and_b32 s57, s39, 0x3000
	v_and_or_b32 v0, v0, s37, v9
	s_or_b32 s37, s84, 0x800
	s_or_b32 s39, s84, 0x1000
	s_or_b32 s41, s84, 0x1800
	s_add_u32 s42, s46, s4
	s_addc_u32 s43, s47, s5
	s_add_u32 s48, s46, s6
	v_and_b32_e32 v5, 32, v5
	s_addc_u32 s49, s47, s7
	v_xad_u32 v153, v0, v5, 16
	v_lshlrev_b32_e32 v0, 15, v1
	s_add_u32 s50, s46, s50
	v_and_b32_e32 v0, 0xffff0000, v0
	s_addc_u32 s51, s47, s51
	v_lshlrev_b32_e32 v4, 6, v8
	v_lshl_add_u32 v0, v2, 12, v0
	v_and_b32_e32 v1, 1, v1
	s_add_u32 s52, s46, s52
	s_waitcnt vmcnt(6)
	v_bitop3_b32 v4, v4, v5, v9 bitop3:0x36
	v_lshl_or_b32 v0, v1, 6, v0
	s_addc_u32 s53, s47, s53
	v_add_u32_e32 v6, s65, v4
	v_add_u32_e32 v7, s66, v4
	v_add_u32_e32 v8, s67, v4
	v_add_u32_e32 v10, s68, v4
	v_add_u32_e32 v4, 16, v4
	v_lshl_add_u32 v128, v3, 1, v0
	s_add_u32 s54, s46, s54
	v_mov_b32_e32 v0, 0
	v_mov_b32_e32 v129, v137
	s_addc_u32 s55, s47, s55
	s_mov_b32 s56, -2
	v_add_u32_e32 v154, s57, v6
	v_add_u32_e32 v141, s84, v4
	v_add_u32_e32 v152, s57, v7
	v_add_u32_e32 v145, s57, v8
	v_add_u32_e32 v142, s57, v10
	v_mov_b32_e32 v1, v0
	v_mov_b32_e32 v2, v0
	v_mov_b32_e32 v3, v0
	v_mov_b32_e32 v4, v0
	v_mov_b32_e32 v5, v0
	v_mov_b32_e32 v6, v0
	v_mov_b32_e32 v7, v0
	v_mov_b32_e32 v8, v0
	v_mov_b32_e32 v9, v0
	v_mov_b32_e32 v10, v0
	v_mov_b32_e32 v11, v0
	v_mov_b32_e32 v12, v0
	v_mov_b32_e32 v13, v0
	v_mov_b32_e32 v14, v0
	v_mov_b32_e32 v15, v0
	v_mov_b32_e32 v16, v0
	v_mov_b32_e32 v17, v0
	v_mov_b32_e32 v18, v0
	v_mov_b32_e32 v19, v0
	v_mov_b32_e32 v20, v0
	v_mov_b32_e32 v21, v0
	v_mov_b32_e32 v22, v0
	v_mov_b32_e32 v23, v0
	v_mov_b32_e32 v24, v0
	v_mov_b32_e32 v25, v0
	v_mov_b32_e32 v26, v0
	v_mov_b32_e32 v27, v0
	v_mov_b32_e32 v28, v0
	v_mov_b32_e32 v29, v0
	v_mov_b32_e32 v30, v0
	v_mov_b32_e32 v31, v0
	v_mov_b32_e32 v32, v0
	v_mov_b32_e32 v33, v0
	v_mov_b32_e32 v34, v0
	v_mov_b32_e32 v35, v0
	v_mov_b32_e32 v36, v0
	v_mov_b32_e32 v37, v0
	v_mov_b32_e32 v38, v0
	v_mov_b32_e32 v39, v0
	v_mov_b32_e32 v40, v0
	v_mov_b32_e32 v41, v0
	v_mov_b32_e32 v42, v0
	v_mov_b32_e32 v43, v0
	v_mov_b32_e32 v44, v0
	v_mov_b32_e32 v45, v0
	v_mov_b32_e32 v46, v0
	v_mov_b32_e32 v47, v0
	v_mov_b32_e32 v48, v0
	v_mov_b32_e32 v49, v0
	v_mov_b32_e32 v50, v0
	v_mov_b32_e32 v51, v0
	v_mov_b32_e32 v52, v0
	v_mov_b32_e32 v53, v0
	v_mov_b32_e32 v54, v0
	v_mov_b32_e32 v55, v0
	v_mov_b32_e32 v56, v0
	v_mov_b32_e32 v57, v0
	v_mov_b32_e32 v58, v0
	v_mov_b32_e32 v59, v0
	v_mov_b32_e32 v60, v0
	v_mov_b32_e32 v61, v0
	v_mov_b32_e32 v62, v0
	v_mov_b32_e32 v63, v0
	v_mov_b32_e32 v64, v0
	v_mov_b32_e32 v65, v0
	v_mov_b32_e32 v66, v0
	v_mov_b32_e32 v67, v0
	v_mov_b32_e32 v68, v0
	v_mov_b32_e32 v69, v0
	v_mov_b32_e32 v70, v0
	v_mov_b32_e32 v71, v0
	v_mov_b32_e32 v72, v0
	v_mov_b32_e32 v73, v0
	v_mov_b32_e32 v74, v0
	v_mov_b32_e32 v75, v0
	v_mov_b32_e32 v76, v0
	v_mov_b32_e32 v77, v0
	v_mov_b32_e32 v78, v0
	v_mov_b32_e32 v79, v0
	v_mov_b32_e32 v80, v0
	v_mov_b32_e32 v81, v0
	v_mov_b32_e32 v82, v0
	v_mov_b32_e32 v83, v0
	v_mov_b32_e32 v84, v0
	v_mov_b32_e32 v85, v0
	v_mov_b32_e32 v86, v0
	v_mov_b32_e32 v87, v0
	v_mov_b32_e32 v88, v0
	v_mov_b32_e32 v89, v0
	v_mov_b32_e32 v90, v0
	v_mov_b32_e32 v91, v0
	v_mov_b32_e32 v92, v0
	v_mov_b32_e32 v93, v0
	v_mov_b32_e32 v94, v0
	v_mov_b32_e32 v95, v0
	v_mov_b32_e32 v96, v0
	v_mov_b32_e32 v97, v0
	v_mov_b32_e32 v98, v0
	v_mov_b32_e32 v99, v0
	v_mov_b32_e32 v100, v0
	v_mov_b32_e32 v101, v0
	v_mov_b32_e32 v102, v0
	v_mov_b32_e32 v103, v0
	v_mov_b32_e32 v104, v0
	v_mov_b32_e32 v105, v0
	v_mov_b32_e32 v106, v0
	v_mov_b32_e32 v107, v0
	v_mov_b32_e32 v108, v0
	v_mov_b32_e32 v109, v0
	v_mov_b32_e32 v110, v0
	v_mov_b32_e32 v111, v0
	v_mov_b32_e32 v112, v0
	v_mov_b32_e32 v113, v0
	v_mov_b32_e32 v114, v0
	v_mov_b32_e32 v115, v0
	v_mov_b32_e32 v116, v0
	v_mov_b32_e32 v117, v0
	v_mov_b32_e32 v118, v0
	v_mov_b32_e32 v119, v0
	v_mov_b32_e32 v120, v0
	v_mov_b32_e32 v121, v0
	v_mov_b32_e32 v122, v0
	v_mov_b32_e32 v123, v0
	v_mov_b32_e32 v124, v0
	v_mov_b32_e32 v125, v0
	v_mov_b32_e32 v126, v0
	v_mov_b32_e32 v127, v0
	s_barrier
	v_add_u32_e32 v159, 0xc000, v132
	v_add_u32_e32 v158, 0xe000, v132
	v_add_u32_e32 v155, s37, v153
	v_add_u32_e32 v156, s39, v153
	v_add_u32_e32 v157, s41, v153
	v_lshl_add_u64 v[204:205], s[42:43], 0, v[128:129]
	v_lshl_add_u64 v[246:247], v[204:205], 0, s[20:21]
	v_lshl_add_u64 v[232:233], s[48:49], 0, v[128:129]
	v_lshl_add_u64 v[244:245], v[232:233], 0, s[20:21]
	v_readfirstlane_b32 s98, v158
	v_readfirstlane_b32 s99, v159
	v_readfirstlane_b32 s100, v143
	v_readfirstlane_b32 s101, v144
	v_readfirstlane_b32 s97, v148
	v_readfirstlane_b32 s32, v149
	v_readfirstlane_b32 s95, v132
	v_readfirstlane_b32 s96, v133
; #define WAIT_V(n) asm volatile("s_waitcnt vmcnt(" #n ")" ::: "memory")
; #define WAIT_L(n) asm volatile("s_waitcnt lgkmcnt(" #n ")" ::: "memory")
; #define BAR __builtin_amdgcn_s_barrier()
; #define SCHED __builtin_amdgcn_sched_barrier(0)
; template <int EPI>
; __device__ __forceinline__ void gemm_tile(const Params& p, const bf16* __restrict__ A, const bf16* __restrict__ Bt, const int K,
;                                           const int nt, const int brow, const int bcol, int pm, int pn) {
;     ...
;   for (int t = 0; t < nt - 2; t += 2) {
;     LDB(B0, 0, 0); SCHED; LDA(At, 0, 0); STAGE(SA(1, 1), A, brow + HALF, t + 1);
;     WAIT_L(8); BAR; WAIT_L(0); MMA(0, 0, At, B0); BAR; SCHED;
;     LDB(B1, 0, 1); STAGE(SB(0, 0), Bt, bcol, t + 2);
;     BAR; WAIT_L(0); MMA(0, 1, At, B1); BAR;
;     LDA(At, 0, 1); STAGE(SA(0, 0), A, brow, t + 2);
;     BAR; WAIT_L(0); MMA(1, 0, At, B0); BAR; SCHED;
;     STAGE(SB(0, 1), Bt, bcol + HALF, t + 2);
;     WAIT_V(6); BAR; MMA(1, 1, At, B1); BAR;
;     LDB(B0, 1, 0); SCHED; LDA(At, 1, 0); STAGE(SA(0, 1), A, brow + HALF, t + 2);
;     WAIT_L(8); BAR; WAIT_L(0); MMA(0, 0, At, B0); BAR; SCHED;
;     LDB(B1, 1, 1); STAGE(SB(1, 0), Bt, bcol, t + 3);
;     BAR; WAIT_L(0); MMA(0, 1, At, B1); BAR;
;     LDA(At, 1, 1); STAGE(SA(1, 0), A, brow, t + 3);
;     BAR; WAIT_L(0); MMA(1, 0, At, B0); BAR; SCHED;
;     STAGE(SB(1, 1), Bt, bcol + HALF, t + 3);
;     WAIT_V(6); BAR; MMA(1, 1, At, B1); BAR;
;   }
.LBB0_1562:
	ds_read_b128 v[162:165], v154
	ds_read_b128 v[166:169], v154 offset:1024
	ds_read_b128 v[170:173], v154 offset:2048
	ds_read_b128 v[174:177], v154 offset:3072
	s_mov_b32 m0, s99
	ds_read_b128 v[178:181], v141
	ds_read_b128 v[182:185], v141 offset:1024
	ds_read_b128 v[186:189], v155
	ds_read_b128 v[190:193], v155 offset:1024
	ds_read_b128 v[196:199], v156
	ds_read_b128 v[200:203], v156 offset:1024
	ds_read_b128 v[208:211], v157
	ds_read_b128 v[212:215], v157 offset:1024
	global_load_lds_dwordx4 v[246:247], off
	s_mov_b32 m0, s98
	s_nop 0
	global_load_lds_dwordx4 v[244:245], off
	s_waitcnt lgkmcnt(8)
	s_setprio 1
	s_barrier
	s_waitcnt lgkmcnt(0)
	v_mfma_f32_16x16x32_bf16 v[124:127], v[178:181], v[162:165], v[124:127]
	v_mfma_f32_16x16x32_bf16 v[120:123], v[178:181], v[170:173], v[120:123]
	v_mfma_f32_16x16x32_bf16 v[116:119], v[186:189], v[162:165], v[116:119]
	v_mfma_f32_16x16x32_bf16 v[112:115], v[186:189], v[170:173], v[112:115]
	v_mfma_f32_16x16x32_bf16 v[108:111], v[196:199], v[162:165], v[108:111]
	v_mfma_f32_16x16x32_bf16 v[104:107], v[196:199], v[170:173], v[104:107]
	v_mfma_f32_16x16x32_bf16 v[100:103], v[208:211], v[162:165], v[100:103]
	v_mfma_f32_16x16x32_bf16 v[96:99], v[208:211], v[170:173], v[96:99]
	v_mfma_f32_16x16x32_bf16 v[124:127], v[182:185], v[166:169], v[124:127]
	v_mfma_f32_16x16x32_bf16 v[120:123], v[182:185], v[174:177], v[120:123]
	v_mfma_f32_16x16x32_bf16 v[116:119], v[190:193], v[166:169], v[116:119]
	v_mfma_f32_16x16x32_bf16 v[112:115], v[190:193], v[174:177], v[112:115]
	v_mfma_f32_16x16x32_bf16 v[108:111], v[200:203], v[166:169], v[108:111]
	v_mfma_f32_16x16x32_bf16 v[104:107], v[200:203], v[174:177], v[104:107]
	v_mfma_f32_16x16x32_bf16 v[100:103], v[212:215], v[166:169], v[100:103]
	v_mfma_f32_16x16x32_bf16 v[96:99], v[212:215], v[174:177], v[96:99]
	s_barrier
	s_setprio 0
	v_lshl_add_u64 v[234:235], s[54:55], 0, v[128:129]
	s_mov_b64 s[84:85], 0x2000100
	v_readfirstlane_b32 s57, v130
	v_lshl_add_u64 v[236:237], v[234:235], 0, s[84:85]
	s_mov_b32 m0, s57
	s_mov_b64 s[84:85], 0x2040100
	v_readfirstlane_b32 s57, v131
	ds_read_b128 v[216:219], v152
	ds_read_b128 v[220:223], v152 offset:1024
	ds_read_b128 v[224:227], v152 offset:2048
	ds_read_b128 v[228:231], v152 offset:3072
	global_load_lds_dwordx4 v[236:237], off
	v_lshl_add_u64 v[236:237], v[234:235], 0, s[84:85]
	s_mov_b32 m0, s57
	s_nop 0
	global_load_lds_dwordx4 v[236:237], off
	v_lshl_add_u64 v[236:237], s[50:51], 0, v[128:129]
	v_lshl_add_u64 v[252:253], v[236:237], 0, s[22:23]
	v_lshl_add_u64 v[238:239], s[52:53], 0, v[128:129]
	v_lshl_add_u64 v[254:255], v[238:239], 0, s[22:23]
	v_lshl_add_u64 v[240:241], v[238:239], 0, s[22:23]
	s_setprio 1
	s_barrier
	s_waitcnt lgkmcnt(0)
	v_mfma_f32_16x16x32_bf16 v[92:95], v[178:181], v[216:219], v[92:95]
	v_mfma_f32_16x16x32_bf16 v[88:91], v[178:181], v[224:227], v[88:91]
	v_mfma_f32_16x16x32_bf16 v[84:87], v[186:189], v[216:219], v[84:87]
	v_mfma_f32_16x16x32_bf16 v[80:83], v[186:189], v[224:227], v[80:83]
	v_mfma_f32_16x16x32_bf16 v[76:79], v[196:199], v[216:219], v[76:79]
	v_mfma_f32_16x16x32_bf16 v[72:75], v[196:199], v[224:227], v[72:75]
	v_mfma_f32_16x16x32_bf16 v[68:71], v[208:211], v[216:219], v[68:71]
	v_mfma_f32_16x16x32_bf16 v[64:67], v[208:211], v[224:227], v[64:67]
	v_mfma_f32_16x16x32_bf16 v[92:95], v[182:185], v[220:223], v[92:95]
	v_mfma_f32_16x16x32_bf16 v[88:91], v[182:185], v[228:231], v[88:91]
	v_mfma_f32_16x16x32_bf16 v[84:87], v[190:193], v[220:223], v[84:87]
	v_mfma_f32_16x16x32_bf16 v[80:83], v[190:193], v[228:231], v[80:83]
	v_mfma_f32_16x16x32_bf16 v[76:79], v[200:203], v[220:223], v[76:79]
	v_mfma_f32_16x16x32_bf16 v[72:75], v[200:203], v[228:231], v[72:75]
	v_mfma_f32_16x16x32_bf16 v[68:71], v[212:215], v[220:223], v[68:71]
	v_mfma_f32_16x16x32_bf16 v[64:67], v[212:215], v[228:231], v[64:67]
	s_barrier
	s_setprio 0
	s_mov_b32 m0, s95
	ds_read_b128 v[178:181], v141 offset:16384
	ds_read_b128 v[182:185], v141 offset:17408
	ds_read_b128 v[186:189], v155 offset:16384
	ds_read_b128 v[190:193], v155 offset:17408
	ds_read_b128 v[196:199], v156 offset:16384
	ds_read_b128 v[200:203], v156 offset:17408
	ds_read_b128 v[208:211], v157 offset:16384
	ds_read_b128 v[212:215], v157 offset:17408
	global_load_lds_dwordx4 v[252:253], off
	s_mov_b32 m0, s96
	s_nop 0
	global_load_lds_dwordx4 v[254:255], off
	s_setprio 1
	s_barrier
	s_waitcnt lgkmcnt(0)
	v_mfma_f32_16x16x32_bf16 v[60:63], v[178:181], v[162:165], v[60:63]
	v_mfma_f32_16x16x32_bf16 v[56:59], v[178:181], v[170:173], v[56:59]
	v_mfma_f32_16x16x32_bf16 v[52:55], v[186:189], v[162:165], v[52:55]
	v_mfma_f32_16x16x32_bf16 v[48:51], v[186:189], v[170:173], v[48:51]
	v_mfma_f32_16x16x32_bf16 v[44:47], v[196:199], v[162:165], v[44:47]
	v_mfma_f32_16x16x32_bf16 v[40:43], v[196:199], v[170:173], v[40:43]
	v_mfma_f32_16x16x32_bf16 v[36:39], v[208:211], v[162:165], v[36:39]
	v_mfma_f32_16x16x32_bf16 v[32:35], v[208:211], v[170:173], v[32:35]
	v_mfma_f32_16x16x32_bf16 v[60:63], v[182:185], v[166:169], v[60:63]
	v_mfma_f32_16x16x32_bf16 v[56:59], v[182:185], v[174:177], v[56:59]
	v_mfma_f32_16x16x32_bf16 v[52:55], v[190:193], v[166:169], v[52:55]
	v_mfma_f32_16x16x32_bf16 v[48:51], v[190:193], v[174:177], v[48:51]
	v_mfma_f32_16x16x32_bf16 v[44:47], v[200:203], v[166:169], v[44:47]
	v_mfma_f32_16x16x32_bf16 v[40:43], v[200:203], v[174:177], v[40:43]
	v_mfma_f32_16x16x32_bf16 v[36:39], v[212:215], v[166:169], v[36:39]
	v_mfma_f32_16x16x32_bf16 v[32:35], v[212:215], v[174:177], v[32:35]
	s_barrier
; #define WAIT_V(n) asm volatile("s_waitcnt vmcnt(" #n ")" ::: "memory")
; #define WAIT_L(n) asm volatile("s_waitcnt lgkmcnt(" #n ")" ::: "memory")
; #define BAR __builtin_amdgcn_s_barrier()
; #define SCHED __builtin_amdgcn_sched_barrier(0)
; template <int EPI>
; __device__ __forceinline__ void gemm_tile(const Params& p, const bf16* __restrict__ A, const bf16* __restrict__ Bt, const int K,
;                                           const int nt, const int brow, const int bcol, int pm, int pn) {
;     ...
;   for (int t = 0; t < nt - 2; t += 2) {
;     LDB(B0, 0, 0); SCHED; LDA(At, 0, 0); STAGE(SA(1, 1), A, brow + HALF, t + 1);
;     WAIT_L(8); BAR; WAIT_L(0); MMA(0, 0, At, B0); BAR; SCHED;
;     LDB(B1, 0, 1); STAGE(SB(0, 0), Bt, bcol, t + 2);
;     BAR; WAIT_L(0); MMA(0, 1, At, B1); BAR;
;     LDA(At, 0, 1); STAGE(SA(0, 0), A, brow, t + 2);
;     BAR; WAIT_L(0); MMA(1, 0, At, B0); BAR; SCHED;
;     STAGE(SB(0, 1), Bt, bcol + HALF, t + 2);
;     WAIT_V(6); BAR; MMA(1, 1, At, B1); BAR;
;     LDB(B0, 1, 0); SCHED; LDA(At, 1, 0); STAGE(SA(0, 1), A, brow + HALF, t + 2);
;     WAIT_L(8); BAR; WAIT_L(0); MMA(0, 0, At, B0); BAR; SCHED;
;     LDB(B1, 1, 1); STAGE(SB(1, 0), Bt, bcol, t + 3);
;     BAR; WAIT_L(0); MMA(0, 1, At, B1); BAR;
;     LDA(At, 1, 1); STAGE(SA(1, 0), A, brow, t + 3);
;     BAR; WAIT_L(0); MMA(1, 0, At, B0); BAR; SCHED;
;     STAGE(SB(1, 1), Bt, bcol + HALF, t + 3);
;     WAIT_V(6); BAR; MMA(1, 1, At, B1); BAR;
;   }
	s_setprio 0
	s_add_i32 s56, s56, 2
	s_add_u32 s42, s42, 0x100
	s_addc_u32 s43, s43, 0
	s_add_u32 s48, s48, 0x100
	s_addc_u32 s49, s49, 0
	s_add_u32 s50, s50, 0x100
	s_addc_u32 s51, s51, 0
	s_add_u32 s52, s52, 0x100
	s_addc_u32 s53, s53, 0
	s_add_u32 s54, s54, 0x100
	s_addc_u32 s55, s55, 0
	s_mov_b64 s[84:85], 0x2080100
	v_readfirstlane_b32 s57, v134
	v_lshl_add_u64 v[162:163], v[234:235], 0, s[84:85]
	s_mov_b32 m0, s57
	s_mov_b64 s[84:85], 0x20c0100
	v_readfirstlane_b32 s57, v135
	global_load_lds_dwordx4 v[162:163], off
	v_lshl_add_u64 v[162:163], v[234:235], 0, s[84:85]
	s_mov_b32 m0, s57
	s_nop 0
	global_load_lds_dwordx4 v[162:163], off
	v_lshl_add_u64 v[248:249], v[204:205], 0, s[22:23]
	v_lshl_add_u64 v[250:251], v[232:233], 0, s[22:23]
	s_waitcnt vmcnt(6)
	s_setprio 1
	s_barrier
	v_mfma_f32_16x16x32_bf16 v[28:31], v[178:181], v[216:219], v[28:31]
	v_mfma_f32_16x16x32_bf16 v[24:27], v[178:181], v[224:227], v[24:27]
	v_mfma_f32_16x16x32_bf16 v[20:23], v[186:189], v[216:219], v[20:23]
	v_mfma_f32_16x16x32_bf16 v[16:19], v[186:189], v[224:227], v[16:19]
	v_mfma_f32_16x16x32_bf16 v[12:15], v[196:199], v[216:219], v[12:15]
	v_mfma_f32_16x16x32_bf16 v[8:11], v[196:199], v[224:227], v[8:11]
	v_mfma_f32_16x16x32_bf16 v[4:7], v[208:211], v[216:219], v[4:7]
	v_mfma_f32_16x16x32_bf16 v[0:3], v[208:211], v[224:227], v[0:3]
	v_mfma_f32_16x16x32_bf16 v[28:31], v[182:185], v[220:223], v[28:31]
	v_mfma_f32_16x16x32_bf16 v[24:27], v[182:185], v[228:231], v[24:27]
	v_mfma_f32_16x16x32_bf16 v[20:23], v[190:193], v[220:223], v[20:23]
	v_mfma_f32_16x16x32_bf16 v[16:19], v[190:193], v[228:231], v[16:19]
	v_mfma_f32_16x16x32_bf16 v[12:15], v[200:203], v[220:223], v[12:15]
	v_mfma_f32_16x16x32_bf16 v[8:11], v[200:203], v[228:231], v[8:11]
	v_mfma_f32_16x16x32_bf16 v[4:7], v[212:215], v[220:223], v[4:7]
	v_mfma_f32_16x16x32_bf16 v[0:3], v[212:215], v[228:231], v[0:3]
	s_barrier
	s_setprio 0
	ds_read_b128 v[162:165], v145
	ds_read_b128 v[166:169], v145 offset:1024
	ds_read_b128 v[170:173], v145 offset:2048
	ds_read_b128 v[174:177], v145 offset:3072
	s_mov_b32 m0, s100
	ds_read_b128 v[178:181], v141 offset:32768
	ds_read_b128 v[182:185], v141 offset:33792
	ds_read_b128 v[186:189], v155 offset:32768
	ds_read_b128 v[190:193], v155 offset:33792
	ds_read_b128 v[196:199], v156 offset:32768
	ds_read_b128 v[200:203], v156 offset:33792
	ds_read_b128 v[208:211], v157 offset:32768
	ds_read_b128 v[212:215], v157 offset:33792
	global_load_lds_dwordx4 v[248:249], off
	s_mov_b32 m0, s101
	s_nop 0
	global_load_lds_dwordx4 v[250:251], off
	s_waitcnt lgkmcnt(8)
	s_setprio 1
	s_barrier
	s_waitcnt lgkmcnt(0)
	v_mfma_f32_16x16x32_bf16 v[124:127], v[178:181], v[162:165], v[124:127]
	v_mfma_f32_16x16x32_bf16 v[120:123], v[178:181], v[170:173], v[120:123]
	v_mfma_f32_16x16x32_bf16 v[116:119], v[186:189], v[162:165], v[116:119]
	v_mfma_f32_16x16x32_bf16 v[112:115], v[186:189], v[170:173], v[112:115]
	v_mfma_f32_16x16x32_bf16 v[108:111], v[196:199], v[162:165], v[108:111]
	v_mfma_f32_16x16x32_bf16 v[104:107], v[196:199], v[170:173], v[104:107]
	v_mfma_f32_16x16x32_bf16 v[100:103], v[208:211], v[162:165], v[100:103]
	v_mfma_f32_16x16x32_bf16 v[96:99], v[208:211], v[170:173], v[96:99]
	v_mfma_f32_16x16x32_bf16 v[124:127], v[182:185], v[166:169], v[124:127]
	v_mfma_f32_16x16x32_bf16 v[120:123], v[182:185], v[174:177], v[120:123]
	v_mfma_f32_16x16x32_bf16 v[116:119], v[190:193], v[166:169], v[116:119]
	v_mfma_f32_16x16x32_bf16 v[112:115], v[190:193], v[174:177], v[112:115]
	v_mfma_f32_16x16x32_bf16 v[108:111], v[200:203], v[166:169], v[108:111]
	v_mfma_f32_16x16x32_bf16 v[104:107], v[200:203], v[174:177], v[104:107]
	v_mfma_f32_16x16x32_bf16 v[100:103], v[212:215], v[166:169], v[100:103]
	v_mfma_f32_16x16x32_bf16 v[96:99], v[212:215], v[174:177], v[96:99]
	s_barrier
	s_setprio 0
	s_mov_b64 s[84:85], 0x2000180
	v_readfirstlane_b32 s57, v146
	v_lshl_add_u64 v[204:205], v[234:235], 0, s[84:85]
	s_mov_b32 m0, s57
	s_mov_b64 s[84:85], 0x2040180
	v_readfirstlane_b32 s57, v147
	ds_read_b128 v[216:219], v142
	ds_read_b128 v[220:223], v142 offset:1024
	ds_read_b128 v[224:227], v142 offset:2048
	ds_read_b128 v[228:231], v142 offset:3072
	global_load_lds_dwordx4 v[204:205], off
	v_lshl_add_u64 v[204:205], v[234:235], 0, s[84:85]
	s_mov_b32 m0, s57
	s_nop 0
	global_load_lds_dwordx4 v[204:205], off
	v_lshl_add_u64 v[252:253], v[236:237], 0, s[24:25]
	v_lshl_add_u64 v[254:255], v[238:239], 0, s[24:25]
	v_lshl_add_u64 v[204:205], v[238:239], 0, s[24:25]
	s_setprio 1
	s_barrier
	s_waitcnt lgkmcnt(0)
	v_mfma_f32_16x16x32_bf16 v[92:95], v[178:181], v[216:219], v[92:95]
	v_mfma_f32_16x16x32_bf16 v[88:91], v[178:181], v[224:227], v[88:91]
	v_mfma_f32_16x16x32_bf16 v[84:87], v[186:189], v[216:219], v[84:87]
	v_mfma_f32_16x16x32_bf16 v[80:83], v[186:189], v[224:227], v[80:83]
	v_mfma_f32_16x16x32_bf16 v[76:79], v[196:199], v[216:219], v[76:79]
	v_mfma_f32_16x16x32_bf16 v[72:75], v[196:199], v[224:227], v[72:75]
	v_mfma_f32_16x16x32_bf16 v[68:71], v[208:211], v[216:219], v[68:71]
	v_mfma_f32_16x16x32_bf16 v[64:67], v[208:211], v[224:227], v[64:67]
	v_mfma_f32_16x16x32_bf16 v[92:95], v[182:185], v[220:223], v[92:95]
	v_mfma_f32_16x16x32_bf16 v[88:91], v[182:185], v[228:231], v[88:91]
	v_mfma_f32_16x16x32_bf16 v[84:87], v[190:193], v[220:223], v[84:87]
	v_mfma_f32_16x16x32_bf16 v[80:83], v[190:193], v[228:231], v[80:83]
	v_mfma_f32_16x16x32_bf16 v[76:79], v[200:203], v[220:223], v[76:79]
	v_mfma_f32_16x16x32_bf16 v[72:75], v[200:203], v[228:231], v[72:75]
	v_mfma_f32_16x16x32_bf16 v[68:71], v[212:215], v[220:223], v[68:71]
	v_mfma_f32_16x16x32_bf16 v[64:67], v[212:215], v[228:231], v[64:67]
	s_barrier
; #define WAIT_V(n) asm volatile("s_waitcnt vmcnt(" #n ")" ::: "memory")
; #define WAIT_L(n) asm volatile("s_waitcnt lgkmcnt(" #n ")" ::: "memory")
; #define BAR __builtin_amdgcn_s_barrier()
; #define SCHED __builtin_amdgcn_sched_barrier(0)
; template <int EPI>
; __device__ __forceinline__ void gemm_tile(const Params& p, const bf16* __restrict__ A, const bf16* __restrict__ Bt, const int K,
;                                           const int nt, const int brow, const int bcol, int pm, int pn) {
;     ...
;   for (int t = 0; t < nt - 2; t += 2) {
;     LDB(B0, 0, 0); SCHED; LDA(At, 0, 0); STAGE(SA(1, 1), A, brow + HALF, t + 1);
;     WAIT_L(8); BAR; WAIT_L(0); MMA(0, 0, At, B0); BAR; SCHED;
;     LDB(B1, 0, 1); STAGE(SB(0, 0), Bt, bcol, t + 2);
;     BAR; WAIT_L(0); MMA(0, 1, At, B1); BAR;
;     LDA(At, 0, 1); STAGE(SA(0, 0), A, brow, t + 2);
;     BAR; WAIT_L(0); MMA(1, 0, At, B0); BAR; SCHED;
;     STAGE(SB(0, 1), Bt, bcol + HALF, t + 2);
;     WAIT_V(6); BAR; MMA(1, 1, At, B1); BAR;
;     LDB(B0, 1, 0); SCHED; LDA(At, 1, 0); STAGE(SA(0, 1), A, brow + HALF, t + 2);
;     WAIT_L(8); BAR; WAIT_L(0); MMA(0, 0, At, B0); BAR; SCHED;
;     LDB(B1, 1, 1); STAGE(SB(1, 0), Bt, bcol, t + 3);
;     BAR; WAIT_L(0); MMA(0, 1, At, B1); BAR;
;     LDA(At, 1, 1); STAGE(SA(1, 0), A, brow, t + 3);
;     BAR; WAIT_L(0); MMA(1, 0, At, B0); BAR; SCHED;
;     STAGE(SB(1, 1), Bt, bcol + HALF, t + 3);
;     WAIT_V(6); BAR; MMA(1, 1, At, B1); BAR;
;   }
;   { LDB(B0, 0, 0); LDA(At, 0, 0); STAGE(SA(1, 1), A, brow + HALF, nt - 1);
;     BAR; WAIT_L(0); MMA(0, 0, At, B0); BAR;
;     LDB(B1, 0, 1); BAR; WAIT_L(0); MMA(0, 1, At, B1); BAR;
;     LDA(At, 0, 1); WAIT_V(4); BAR; WAIT_L(0); MMA(1, 0, At, B0); MMA(1, 1, At, B1); BAR; }
	s_setprio 0
	s_mov_b32 m0, s97
	ds_read_b128 v[178:181], v141 offset:49152
	ds_read_b128 v[182:185], v141 offset:50176
	ds_read_b128 v[186:189], v155 offset:49152
	ds_read_b128 v[190:193], v155 offset:50176
	ds_read_b128 v[196:199], v156 offset:49152
	ds_read_b128 v[200:203], v156 offset:50176
	ds_read_b128 v[208:211], v157 offset:49152
	ds_read_b128 v[212:215], v157 offset:50176
	global_load_lds_dwordx4 v[252:253], off
	s_mov_b32 m0, s32
	s_nop 0
	global_load_lds_dwordx4 v[254:255], off
	s_setprio 1
	s_barrier
	s_waitcnt lgkmcnt(0)
	v_mfma_f32_16x16x32_bf16 v[60:63], v[178:181], v[162:165], v[60:63]
	v_mfma_f32_16x16x32_bf16 v[56:59], v[178:181], v[170:173], v[56:59]
	v_mfma_f32_16x16x32_bf16 v[52:55], v[186:189], v[162:165], v[52:55]
	v_mfma_f32_16x16x32_bf16 v[48:51], v[186:189], v[170:173], v[48:51]
	v_mfma_f32_16x16x32_bf16 v[44:47], v[196:199], v[162:165], v[44:47]
	v_mfma_f32_16x16x32_bf16 v[40:43], v[196:199], v[170:173], v[40:43]
	v_mfma_f32_16x16x32_bf16 v[36:39], v[208:211], v[162:165], v[36:39]
	v_mfma_f32_16x16x32_bf16 v[32:35], v[208:211], v[170:173], v[32:35]
	v_mfma_f32_16x16x32_bf16 v[60:63], v[182:185], v[166:169], v[60:63]
	v_mfma_f32_16x16x32_bf16 v[56:59], v[182:185], v[174:177], v[56:59]
	v_mfma_f32_16x16x32_bf16 v[52:55], v[190:193], v[166:169], v[52:55]
	v_mfma_f32_16x16x32_bf16 v[48:51], v[190:193], v[174:177], v[48:51]
	v_mfma_f32_16x16x32_bf16 v[44:47], v[200:203], v[166:169], v[44:47]
	v_mfma_f32_16x16x32_bf16 v[40:43], v[200:203], v[174:177], v[40:43]
	v_mfma_f32_16x16x32_bf16 v[36:39], v[212:215], v[166:169], v[36:39]
	v_mfma_f32_16x16x32_bf16 v[32:35], v[212:215], v[174:177], v[32:35]
	s_barrier
	s_setprio 0
	s_mov_b64 s[84:85], 0x2080180
	v_readfirstlane_b32 s57, v150
	v_lshl_add_u64 v[162:163], v[234:235], 0, s[84:85]
	s_mov_b32 m0, s57
	v_readfirstlane_b32 s57, v151
	global_load_lds_dwordx4 v[162:163], off
	v_lshl_add_u64 v[162:163], v[234:235], 0, s[26:27]
	s_mov_b32 m0, s57
	s_nop 0
	global_load_lds_dwordx4 v[162:163], off
	v_lshl_add_u64 v[204:205], s[42:43], 0, v[128:129]
	v_lshl_add_u64 v[246:247], v[204:205], 0, s[20:21]
	v_lshl_add_u64 v[232:233], s[48:49], 0, v[128:129]
	v_lshl_add_u64 v[244:245], v[232:233], 0, s[20:21]
	s_waitcnt vmcnt(6)
	s_setprio 1
	s_barrier
	v_mfma_f32_16x16x32_bf16 v[28:31], v[178:181], v[216:219], v[28:31]
	v_mfma_f32_16x16x32_bf16 v[24:27], v[178:181], v[224:227], v[24:27]
	v_mfma_f32_16x16x32_bf16 v[20:23], v[186:189], v[216:219], v[20:23]
	v_mfma_f32_16x16x32_bf16 v[16:19], v[186:189], v[224:227], v[16:19]
	v_mfma_f32_16x16x32_bf16 v[12:15], v[196:199], v[216:219], v[12:15]
	v_mfma_f32_16x16x32_bf16 v[8:11], v[196:199], v[224:227], v[8:11]
	v_mfma_f32_16x16x32_bf16 v[4:7], v[208:211], v[216:219], v[4:7]
	v_mfma_f32_16x16x32_bf16 v[0:3], v[208:211], v[224:227], v[0:3]
	v_mfma_f32_16x16x32_bf16 v[28:31], v[182:185], v[220:223], v[28:31]
	v_mfma_f32_16x16x32_bf16 v[24:27], v[182:185], v[228:231], v[24:27]
	v_mfma_f32_16x16x32_bf16 v[20:23], v[190:193], v[220:223], v[20:23]
	v_mfma_f32_16x16x32_bf16 v[16:19], v[190:193], v[228:231], v[16:19]
	v_mfma_f32_16x16x32_bf16 v[12:15], v[200:203], v[220:223], v[12:15]
	v_mfma_f32_16x16x32_bf16 v[8:11], v[200:203], v[228:231], v[8:11]
	v_mfma_f32_16x16x32_bf16 v[4:7], v[212:215], v[220:223], v[4:7]
	v_mfma_f32_16x16x32_bf16 v[0:3], v[212:215], v[228:231], v[0:3]
	s_barrier
	s_setprio 0
	s_cmp_lt_u32 s56, 28
	s_cbranch_scc1 .LBB0_1562
	s_add_u32 s4, s60, s4
	s_addc_u32 s5, s61, s5
	v_lshl_add_u64 v[150:151], s[4:5], 0, v[136:137]
	v_readfirstlane_b32 s4, v159
	s_mov_b32 m0, s4
	s_add_u32 s4, s60, s6
	v_lshl_add_u64 v[150:151], v[150:151], 0, s[28:29]
	s_addc_u32 s5, s61, s7
	ds_read_b128 v[128:131], v154
	ds_read_b128 v[132:135], v154 offset:1024
	ds_read_b128 v[146:149], v154 offset:2048
	ds_read_b128 v[162:165], v154 offset:3072
	ds_read_b128 v[166:169], v141
	ds_read_b128 v[170:173], v141 offset:1024
	ds_read_b128 v[174:177], v155
	ds_read_b128 v[178:181], v155 offset:1024
	ds_read_b128 v[182:185], v156
	ds_read_b128 v[186:189], v156 offset:1024
	ds_read_b128 v[190:193], v157
	ds_read_b128 v[196:199], v157 offset:1024
	global_load_lds_dwordx4 v[150:151], off
	v_lshl_add_u64 v[150:151], s[4:5], 0, v[136:137]
	v_readfirstlane_b32 s4, v158
	v_lshl_add_u64 v[150:151], v[150:151], 0, s[28:29]
	s_mov_b32 m0, s4
	s_nop 0
	global_load_lds_dwordx4 v[150:151], off
	s_setprio 1
	s_barrier
	s_waitcnt lgkmcnt(0)
	v_mfma_f32_16x16x32_bf16 v[124:127], v[166:169], v[128:131], v[124:127]
	v_mfma_f32_16x16x32_bf16 v[120:123], v[166:169], v[146:149], v[120:123]
	v_mfma_f32_16x16x32_bf16 v[116:119], v[174:177], v[128:131], v[116:119]
	v_mfma_f32_16x16x32_bf16 v[112:115], v[174:177], v[146:149], v[112:115]
	v_mfma_f32_16x16x32_bf16 v[108:111], v[182:185], v[128:131], v[108:111]
	v_mfma_f32_16x16x32_bf16 v[104:107], v[182:185], v[146:149], v[104:107]
	v_mfma_f32_16x16x32_bf16 v[124:127], v[170:173], v[132:135], v[124:127]
	v_mfma_f32_16x16x32_bf16 v[120:123], v[170:173], v[162:165], v[120:123]
	v_mfma_f32_16x16x32_bf16 v[116:119], v[178:181], v[132:135], v[116:119]
	v_mfma_f32_16x16x32_bf16 v[112:115], v[178:181], v[162:165], v[112:115]
	v_mfma_f32_16x16x32_bf16 v[108:111], v[186:189], v[132:135], v[108:111]
	v_mfma_f32_16x16x32_bf16 v[104:107], v[186:189], v[162:165], v[104:107]
	v_mfma_f32_16x16x32_bf16 v[100:103], v[190:193], v[128:131], v[100:103]
	v_mfma_f32_16x16x32_bf16 v[96:99], v[190:193], v[146:149], v[96:99]
	v_mfma_f32_16x16x32_bf16 v[100:103], v[196:199], v[132:135], v[100:103]
	v_mfma_f32_16x16x32_bf16 v[96:99], v[196:199], v[162:165], v[96:99]
	s_barrier
; #define WAIT_V(n) asm volatile("s_waitcnt vmcnt(" #n ")" ::: "memory")
; #define WAIT_L(n) asm volatile("s_waitcnt lgkmcnt(" #n ")" ::: "memory")
; #define BAR __builtin_amdgcn_s_barrier()
; template <int EPI>
; __device__ __forceinline__ void gemm_tile(const Params& p, const bf16* __restrict__ A, const bf16* __restrict__ Bt, const int K,
;                                           const int nt, const int brow, const int bcol, int pm, int pn) {
;     ...
;   { LDB(B0, 0, 0); LDA(At, 0, 0); STAGE(SA(1, 1), A, brow + HALF, nt - 1);
;     BAR; WAIT_L(0); MMA(0, 0, At, B0); BAR;
;     LDB(B1, 0, 1); BAR; WAIT_L(0); MMA(0, 1, At, B1); BAR;
;     LDA(At, 0, 1); WAIT_V(4); BAR; WAIT_L(0); MMA(1, 0, At, B0); MMA(1, 1, At, B1); BAR; }
;   { LDB(B0, 1, 0); LDA(At, 1, 0); WAIT_V(2); BAR; WAIT_L(0); MMA(0, 0, At, B0); BAR;
;     LDB(B1, 1, 1); WAIT_V(0); BAR; WAIT_L(0); MMA(0, 1, At, B1); BAR;
;     LDA(At, 1, 1); BAR; WAIT_L(0); MMA(1, 0, At, B0); MMA(1, 1, At, B1); BAR; }
	s_setprio 0
	ds_read_b128 v[200:203], v152
	ds_read_b128 v[208:211], v152 offset:1024
	ds_read_b128 v[212:215], v152 offset:2048
	ds_read_b128 v[150:153], v152 offset:3072
	s_setprio 1
	s_barrier
	s_waitcnt lgkmcnt(0)
	v_mfma_f32_16x16x32_bf16 v[92:95], v[166:169], v[200:203], v[92:95]
	v_mfma_f32_16x16x32_bf16 v[88:91], v[166:169], v[212:215], v[88:91]
	v_mfma_f32_16x16x32_bf16 v[68:71], v[190:193], v[200:203], v[68:71]
	v_mfma_f32_16x16x32_bf16 v[92:95], v[170:173], v[208:211], v[92:95]
	v_mfma_f32_16x16x32_bf16 v[88:91], v[170:173], v[150:153], v[88:91]
	v_mfma_f32_16x16x32_bf16 v[84:87], v[174:177], v[200:203], v[84:87]
	v_mfma_f32_16x16x32_bf16 v[80:83], v[174:177], v[212:215], v[80:83]
	v_mfma_f32_16x16x32_bf16 v[76:79], v[182:185], v[200:203], v[76:79]
	v_mfma_f32_16x16x32_bf16 v[72:75], v[182:185], v[212:215], v[72:75]
	v_mfma_f32_16x16x32_bf16 v[68:71], v[196:199], v[208:211], v[68:71]
	v_mfma_f32_16x16x32_bf16 v[64:67], v[190:193], v[212:215], v[64:67]
	v_mfma_f32_16x16x32_bf16 v[166:169], v[178:181], v[208:211], v[84:87]
	v_mfma_f32_16x16x32_bf16 v[170:173], v[178:181], v[150:153], v[80:83]
	v_mfma_f32_16x16x32_bf16 v[174:177], v[186:189], v[208:211], v[76:79]
	v_mfma_f32_16x16x32_bf16 v[178:181], v[186:189], v[150:153], v[72:75]
	v_mfma_f32_16x16x32_bf16 v[182:185], v[196:199], v[150:153], v[64:67]
	s_barrier
	s_setprio 0
	s_nop 0
	ds_read_b128 v[64:67], v141 offset:16384
	ds_read_b128 v[72:75], v141 offset:17408
	ds_read_b128 v[76:79], v155 offset:16384
	ds_read_b128 v[80:83], v155 offset:17408
	ds_read_b128 v[84:87], v156 offset:16384
	ds_read_b128 v[186:189], v156 offset:17408
	ds_read_b128 v[190:193], v157 offset:16384
	ds_read_b128 v[196:199], v157 offset:17408
	s_waitcnt vmcnt(4)
	s_setprio 1
	s_barrier
	s_waitcnt lgkmcnt(0)
	v_mfma_f32_16x16x32_bf16 v[60:63], v[64:67], v[128:131], v[60:63]
	v_mfma_f32_16x16x32_bf16 v[52:55], v[76:79], v[128:131], v[52:55]
	v_mfma_f32_16x16x32_bf16 v[44:47], v[84:87], v[128:131], v[44:47]
	v_mfma_f32_16x16x32_bf16 v[36:39], v[190:193], v[128:131], v[36:39]
	v_mfma_f32_16x16x32_bf16 v[32:35], v[190:193], v[146:149], v[32:35]
	v_mfma_f32_16x16x32_bf16 v[60:63], v[72:75], v[132:135], v[60:63]
	v_mfma_f32_16x16x32_bf16 v[56:59], v[64:67], v[146:149], v[56:59]
	v_mfma_f32_16x16x32_bf16 v[52:55], v[80:83], v[132:135], v[52:55]
	v_mfma_f32_16x16x32_bf16 v[48:51], v[76:79], v[146:149], v[48:51]
	v_mfma_f32_16x16x32_bf16 v[44:47], v[186:189], v[132:135], v[44:47]
	v_mfma_f32_16x16x32_bf16 v[40:43], v[84:87], v[146:149], v[40:43]
	v_mfma_f32_16x16x32_bf16 v[36:39], v[196:199], v[132:135], v[36:39]
	v_mfma_f32_16x16x32_bf16 v[32:35], v[196:199], v[162:165], v[32:35]
	v_mfma_f32_16x16x32_bf16 v[216:219], v[72:75], v[162:165], v[56:59]
	v_mfma_f32_16x16x32_bf16 v[220:223], v[80:83], v[162:165], v[48:51]
	v_mfma_f32_16x16x32_bf16 v[224:227], v[186:189], v[162:165], v[40:43]
	s_setprio 0
	s_setprio 1
	v_mfma_f32_16x16x32_bf16 v[28:31], v[64:67], v[200:203], v[28:31]
	v_mfma_f32_16x16x32_bf16 v[24:27], v[64:67], v[212:215], v[24:27]
	v_mfma_f32_16x16x32_bf16 v[20:23], v[76:79], v[200:203], v[20:23]
	v_mfma_f32_16x16x32_bf16 v[16:19], v[76:79], v[212:215], v[16:19]
	v_mfma_f32_16x16x32_bf16 v[4:7], v[190:193], v[200:203], v[4:7]
	v_mfma_f32_16x16x32_bf16 v[28:31], v[72:75], v[208:211], v[28:31]
	v_mfma_f32_16x16x32_bf16 v[24:27], v[72:75], v[150:153], v[24:27]
	v_mfma_f32_16x16x32_bf16 v[20:23], v[80:83], v[208:211], v[20:23]
	v_mfma_f32_16x16x32_bf16 v[16:19], v[80:83], v[150:153], v[16:19]
	v_mfma_f32_16x16x32_bf16 v[12:15], v[84:87], v[200:203], v[12:15]
	v_mfma_f32_16x16x32_bf16 v[8:11], v[84:87], v[212:215], v[8:11]
	v_mfma_f32_16x16x32_bf16 v[4:7], v[196:199], v[208:211], v[4:7]
	v_mfma_f32_16x16x32_bf16 v[0:3], v[190:193], v[212:215], v[0:3]
	v_mfma_f32_16x16x32_bf16 v[146:149], v[186:189], v[208:211], v[12:15]
	v_mfma_f32_16x16x32_bf16 v[162:165], v[186:189], v[150:153], v[8:11]
	v_mfma_f32_16x16x32_bf16 v[150:153], v[196:199], v[150:153], v[0:3]
	s_barrier
	s_setprio 0
	s_nop 2
	ds_read_b128 v[0:3], v145
	ds_read_b128 v[8:11], v145 offset:1024
	ds_read_b128 v[12:15], v145 offset:2048
	ds_read_b128 v[186:189], v145 offset:3072
	ds_read_b128 v[40:43], v141 offset:32768
	ds_read_b128 v[48:51], v141 offset:33792
	ds_read_b128 v[56:59], v155 offset:32768
	ds_read_b128 v[64:67], v155 offset:33792
	ds_read_b128 v[190:193], v156 offset:32768
	ds_read_b128 v[196:199], v156 offset:33792
	ds_read_b128 v[200:203], v157 offset:32768
	ds_read_b128 v[208:211], v157 offset:33792
	s_waitcnt vmcnt(2)
	s_setprio 1
	s_barrier
; #define WAIT_V(n) asm volatile("s_waitcnt vmcnt(" #n ")" ::: "memory")
; #define WAIT_L(n) asm volatile("s_waitcnt lgkmcnt(" #n ")" ::: "memory")
; #define BAR __builtin_amdgcn_s_barrier()
; template <int EPI>
; __device__ __forceinline__ void gemm_tile(const Params& p, const bf16* __restrict__ A, const bf16* __restrict__ Bt, const int K,
;                                           const int nt, const int brow, const int bcol, int pm, int pn) {
;     ...
;     LDA(At, 0, 1); WAIT_V(4); BAR; WAIT_L(0); MMA(1, 0, At, B0); MMA(1, 1, At, B1); BAR; }
;   { LDB(B0, 1, 0); LDA(At, 1, 0); WAIT_V(2); BAR; WAIT_L(0); MMA(0, 0, At, B0); BAR;
;     LDB(B1, 1, 1); WAIT_V(0); BAR; WAIT_L(0); MMA(0, 1, At, B1); BAR;
;     LDA(At, 1, 1); BAR; WAIT_L(0); MMA(1, 0, At, B0); MMA(1, 1, At, B1); BAR; }
;   if (wr == 0) BAR;
	s_waitcnt lgkmcnt(0)
	v_mfma_f32_16x16x32_bf16 v[72:75], v[40:43], v[0:3], v[124:127]
	v_mfma_f32_16x16x32_bf16 v[80:83], v[48:51], v[8:11], v[72:75]
	v_mfma_f32_16x16x32_bf16 v[72:75], v[40:43], v[12:15], v[120:123]
	v_mfma_f32_16x16x32_bf16 v[132:135], v[48:51], v[186:189], v[72:75]
	v_mfma_f32_16x16x32_bf16 v[72:75], v[56:59], v[0:3], v[116:119]
	v_mfma_f32_16x16x32_bf16 v[84:87], v[64:67], v[8:11], v[72:75]
	v_mfma_f32_16x16x32_bf16 v[72:75], v[56:59], v[12:15], v[112:115]
	v_mfma_f32_16x16x32_bf16 v[128:131], v[64:67], v[186:189], v[72:75]
	v_mfma_f32_16x16x32_bf16 v[72:75], v[190:193], v[0:3], v[108:111]
	v_mfma_f32_16x16x32_bf16 v[120:123], v[196:199], v[8:11], v[72:75]
	v_mfma_f32_16x16x32_bf16 v[72:75], v[190:193], v[12:15], v[104:107]
	v_mfma_f32_16x16x32_bf16 v[124:127], v[196:199], v[186:189], v[72:75]
	v_mfma_f32_16x16x32_bf16 v[72:75], v[200:203], v[0:3], v[100:103]
	v_mfma_f32_16x16x32_bf16 v[116:119], v[208:211], v[8:11], v[72:75]
	v_mfma_f32_16x16x32_bf16 v[72:75], v[200:203], v[12:15], v[96:99]
	v_mfma_f32_16x16x32_bf16 v[112:115], v[208:211], v[186:189], v[72:75]
	s_barrier
	s_setprio 0
	ds_read_b128 v[96:99], v142
	ds_read_b128 v[100:103], v142 offset:1024
	ds_read_b128 v[212:215], v142 offset:2048
	ds_read_b128 v[142:145], v142 offset:3072
	s_waitcnt vmcnt(0)
	s_setprio 1
	s_barrier
	s_waitcnt lgkmcnt(0)
	v_mfma_f32_16x16x32_bf16 v[72:75], v[40:43], v[96:99], v[92:95]
	v_mfma_f32_16x16x32_bf16 v[40:43], v[40:43], v[212:215], v[88:91]
	v_mfma_f32_16x16x32_bf16 v[108:111], v[48:51], v[142:145], v[40:43]
	v_mfma_f32_16x16x32_bf16 v[40:43], v[56:59], v[96:99], v[166:169]
	v_mfma_f32_16x16x32_bf16 v[76:79], v[64:67], v[100:103], v[40:43]
	v_mfma_f32_16x16x32_bf16 v[40:43], v[56:59], v[212:215], v[170:173]
	v_mfma_f32_16x16x32_bf16 v[104:107], v[64:67], v[142:145], v[40:43]
	v_mfma_f32_16x16x32_bf16 v[40:43], v[190:193], v[96:99], v[174:177]
	v_mfma_f32_16x16x32_bf16 v[92:95], v[196:199], v[100:103], v[40:43]
	v_mfma_f32_16x16x32_bf16 v[40:43], v[190:193], v[212:215], v[178:181]
	v_mfma_f32_16x16x32_bf16 v[64:67], v[196:199], v[142:145], v[40:43]
	v_mfma_f32_16x16x32_bf16 v[40:43], v[200:203], v[96:99], v[68:71]
	v_mfma_f32_16x16x32_bf16 v[88:91], v[208:211], v[100:103], v[40:43]
	v_mfma_f32_16x16x32_bf16 v[40:43], v[200:203], v[212:215], v[182:185]
	v_mfma_f32_16x16x32_bf16 v[72:75], v[48:51], v[100:103], v[72:75]
	v_mfma_f32_16x16x32_bf16 v[68:71], v[208:211], v[142:145], v[40:43]
	s_barrier
	s_setprio 0
	ds_read_b128 v[166:169], v141 offset:49152
	ds_read_b128 v[170:173], v141 offset:50176
	ds_read_b128 v[174:177], v155 offset:49152
	ds_read_b128 v[178:181], v155 offset:50176
	ds_read_b128 v[182:185], v156 offset:49152
	ds_read_b128 v[190:193], v156 offset:50176
	ds_read_b128 v[196:199], v157 offset:49152
	ds_read_b128 v[154:157], v157 offset:50176
	s_setprio 1
	s_barrier
	s_waitcnt lgkmcnt(0)
	v_mfma_f32_16x16x32_bf16 v[40:43], v[166:169], v[0:3], v[60:63]
	v_mfma_f32_16x16x32_bf16 v[56:59], v[170:173], v[8:11], v[40:43]
	v_mfma_f32_16x16x32_bf16 v[40:43], v[166:169], v[12:15], v[216:219]
	v_mfma_f32_16x16x32_bf16 v[60:63], v[170:173], v[186:189], v[40:43]
	v_mfma_f32_16x16x32_bf16 v[40:43], v[174:177], v[0:3], v[52:55]
	v_mfma_f32_16x16x32_bf16 v[48:51], v[178:181], v[8:11], v[40:43]
	v_mfma_f32_16x16x32_bf16 v[40:43], v[174:177], v[12:15], v[220:223]
	v_mfma_f32_16x16x32_bf16 v[52:55], v[178:181], v[186:189], v[40:43]
	v_mfma_f32_16x16x32_bf16 v[40:43], v[182:185], v[0:3], v[44:47]
	v_mfma_f32_16x16x32_bf16 v[0:3], v[196:199], v[0:3], v[36:39]
	v_mfma_f32_16x16x32_bf16 v[44:47], v[182:185], v[12:15], v[224:227]
	v_mfma_f32_16x16x32_bf16 v[36:39], v[154:157], v[8:11], v[0:3]
	v_mfma_f32_16x16x32_bf16 v[0:3], v[196:199], v[12:15], v[32:35]
	v_mfma_f32_16x16x32_bf16 v[40:43], v[190:193], v[8:11], v[40:43]
	v_mfma_f32_16x16x32_bf16 v[44:47], v[190:193], v[186:189], v[44:47]
	v_mfma_f32_16x16x32_bf16 v[32:35], v[154:157], v[186:189], v[0:3]
	s_setprio 0
	s_setprio 1
	v_mfma_f32_16x16x32_bf16 v[0:3], v[166:169], v[96:99], v[28:31]
	v_mfma_f32_16x16x32_bf16 v[8:11], v[170:173], v[100:103], v[0:3]
	v_mfma_f32_16x16x32_bf16 v[0:3], v[166:169], v[212:215], v[24:27]
	v_mfma_f32_16x16x32_bf16 v[28:31], v[170:173], v[142:145], v[0:3]
	v_mfma_f32_16x16x32_bf16 v[0:3], v[174:177], v[96:99], v[20:23]
	v_mfma_f32_16x16x32_bf16 v[12:15], v[178:181], v[100:103], v[0:3]
	v_mfma_f32_16x16x32_bf16 v[0:3], v[174:177], v[212:215], v[16:19]
	v_mfma_f32_16x16x32_bf16 v[24:27], v[178:181], v[142:145], v[0:3]
	v_mfma_f32_16x16x32_bf16 v[0:3], v[182:185], v[96:99], v[146:149]
	v_mfma_f32_16x16x32_bf16 v[4:7], v[196:199], v[96:99], v[4:7]
	v_mfma_f32_16x16x32_bf16 v[20:23], v[190:193], v[100:103], v[0:3]
	v_mfma_f32_16x16x32_bf16 v[0:3], v[182:185], v[212:215], v[162:165]
	v_mfma_f32_16x16x32_bf16 v[16:19], v[154:157], v[100:103], v[4:7]
	v_mfma_f32_16x16x32_bf16 v[4:7], v[196:199], v[212:215], v[150:153]
	v_mfma_f32_16x16x32_bf16 v[0:3], v[190:193], v[142:145], v[0:3]
	v_mfma_f32_16x16x32_bf16 v[4:7], v[154:157], v[142:145], v[4:7]
	s_barrier
	s_setprio 0
	s_cmpk_gt_u32 s94, 0xff
	s_cbranch_scc1 .LBB0_1565
	s_barrier

; #define WAIT_V(n) asm volatile("s_waitcnt vmcnt(" #n ")" ::: "memory")
; #define WAIT_L(n) asm volatile("s_waitcnt lgkmcnt(" #n ")" ::: "memory")
; #define BAR __builtin_amdgcn_s_barrier()
; #define SCHED __builtin_amdgcn_sched_barrier(0)
; template <int EPI>
; __device__ __forceinline__ void gemm_tile(const Params& p, const bf16* __restrict__ A, const bf16* __restrict__ Bt, const int K,
;                                           const int nt, const int brow, const int bcol, int pm, int pn) {
;     ...
;   for (int t = 0; t < nt - 2; t += 2) {
;     LDB(B0, 0, 0); SCHED; LDA(At, 0, 0); STAGE(SA(1, 1), A, brow + HALF, t + 1);
;     WAIT_L(8); BAR; WAIT_L(0); MMA(0, 0, At, B0); BAR; SCHED;
;     LDB(B1, 0, 1); STAGE(SB(0, 0), Bt, bcol, t + 2);
;     BAR; WAIT_L(0); MMA(0, 1, At, B1); BAR;
;     LDA(At, 0, 1); STAGE(SA(0, 0), A, brow, t + 2);
;     BAR; WAIT_L(0); MMA(1, 0, At, B0); BAR; SCHED;
;     STAGE(SB(0, 1), Bt, bcol + HALF, t + 2);
;     WAIT_V(6); BAR; MMA(1, 1, At, B1); BAR;
;     LDB(B0, 1, 0); SCHED; LDA(At, 1, 0); STAGE(SA(0, 1), A, brow + HALF, t + 2);
;     WAIT_L(8); BAR; WAIT_L(0); MMA(0, 0, At, B0); BAR; SCHED;
;     LDB(B1, 1, 1); STAGE(SB(1, 0), Bt, bcol, t + 3);
;     BAR; WAIT_L(0); MMA(0, 1, At, B1); BAR;
;     LDA(At, 1, 1); STAGE(SA(1, 0), A, brow, t + 3);
;     BAR; WAIT_L(0); MMA(1, 0, At, B0); BAR; SCHED;
;     STAGE(SB(1, 1), Bt, bcol + HALF, t + 3);
;     WAIT_V(6); BAR; MMA(1, 1, At, B1); BAR;
;   }
.LBB0_1704:
	ds_read_b128 v[158:161], v155
	ds_read_b128 v[162:165], v155 offset:1024
	ds_read_b128 v[166:169], v155 offset:2048
	ds_read_b128 v[170:173], v155 offset:3072
	s_mov_b32 m0, s99
	ds_read_b128 v[174:177], v137
	ds_read_b128 v[178:181], v137 offset:1024
	ds_read_b128 v[182:185], v136
	ds_read_b128 v[186:189], v136 offset:1024
	ds_read_b128 v[190:193], v135
	ds_read_b128 v[196:199], v135 offset:1024
	ds_read_b128 v[200:203], v133
	ds_read_b128 v[208:211], v133 offset:1024
	global_load_lds_dwordx4 v[246:247], off
	s_mov_b32 m0, s98
	s_nop 0
	global_load_lds_dwordx4 v[244:245], off
	s_waitcnt lgkmcnt(8)
	s_setprio 1
	s_barrier
	s_waitcnt lgkmcnt(0)
	v_mfma_f32_16x16x32_bf16 v[124:127], v[174:177], v[158:161], v[124:127]
	v_mfma_f32_16x16x32_bf16 v[120:123], v[174:177], v[166:169], v[120:123]
	v_mfma_f32_16x16x32_bf16 v[116:119], v[182:185], v[158:161], v[116:119]
	v_mfma_f32_16x16x32_bf16 v[112:115], v[182:185], v[166:169], v[112:115]
	v_mfma_f32_16x16x32_bf16 v[108:111], v[190:193], v[158:161], v[108:111]
	v_mfma_f32_16x16x32_bf16 v[104:107], v[190:193], v[166:169], v[104:107]
	v_mfma_f32_16x16x32_bf16 v[100:103], v[200:203], v[158:161], v[100:103]
	v_mfma_f32_16x16x32_bf16 v[96:99], v[200:203], v[166:169], v[96:99]
	v_mfma_f32_16x16x32_bf16 v[124:127], v[178:181], v[162:165], v[124:127]
	v_mfma_f32_16x16x32_bf16 v[120:123], v[178:181], v[170:173], v[120:123]
	v_mfma_f32_16x16x32_bf16 v[116:119], v[186:189], v[162:165], v[116:119]
	v_mfma_f32_16x16x32_bf16 v[112:115], v[186:189], v[170:173], v[112:115]
	v_mfma_f32_16x16x32_bf16 v[108:111], v[196:199], v[162:165], v[108:111]
	v_mfma_f32_16x16x32_bf16 v[104:107], v[196:199], v[170:173], v[104:107]
	v_mfma_f32_16x16x32_bf16 v[100:103], v[208:211], v[162:165], v[100:103]
	v_mfma_f32_16x16x32_bf16 v[96:99], v[208:211], v[170:173], v[96:99]
	s_barrier
	s_setprio 0
	v_lshl_add_u64 v[228:229], s[68:69], 0, v[130:131]
	s_mov_b64 s[84:85], 0x4c00100
	v_lshl_add_u64 v[230:231], v[228:229], 0, s[84:85]
	v_readfirstlane_b32 s84, v132
	s_mov_b32 m0, s84
	s_mov_b64 s[84:85], 0x4cb0100
	ds_read_b128 v[212:215], v151
	ds_read_b128 v[216:219], v151 offset:1024
	ds_read_b128 v[220:223], v151 offset:2048
	ds_read_b128 v[224:227], v151 offset:3072
	global_load_lds_dwordx4 v[230:231], off
	v_lshl_add_u64 v[230:231], v[228:229], 0, s[84:85]
	v_readfirstlane_b32 s84, v134
	s_mov_b32 m0, s84
	s_nop 0
	global_load_lds_dwordx4 v[230:231], off
	s_mov_b64 s[84:85], 0x12502100
	v_lshl_add_u64 v[252:253], v[204:205], 0, s[84:85]
	s_mov_b64 s[84:85], 0x125b2100
	v_lshl_add_u64 v[254:255], v[204:205], 0, s[84:85]
	v_lshl_add_u64 v[230:231], v[204:205], 0, s[84:85]
	v_readfirstlane_b32 s84, v138
	s_mov_b32 m0, s84
	s_setprio 1
	s_barrier
	s_waitcnt lgkmcnt(0)
	v_mfma_f32_16x16x32_bf16 v[92:95], v[174:177], v[212:215], v[92:95]
	v_mfma_f32_16x16x32_bf16 v[88:91], v[174:177], v[220:223], v[88:91]
	v_mfma_f32_16x16x32_bf16 v[84:87], v[182:185], v[212:215], v[84:87]
	v_mfma_f32_16x16x32_bf16 v[80:83], v[182:185], v[220:223], v[80:83]
	v_mfma_f32_16x16x32_bf16 v[76:79], v[190:193], v[212:215], v[76:79]
	v_mfma_f32_16x16x32_bf16 v[72:75], v[190:193], v[220:223], v[72:75]
	v_mfma_f32_16x16x32_bf16 v[68:71], v[200:203], v[212:215], v[68:71]
	v_mfma_f32_16x16x32_bf16 v[64:67], v[200:203], v[220:223], v[64:67]
	v_mfma_f32_16x16x32_bf16 v[92:95], v[178:181], v[216:219], v[92:95]
	v_mfma_f32_16x16x32_bf16 v[88:91], v[178:181], v[224:227], v[88:91]
	v_mfma_f32_16x16x32_bf16 v[84:87], v[186:189], v[216:219], v[84:87]
	v_mfma_f32_16x16x32_bf16 v[80:83], v[186:189], v[224:227], v[80:83]
	v_mfma_f32_16x16x32_bf16 v[76:79], v[196:199], v[216:219], v[76:79]
	v_mfma_f32_16x16x32_bf16 v[72:75], v[196:199], v[224:227], v[72:75]
	v_mfma_f32_16x16x32_bf16 v[68:71], v[208:211], v[216:219], v[68:71]
	v_mfma_f32_16x16x32_bf16 v[64:67], v[208:211], v[224:227], v[64:67]
	s_barrier
	s_setprio 0
	ds_read_b128 v[174:177], v137 offset:16384
	ds_read_b128 v[178:181], v137 offset:17408
	ds_read_b128 v[182:185], v136 offset:16384
	ds_read_b128 v[186:189], v136 offset:17408
	ds_read_b128 v[190:193], v135 offset:16384
	ds_read_b128 v[196:199], v135 offset:17408
	ds_read_b128 v[200:203], v133 offset:16384
	ds_read_b128 v[208:211], v133 offset:17408
	global_load_lds_dwordx4 v[252:253], off
	v_readfirstlane_b32 s84, v139
	s_mov_b32 m0, s84
	s_nop 0
	global_load_lds_dwordx4 v[254:255], off
	s_setprio 1
	s_barrier
	s_waitcnt lgkmcnt(0)
	v_mfma_f32_16x16x32_bf16 v[60:63], v[174:177], v[158:161], v[60:63]
	v_mfma_f32_16x16x32_bf16 v[56:59], v[174:177], v[166:169], v[56:59]
	v_mfma_f32_16x16x32_bf16 v[52:55], v[182:185], v[158:161], v[52:55]
	v_mfma_f32_16x16x32_bf16 v[48:51], v[182:185], v[166:169], v[48:51]
	v_mfma_f32_16x16x32_bf16 v[44:47], v[190:193], v[158:161], v[44:47]
	v_mfma_f32_16x16x32_bf16 v[40:43], v[190:193], v[166:169], v[40:43]
	v_mfma_f32_16x16x32_bf16 v[36:39], v[200:203], v[158:161], v[36:39]
	v_mfma_f32_16x16x32_bf16 v[32:35], v[200:203], v[166:169], v[32:35]
	v_mfma_f32_16x16x32_bf16 v[60:63], v[178:181], v[162:165], v[60:63]
	v_mfma_f32_16x16x32_bf16 v[56:59], v[178:181], v[170:173], v[56:59]
	v_mfma_f32_16x16x32_bf16 v[52:55], v[186:189], v[162:165], v[52:55]
	v_mfma_f32_16x16x32_bf16 v[48:51], v[186:189], v[170:173], v[48:51]
	v_mfma_f32_16x16x32_bf16 v[44:47], v[196:199], v[162:165], v[44:47]
	v_mfma_f32_16x16x32_bf16 v[40:43], v[196:199], v[170:173], v[40:43]
	v_mfma_f32_16x16x32_bf16 v[36:39], v[208:211], v[162:165], v[36:39]
	v_mfma_f32_16x16x32_bf16 v[32:35], v[208:211], v[170:173], v[32:35]
	s_barrier
; #define WAIT_V(n) asm volatile("s_waitcnt vmcnt(" #n ")" ::: "memory")
; #define WAIT_L(n) asm volatile("s_waitcnt lgkmcnt(" #n ")" ::: "memory")
; #define BAR __builtin_amdgcn_s_barrier()
; #define SCHED __builtin_amdgcn_sched_barrier(0)
; template <int EPI>
; __device__ __forceinline__ void gemm_tile(const Params& p, const bf16* __restrict__ A, const bf16* __restrict__ Bt, const int K,
;                                           const int nt, const int brow, const int bcol, int pm, int pn) {
;     ...
;   for (int t = 0; t < nt - 2; t += 2) {
;     LDB(B0, 0, 0); SCHED; LDA(At, 0, 0); STAGE(SA(1, 1), A, brow + HALF, t + 1);
;     WAIT_L(8); BAR; WAIT_L(0); MMA(0, 0, At, B0); BAR; SCHED;
;     LDB(B1, 0, 1); STAGE(SB(0, 0), Bt, bcol, t + 2);
;     BAR; WAIT_L(0); MMA(0, 1, At, B1); BAR;
;     LDA(At, 0, 1); STAGE(SA(0, 0), A, brow, t + 2);
;     BAR; WAIT_L(0); MMA(1, 0, At, B0); BAR; SCHED;
;     STAGE(SB(0, 1), Bt, bcol + HALF, t + 2);
;     WAIT_V(6); BAR; MMA(1, 1, At, B1); BAR;
;     LDB(B0, 1, 0); SCHED; LDA(At, 1, 0); STAGE(SA(0, 1), A, brow + HALF, t + 2);
;     WAIT_L(8); BAR; WAIT_L(0); MMA(0, 0, At, B0); BAR; SCHED;
;     LDB(B1, 1, 1); STAGE(SB(1, 0), Bt, bcol, t + 3);
;     BAR; WAIT_L(0); MMA(0, 1, At, B1); BAR;
;     LDA(At, 1, 1); STAGE(SA(1, 0), A, brow, t + 3);
;     BAR; WAIT_L(0); MMA(1, 0, At, B0); BAR; SCHED;
;     STAGE(SB(1, 1), Bt, bcol + HALF, t + 3);
;     WAIT_V(6); BAR; MMA(1, 1, At, B1); BAR;
;   }
	s_setprio 0
	s_add_i32 s88, s88, 2
	s_add_u32 s68, s68, 0x100
	s_addc_u32 s69, s69, 0
	s_add_u32 s70, s70, 0x100
	s_addc_u32 s71, s71, 0
	s_mov_b64 s[84:85], 0x4d60100
	v_lshl_add_u64 v[158:159], v[228:229], 0, s[84:85]
	v_readfirstlane_b32 s84, v140
	s_mov_b32 m0, s84
	s_mov_b64 s[84:85], 0x4e10100
	global_load_lds_dwordx4 v[158:159], off
	v_lshl_add_u64 v[158:159], v[228:229], 0, s[84:85]
	v_readfirstlane_b32 s84, v141
	s_mov_b32 m0, s84
	s_nop 0
	global_load_lds_dwordx4 v[158:159], off
	s_mov_b64 s[84:85], 0x12662100
	v_lshl_add_u64 v[248:249], v[204:205], 0, s[84:85]
	s_mov_b64 s[84:85], 0x12712100
	v_lshl_add_u64 v[250:251], v[204:205], 0, s[84:85]
	s_waitcnt vmcnt(6)
	s_setprio 1
	s_barrier
	v_mfma_f32_16x16x32_bf16 v[28:31], v[174:177], v[212:215], v[28:31]
	v_mfma_f32_16x16x32_bf16 v[24:27], v[174:177], v[220:223], v[24:27]
	v_mfma_f32_16x16x32_bf16 v[20:23], v[182:185], v[212:215], v[20:23]
	v_mfma_f32_16x16x32_bf16 v[16:19], v[182:185], v[220:223], v[16:19]
	v_mfma_f32_16x16x32_bf16 v[12:15], v[190:193], v[212:215], v[12:15]
	v_mfma_f32_16x16x32_bf16 v[8:11], v[190:193], v[220:223], v[8:11]
	v_mfma_f32_16x16x32_bf16 v[4:7], v[200:203], v[212:215], v[4:7]
	v_mfma_f32_16x16x32_bf16 v[0:3], v[200:203], v[220:223], v[0:3]
	v_mfma_f32_16x16x32_bf16 v[28:31], v[178:181], v[216:219], v[28:31]
	v_mfma_f32_16x16x32_bf16 v[24:27], v[178:181], v[224:227], v[24:27]
	v_mfma_f32_16x16x32_bf16 v[20:23], v[186:189], v[216:219], v[20:23]
	v_mfma_f32_16x16x32_bf16 v[16:19], v[186:189], v[224:227], v[16:19]
	v_mfma_f32_16x16x32_bf16 v[12:15], v[196:199], v[216:219], v[12:15]
	v_mfma_f32_16x16x32_bf16 v[8:11], v[196:199], v[224:227], v[8:11]
	v_mfma_f32_16x16x32_bf16 v[4:7], v[208:211], v[216:219], v[4:7]
	v_mfma_f32_16x16x32_bf16 v[0:3], v[208:211], v[224:227], v[0:3]
	s_barrier
	s_setprio 0
	ds_read_b128 v[158:161], v145
	ds_read_b128 v[162:165], v145 offset:1024
	ds_read_b128 v[166:169], v145 offset:2048
	ds_read_b128 v[170:173], v145 offset:3072
	s_mov_b32 m0, s100
	ds_read_b128 v[174:177], v137 offset:32768
	ds_read_b128 v[178:181], v137 offset:33792
	ds_read_b128 v[182:185], v136 offset:32768
	ds_read_b128 v[186:189], v136 offset:33792
	ds_read_b128 v[190:193], v135 offset:32768
	ds_read_b128 v[196:199], v135 offset:33792
	ds_read_b128 v[200:203], v133 offset:32768
	ds_read_b128 v[208:211], v133 offset:33792
	global_load_lds_dwordx4 v[248:249], off
	s_mov_b32 m0, s101
	s_nop 0
	global_load_lds_dwordx4 v[250:251], off
	s_waitcnt lgkmcnt(8)
	s_setprio 1
	s_barrier
	s_waitcnt lgkmcnt(0)
	v_mfma_f32_16x16x32_bf16 v[124:127], v[174:177], v[158:161], v[124:127]
	v_mfma_f32_16x16x32_bf16 v[120:123], v[174:177], v[166:169], v[120:123]
	v_mfma_f32_16x16x32_bf16 v[116:119], v[182:185], v[158:161], v[116:119]
	v_mfma_f32_16x16x32_bf16 v[112:115], v[182:185], v[166:169], v[112:115]
	v_mfma_f32_16x16x32_bf16 v[108:111], v[190:193], v[158:161], v[108:111]
	v_mfma_f32_16x16x32_bf16 v[104:107], v[190:193], v[166:169], v[104:107]
	v_mfma_f32_16x16x32_bf16 v[100:103], v[200:203], v[158:161], v[100:103]
	v_mfma_f32_16x16x32_bf16 v[96:99], v[200:203], v[166:169], v[96:99]
	v_mfma_f32_16x16x32_bf16 v[124:127], v[178:181], v[162:165], v[124:127]
	v_mfma_f32_16x16x32_bf16 v[120:123], v[178:181], v[170:173], v[120:123]
	v_mfma_f32_16x16x32_bf16 v[116:119], v[186:189], v[162:165], v[116:119]
	v_mfma_f32_16x16x32_bf16 v[112:115], v[186:189], v[170:173], v[112:115]
	v_mfma_f32_16x16x32_bf16 v[108:111], v[196:199], v[162:165], v[108:111]
	v_mfma_f32_16x16x32_bf16 v[104:107], v[196:199], v[170:173], v[104:107]
	v_mfma_f32_16x16x32_bf16 v[100:103], v[208:211], v[162:165], v[100:103]
	v_mfma_f32_16x16x32_bf16 v[96:99], v[208:211], v[170:173], v[96:99]
	s_barrier
	s_setprio 0
	s_mov_b64 s[84:85], 0x4c00180
	v_lshl_add_u64 v[230:231], v[228:229], 0, s[84:85]
	v_readfirstlane_b32 s84, v146
	s_mov_b32 m0, s84
	v_readfirstlane_b32 s84, v147
	ds_read_b128 v[212:215], v142
	ds_read_b128 v[216:219], v142 offset:1024
	ds_read_b128 v[220:223], v142 offset:2048
	ds_read_b128 v[224:227], v142 offset:3072
	global_load_lds_dwordx4 v[230:231], off
	v_lshl_add_u64 v[230:231], v[228:229], 0, s[10:11]
	s_mov_b32 m0, s84
	s_nop 0
	global_load_lds_dwordx4 v[230:231], off
	v_lshl_add_u64 v[252:253], v[204:205], 0, s[12:13]
	v_lshl_add_u64 v[230:231], v[204:205], 0, s[12:13]
	v_lshl_add_u64 v[254:255], v[204:205], 0, s[14:15]
	v_lshl_add_u64 v[204:205], v[204:205], 0, s[14:15]
	v_readfirstlane_b32 s84, v148
	s_mov_b32 m0, s84
	s_setprio 1
	s_barrier
	s_waitcnt lgkmcnt(0)
	v_mfma_f32_16x16x32_bf16 v[92:95], v[174:177], v[212:215], v[92:95]
	v_mfma_f32_16x16x32_bf16 v[88:91], v[174:177], v[220:223], v[88:91]
	v_mfma_f32_16x16x32_bf16 v[84:87], v[182:185], v[212:215], v[84:87]
	v_mfma_f32_16x16x32_bf16 v[80:83], v[182:185], v[220:223], v[80:83]
	v_mfma_f32_16x16x32_bf16 v[76:79], v[190:193], v[212:215], v[76:79]
	v_mfma_f32_16x16x32_bf16 v[72:75], v[190:193], v[220:223], v[72:75]
	v_mfma_f32_16x16x32_bf16 v[68:71], v[200:203], v[212:215], v[68:71]
	v_mfma_f32_16x16x32_bf16 v[64:67], v[200:203], v[220:223], v[64:67]
	v_mfma_f32_16x16x32_bf16 v[92:95], v[178:181], v[216:219], v[92:95]
	v_mfma_f32_16x16x32_bf16 v[88:91], v[178:181], v[224:227], v[88:91]
	v_mfma_f32_16x16x32_bf16 v[84:87], v[186:189], v[216:219], v[84:87]
	v_mfma_f32_16x16x32_bf16 v[80:83], v[186:189], v[224:227], v[80:83]
	v_mfma_f32_16x16x32_bf16 v[76:79], v[196:199], v[216:219], v[76:79]
	v_mfma_f32_16x16x32_bf16 v[72:75], v[196:199], v[224:227], v[72:75]
	v_mfma_f32_16x16x32_bf16 v[68:71], v[208:211], v[216:219], v[68:71]
	v_mfma_f32_16x16x32_bf16 v[64:67], v[208:211], v[224:227], v[64:67]
	s_barrier
; #define WAIT_V(n) asm volatile("s_waitcnt vmcnt(" #n ")" ::: "memory")
; #define WAIT_L(n) asm volatile("s_waitcnt lgkmcnt(" #n ")" ::: "memory")
; #define BAR __builtin_amdgcn_s_barrier()
; #define SCHED __builtin_amdgcn_sched_barrier(0)
; template <int EPI>
; __device__ __forceinline__ void gemm_tile(const Params& p, const bf16* __restrict__ A, const bf16* __restrict__ Bt, const int K,
;                                           const int nt, const int brow, const int bcol, int pm, int pn) {
;     ...
;   for (int t = 0; t < nt - 2; t += 2) {
;     LDB(B0, 0, 0); SCHED; LDA(At, 0, 0); STAGE(SA(1, 1), A, brow + HALF, t + 1);
;     WAIT_L(8); BAR; WAIT_L(0); MMA(0, 0, At, B0); BAR; SCHED;
;     LDB(B1, 0, 1); STAGE(SB(0, 0), Bt, bcol, t + 2);
;     BAR; WAIT_L(0); MMA(0, 1, At, B1); BAR;
;     LDA(At, 0, 1); STAGE(SA(0, 0), A, brow, t + 2);
;     BAR; WAIT_L(0); MMA(1, 0, At, B0); BAR; SCHED;
;     STAGE(SB(0, 1), Bt, bcol + HALF, t + 2);
;     WAIT_V(6); BAR; MMA(1, 1, At, B1); BAR;
;     LDB(B0, 1, 0); SCHED; LDA(At, 1, 0); STAGE(SA(0, 1), A, brow + HALF, t + 2);
;     WAIT_L(8); BAR; WAIT_L(0); MMA(0, 0, At, B0); BAR; SCHED;
;     LDB(B1, 1, 1); STAGE(SB(1, 0), Bt, bcol, t + 3);
;     BAR; WAIT_L(0); MMA(0, 1, At, B1); BAR;
;     LDA(At, 1, 1); STAGE(SA(1, 0), A, brow, t + 3);
;     BAR; WAIT_L(0); MMA(1, 0, At, B0); BAR; SCHED;
;     STAGE(SB(1, 1), Bt, bcol + HALF, t + 3);
;     WAIT_V(6); BAR; MMA(1, 1, At, B1); BAR;
;   }
;   { LDB(B0, 0, 0); LDA(At, 0, 0); STAGE(SA(1, 1), A, brow + HALF, nt - 1);
;     BAR; WAIT_L(0); MMA(0, 0, At, B0); BAR;
;     LDB(B1, 0, 1); BAR; WAIT_L(0); MMA(0, 1, At, B1); BAR;
;     LDA(At, 0, 1); WAIT_V(4); BAR; WAIT_L(0); MMA(1, 0, At, B0); MMA(1, 1, At, B1); BAR; }
	s_setprio 0
	ds_read_b128 v[174:177], v137 offset:49152
	ds_read_b128 v[178:181], v137 offset:50176
	ds_read_b128 v[182:185], v136 offset:49152
	ds_read_b128 v[186:189], v136 offset:50176
	ds_read_b128 v[190:193], v135 offset:49152
	ds_read_b128 v[196:199], v135 offset:50176
	ds_read_b128 v[200:203], v133 offset:49152
	ds_read_b128 v[208:211], v133 offset:50176
	global_load_lds_dwordx4 v[252:253], off
	v_readfirstlane_b32 s84, v149
	s_mov_b32 m0, s84
	s_nop 0
	global_load_lds_dwordx4 v[254:255], off
	s_setprio 1
	s_barrier
	s_waitcnt lgkmcnt(0)
	v_mfma_f32_16x16x32_bf16 v[60:63], v[174:177], v[158:161], v[60:63]
	v_mfma_f32_16x16x32_bf16 v[56:59], v[174:177], v[166:169], v[56:59]
	v_mfma_f32_16x16x32_bf16 v[52:55], v[182:185], v[158:161], v[52:55]
	v_mfma_f32_16x16x32_bf16 v[48:51], v[182:185], v[166:169], v[48:51]
	v_mfma_f32_16x16x32_bf16 v[44:47], v[190:193], v[158:161], v[44:47]
	v_mfma_f32_16x16x32_bf16 v[40:43], v[190:193], v[166:169], v[40:43]
	v_mfma_f32_16x16x32_bf16 v[36:39], v[200:203], v[158:161], v[36:39]
	v_mfma_f32_16x16x32_bf16 v[32:35], v[200:203], v[166:169], v[32:35]
	v_mfma_f32_16x16x32_bf16 v[60:63], v[178:181], v[162:165], v[60:63]
	v_mfma_f32_16x16x32_bf16 v[56:59], v[178:181], v[170:173], v[56:59]
	v_mfma_f32_16x16x32_bf16 v[52:55], v[186:189], v[162:165], v[52:55]
	v_mfma_f32_16x16x32_bf16 v[48:51], v[186:189], v[170:173], v[48:51]
	v_mfma_f32_16x16x32_bf16 v[44:47], v[196:199], v[162:165], v[44:47]
	v_mfma_f32_16x16x32_bf16 v[40:43], v[196:199], v[170:173], v[40:43]
	v_mfma_f32_16x16x32_bf16 v[36:39], v[208:211], v[162:165], v[36:39]
	v_mfma_f32_16x16x32_bf16 v[32:35], v[208:211], v[170:173], v[32:35]
	s_barrier
	s_setprio 0
	v_readfirstlane_b32 s84, v150
	v_lshl_add_u64 v[158:159], v[228:229], 0, s[16:17]
	s_mov_b32 m0, s84
	v_readfirstlane_b32 s84, v152
	global_load_lds_dwordx4 v[158:159], off
	v_lshl_add_u64 v[158:159], v[228:229], 0, s[18:19]
	s_mov_b32 m0, s84
	s_nop 0
	global_load_lds_dwordx4 v[158:159], off
	v_lshl_add_u64 v[204:205], s[70:71], 0, v[130:131]
	s_mov_b64 s[84:85], 0x12662080
	v_lshl_add_u64 v[246:247], v[204:205], 0, s[84:85]
	s_mov_b64 s[84:85], 0x12712080
	v_lshl_add_u64 v[244:245], v[204:205], 0, s[84:85]
	s_waitcnt vmcnt(6)
	s_setprio 1
	s_barrier
	v_mfma_f32_16x16x32_bf16 v[28:31], v[174:177], v[212:215], v[28:31]
	v_mfma_f32_16x16x32_bf16 v[24:27], v[174:177], v[220:223], v[24:27]
	v_mfma_f32_16x16x32_bf16 v[20:23], v[182:185], v[212:215], v[20:23]
	v_mfma_f32_16x16x32_bf16 v[16:19], v[182:185], v[220:223], v[16:19]
	v_mfma_f32_16x16x32_bf16 v[12:15], v[190:193], v[212:215], v[12:15]
	v_mfma_f32_16x16x32_bf16 v[8:11], v[190:193], v[220:223], v[8:11]
	v_mfma_f32_16x16x32_bf16 v[4:7], v[200:203], v[212:215], v[4:7]
	v_mfma_f32_16x16x32_bf16 v[0:3], v[200:203], v[220:223], v[0:3]
	v_mfma_f32_16x16x32_bf16 v[28:31], v[178:181], v[216:219], v[28:31]
	v_mfma_f32_16x16x32_bf16 v[24:27], v[178:181], v[224:227], v[24:27]
	v_mfma_f32_16x16x32_bf16 v[20:23], v[186:189], v[216:219], v[20:23]
	v_mfma_f32_16x16x32_bf16 v[16:19], v[186:189], v[224:227], v[16:19]
	v_mfma_f32_16x16x32_bf16 v[12:15], v[196:199], v[216:219], v[12:15]
	v_mfma_f32_16x16x32_bf16 v[8:11], v[196:199], v[224:227], v[8:11]
	v_mfma_f32_16x16x32_bf16 v[4:7], v[208:211], v[216:219], v[4:7]
	v_mfma_f32_16x16x32_bf16 v[0:3], v[208:211], v[224:227], v[0:3]
	s_barrier
	s_setprio 0
	s_cmpk_lt_u32 s88, 0x54
	s_cbranch_scc1 .LBB0_1704
	s_add_u32 s68, s62, s87
	s_addc_u32 s69, s63, s86
	v_lshl_add_u64 v[130:131], s[68:69], 0, v[128:129]
	v_readfirstlane_b32 s68, v154
	s_mov_b32 m0, s68
	s_add_u32 s68, s62, s79
	v_lshl_add_u64 v[130:131], v[130:131], 0, s[20:21]
	s_addc_u32 s69, s63, s78
	ds_read_b128 v[138:141], v155
	ds_read_b128 v[146:149], v155 offset:1024
	ds_read_b128 v[158:161], v155 offset:2048
	ds_read_b128 v[162:165], v155 offset:3072
	ds_read_b128 v[166:169], v137
	ds_read_b128 v[170:173], v137 offset:1024
	ds_read_b128 v[174:177], v136
	ds_read_b128 v[178:181], v136 offset:1024
	ds_read_b128 v[182:185], v135
	ds_read_b128 v[186:189], v135 offset:1024
	ds_read_b128 v[190:193], v133
	ds_read_b128 v[196:199], v133 offset:1024
	global_load_lds_dwordx4 v[130:131], off
	v_lshl_add_u64 v[130:131], s[68:69], 0, v[128:129]
	v_readfirstlane_b32 s68, v153
	v_lshl_add_u64 v[130:131], v[130:131], 0, s[20:21]
	s_mov_b32 m0, s68
	s_nop 0
	global_load_lds_dwordx4 v[130:131], off
	s_setprio 1
	s_barrier
	s_waitcnt lgkmcnt(0)
	v_mfma_f32_16x16x32_bf16 v[124:127], v[166:169], v[138:141], v[124:127]
	v_mfma_f32_16x16x32_bf16 v[120:123], v[166:169], v[158:161], v[120:123]
	v_mfma_f32_16x16x32_bf16 v[116:119], v[174:177], v[138:141], v[116:119]
	v_mfma_f32_16x16x32_bf16 v[108:111], v[182:185], v[138:141], v[108:111]
	v_mfma_f32_16x16x32_bf16 v[124:127], v[170:173], v[146:149], v[124:127]
	v_mfma_f32_16x16x32_bf16 v[120:123], v[170:173], v[162:165], v[120:123]
	v_mfma_f32_16x16x32_bf16 v[116:119], v[178:181], v[146:149], v[116:119]
	v_mfma_f32_16x16x32_bf16 v[112:115], v[174:177], v[158:161], v[112:115]
	v_mfma_f32_16x16x32_bf16 v[108:111], v[186:189], v[146:149], v[108:111]
	v_mfma_f32_16x16x32_bf16 v[104:107], v[182:185], v[158:161], v[104:107]
	v_mfma_f32_16x16x32_bf16 v[100:103], v[190:193], v[138:141], v[100:103]
	v_mfma_f32_16x16x32_bf16 v[96:99], v[190:193], v[158:161], v[96:99]
	v_mfma_f32_16x16x32_bf16 v[152:155], v[178:181], v[162:165], v[112:115]
	v_mfma_f32_16x16x32_bf16 v[200:203], v[186:189], v[162:165], v[104:107]
	v_mfma_f32_16x16x32_bf16 v[208:211], v[196:199], v[146:149], v[100:103]
	v_mfma_f32_16x16x32_bf16 v[212:215], v[196:199], v[162:165], v[96:99]
	s_barrier
; #define WAIT_V(n) asm volatile("s_waitcnt vmcnt(" #n ")" ::: "memory")
; #define WAIT_L(n) asm volatile("s_waitcnt lgkmcnt(" #n ")" ::: "memory")
; #define BAR __builtin_amdgcn_s_barrier()
; template <int EPI>
; __device__ __forceinline__ void gemm_tile(const Params& p, const bf16* __restrict__ A, const bf16* __restrict__ Bt, const int K,
;                                           const int nt, const int brow, const int bcol, int pm, int pn) {
;     ...
;   { LDB(B0, 0, 0); LDA(At, 0, 0); STAGE(SA(1, 1), A, brow + HALF, nt - 1);
;     BAR; WAIT_L(0); MMA(0, 0, At, B0); BAR;
;     LDB(B1, 0, 1); BAR; WAIT_L(0); MMA(0, 1, At, B1); BAR;
;     LDA(At, 0, 1); WAIT_V(4); BAR; WAIT_L(0); MMA(1, 0, At, B0); MMA(1, 1, At, B1); BAR; }
;   { LDB(B0, 1, 0); LDA(At, 1, 0); WAIT_V(2); BAR; WAIT_L(0); MMA(0, 0, At, B0); BAR;
;     LDB(B1, 1, 1); WAIT_V(0); BAR; WAIT_L(0); MMA(0, 1, At, B1); BAR;
;     LDA(At, 1, 1); BAR; WAIT_L(0); MMA(1, 0, At, B0); MMA(1, 1, At, B1); BAR; }
	s_setprio 0
	s_nop 1
	ds_read_b128 v[96:99], v151
	ds_read_b128 v[100:103], v151 offset:1024
	ds_read_b128 v[104:107], v151 offset:2048
	ds_read_b128 v[112:115], v151 offset:3072
	s_setprio 1
	s_barrier
	s_waitcnt lgkmcnt(0)
	v_mfma_f32_16x16x32_bf16 v[92:95], v[166:169], v[96:99], v[92:95]
	v_mfma_f32_16x16x32_bf16 v[88:91], v[166:169], v[104:107], v[88:91]
	v_mfma_f32_16x16x32_bf16 v[84:87], v[174:177], v[96:99], v[84:87]
	v_mfma_f32_16x16x32_bf16 v[76:79], v[182:185], v[96:99], v[76:79]
	v_mfma_f32_16x16x32_bf16 v[92:95], v[170:173], v[100:103], v[92:95]
	v_mfma_f32_16x16x32_bf16 v[88:91], v[170:173], v[112:115], v[88:91]
	v_mfma_f32_16x16x32_bf16 v[84:87], v[178:181], v[100:103], v[84:87]
	v_mfma_f32_16x16x32_bf16 v[80:83], v[174:177], v[104:107], v[80:83]
	v_mfma_f32_16x16x32_bf16 v[76:79], v[186:189], v[100:103], v[76:79]
	v_mfma_f32_16x16x32_bf16 v[72:75], v[182:185], v[104:107], v[72:75]
	v_mfma_f32_16x16x32_bf16 v[68:71], v[190:193], v[96:99], v[68:71]
	v_mfma_f32_16x16x32_bf16 v[64:67], v[190:193], v[104:107], v[64:67]
	v_mfma_f32_16x16x32_bf16 v[166:169], v[178:181], v[112:115], v[80:83]
	v_mfma_f32_16x16x32_bf16 v[170:173], v[186:189], v[112:115], v[72:75]
	v_mfma_f32_16x16x32_bf16 v[174:177], v[196:199], v[100:103], v[68:71]
	v_mfma_f32_16x16x32_bf16 v[178:181], v[196:199], v[112:115], v[64:67]
	s_barrier
	s_setprio 0
	s_nop 1
	ds_read_b128 v[64:67], v137 offset:16384
	ds_read_b128 v[68:71], v137 offset:17408
	ds_read_b128 v[72:75], v136 offset:16384
	ds_read_b128 v[80:83], v136 offset:17408
	ds_read_b128 v[182:185], v135 offset:16384
	ds_read_b128 v[186:189], v135 offset:17408
	ds_read_b128 v[190:193], v133 offset:16384
	ds_read_b128 v[196:199], v133 offset:17408
	s_waitcnt vmcnt(4)
	s_setprio 1
	s_barrier
	s_waitcnt lgkmcnt(0)
	v_mfma_f32_16x16x32_bf16 v[60:63], v[64:67], v[138:141], v[60:63]
	v_mfma_f32_16x16x32_bf16 v[56:59], v[64:67], v[158:161], v[56:59]
	v_mfma_f32_16x16x32_bf16 v[52:55], v[72:75], v[138:141], v[52:55]
	v_mfma_f32_16x16x32_bf16 v[44:47], v[182:185], v[138:141], v[44:47]
	v_mfma_f32_16x16x32_bf16 v[60:63], v[68:71], v[146:149], v[60:63]
	v_mfma_f32_16x16x32_bf16 v[56:59], v[68:71], v[162:165], v[56:59]
	v_mfma_f32_16x16x32_bf16 v[52:55], v[80:83], v[146:149], v[52:55]
	v_mfma_f32_16x16x32_bf16 v[48:51], v[72:75], v[158:161], v[48:51]
	v_mfma_f32_16x16x32_bf16 v[44:47], v[186:189], v[146:149], v[44:47]
	v_mfma_f32_16x16x32_bf16 v[40:43], v[182:185], v[158:161], v[40:43]
	v_mfma_f32_16x16x32_bf16 v[36:39], v[190:193], v[138:141], v[36:39]
	v_mfma_f32_16x16x32_bf16 v[32:35], v[190:193], v[158:161], v[32:35]
	v_mfma_f32_16x16x32_bf16 v[216:219], v[80:83], v[162:165], v[48:51]
	v_mfma_f32_16x16x32_bf16 v[220:223], v[186:189], v[162:165], v[40:43]
	v_mfma_f32_16x16x32_bf16 v[138:141], v[196:199], v[146:149], v[36:39]
	v_mfma_f32_16x16x32_bf16 v[146:149], v[196:199], v[162:165], v[32:35]
	s_setprio 0
	s_setprio 1
	v_mfma_f32_16x16x32_bf16 v[28:31], v[64:67], v[96:99], v[28:31]
	v_mfma_f32_16x16x32_bf16 v[24:27], v[64:67], v[104:107], v[24:27]
	v_mfma_f32_16x16x32_bf16 v[20:23], v[72:75], v[96:99], v[20:23]
	v_mfma_f32_16x16x32_bf16 v[12:15], v[182:185], v[96:99], v[12:15]
	v_mfma_f32_16x16x32_bf16 v[28:31], v[68:71], v[100:103], v[28:31]
	v_mfma_f32_16x16x32_bf16 v[24:27], v[68:71], v[112:115], v[24:27]
	v_mfma_f32_16x16x32_bf16 v[20:23], v[80:83], v[100:103], v[20:23]
	v_mfma_f32_16x16x32_bf16 v[16:19], v[72:75], v[104:107], v[16:19]
	v_mfma_f32_16x16x32_bf16 v[12:15], v[186:189], v[100:103], v[12:15]
	v_mfma_f32_16x16x32_bf16 v[8:11], v[182:185], v[104:107], v[8:11]
	v_mfma_f32_16x16x32_bf16 v[4:7], v[190:193], v[96:99], v[4:7]
	v_mfma_f32_16x16x32_bf16 v[0:3], v[190:193], v[104:107], v[0:3]
	v_mfma_f32_16x16x32_bf16 v[158:161], v[80:83], v[112:115], v[16:19]
	v_mfma_f32_16x16x32_bf16 v[162:165], v[186:189], v[112:115], v[8:11]
	v_mfma_f32_16x16x32_bf16 v[182:185], v[196:199], v[100:103], v[4:7]
	v_mfma_f32_16x16x32_bf16 v[186:189], v[196:199], v[112:115], v[0:3]
	s_barrier
	s_setprio 0
	s_nop 1
	ds_read_b128 v[0:3], v145
	ds_read_b128 v[4:7], v145 offset:1024
	ds_read_b128 v[8:11], v145 offset:2048
	ds_read_b128 v[16:19], v145 offset:3072
	ds_read_b128 v[32:35], v137 offset:32768
	ds_read_b128 v[36:39], v137 offset:33792
	ds_read_b128 v[40:43], v136 offset:32768
	ds_read_b128 v[48:51], v136 offset:33792
	ds_read_b128 v[190:193], v135 offset:32768
	ds_read_b128 v[196:199], v135 offset:33792
	ds_read_b128 v[224:227], v133 offset:32768
	ds_read_b128 v[228:231], v133 offset:33792
	s_waitcnt vmcnt(2)
	s_setprio 1
	s_barrier
; #define WAIT_V(n) asm volatile("s_waitcnt vmcnt(" #n ")" ::: "memory")
; #define WAIT_L(n) asm volatile("s_waitcnt lgkmcnt(" #n ")" ::: "memory")
; #define BAR __builtin_amdgcn_s_barrier()
; template <int EPI>
; __device__ __forceinline__ void gemm_tile(const Params& p, const bf16* __restrict__ A, const bf16* __restrict__ Bt, const int K,
;                                           const int nt, const int brow, const int bcol, int pm, int pn) {
;     ...
;     LDA(At, 0, 1); WAIT_V(4); BAR; WAIT_L(0); MMA(1, 0, At, B0); MMA(1, 1, At, B1); BAR; }
;   { LDB(B0, 1, 0); LDA(At, 1, 0); WAIT_V(2); BAR; WAIT_L(0); MMA(0, 0, At, B0); BAR;
;     LDB(B1, 1, 1); WAIT_V(0); BAR; WAIT_L(0); MMA(0, 1, At, B1); BAR;
;     LDA(At, 1, 1); BAR; WAIT_L(0); MMA(1, 0, At, B0); MMA(1, 1, At, B1); BAR; }
;   if (wr == 0) BAR;
	s_waitcnt lgkmcnt(0)
	v_mfma_f32_16x16x32_bf16 v[64:67], v[32:35], v[0:3], v[124:127]
	v_mfma_f32_16x16x32_bf16 v[96:99], v[36:39], v[4:7], v[64:67]
	v_mfma_f32_16x16x32_bf16 v[64:67], v[32:35], v[8:11], v[120:123]
	v_mfma_f32_16x16x32_bf16 v[112:115], v[36:39], v[16:19], v[64:67]
	v_mfma_f32_16x16x32_bf16 v[64:67], v[40:43], v[0:3], v[116:119]
	v_mfma_f32_16x16x32_bf16 v[100:103], v[48:51], v[4:7], v[64:67]
	v_mfma_f32_16x16x32_bf16 v[64:67], v[40:43], v[8:11], v[152:155]
	v_mfma_f32_16x16x32_bf16 v[116:119], v[48:51], v[16:19], v[64:67]
	v_mfma_f32_16x16x32_bf16 v[64:67], v[190:193], v[0:3], v[108:111]
	v_mfma_f32_16x16x32_bf16 v[104:107], v[196:199], v[4:7], v[64:67]
	v_mfma_f32_16x16x32_bf16 v[64:67], v[190:193], v[8:11], v[200:203]
	v_mfma_f32_16x16x32_bf16 v[120:123], v[196:199], v[16:19], v[64:67]
	v_mfma_f32_16x16x32_bf16 v[64:67], v[224:227], v[0:3], v[208:211]
	v_mfma_f32_16x16x32_bf16 v[108:111], v[228:231], v[4:7], v[64:67]
	v_mfma_f32_16x16x32_bf16 v[64:67], v[224:227], v[8:11], v[212:215]
	v_mfma_f32_16x16x32_bf16 v[124:127], v[228:231], v[16:19], v[64:67]
	s_barrier
	s_setprio 0
	ds_read_b128 v[150:153], v142
	ds_read_b128 v[200:203], v142 offset:1024
	ds_read_b128 v[208:211], v142 offset:2048
	ds_read_b128 v[142:145], v142 offset:3072
	s_waitcnt vmcnt(0)
	s_setprio 1
	s_barrier
	s_waitcnt lgkmcnt(0)
	v_mfma_f32_16x16x32_bf16 v[64:67], v[32:35], v[150:153], v[92:95]
	v_mfma_f32_16x16x32_bf16 v[32:35], v[32:35], v[208:211], v[88:91]
	v_mfma_f32_16x16x32_bf16 v[80:83], v[36:39], v[142:145], v[32:35]
	v_mfma_f32_16x16x32_bf16 v[32:35], v[40:43], v[150:153], v[84:87]
	v_mfma_f32_16x16x32_bf16 v[68:71], v[48:51], v[200:203], v[32:35]
	v_mfma_f32_16x16x32_bf16 v[32:35], v[40:43], v[208:211], v[166:169]
	v_mfma_f32_16x16x32_bf16 v[84:87], v[48:51], v[142:145], v[32:35]
	v_mfma_f32_16x16x32_bf16 v[32:35], v[190:193], v[150:153], v[76:79]
	v_mfma_f32_16x16x32_bf16 v[72:75], v[196:199], v[200:203], v[32:35]
	v_mfma_f32_16x16x32_bf16 v[32:35], v[190:193], v[208:211], v[170:173]
	v_mfma_f32_16x16x32_bf16 v[88:91], v[196:199], v[142:145], v[32:35]
	v_mfma_f32_16x16x32_bf16 v[32:35], v[224:227], v[150:153], v[174:177]
	v_mfma_f32_16x16x32_bf16 v[76:79], v[228:231], v[200:203], v[32:35]
	v_mfma_f32_16x16x32_bf16 v[32:35], v[224:227], v[208:211], v[178:181]
	v_mfma_f32_16x16x32_bf16 v[64:67], v[36:39], v[200:203], v[64:67]
	v_mfma_f32_16x16x32_bf16 v[92:95], v[228:231], v[142:145], v[32:35]
	s_barrier
	s_setprio 0
	ds_read_b128 v[166:169], v137 offset:49152
	ds_read_b128 v[170:173], v137 offset:50176
	ds_read_b128 v[174:177], v136 offset:49152
	ds_read_b128 v[178:181], v136 offset:50176
	ds_read_b128 v[190:193], v135 offset:49152
	ds_read_b128 v[134:137], v135 offset:50176
	ds_read_b128 v[196:199], v133 offset:49152
	ds_read_b128 v[130:133], v133 offset:50176
	s_setprio 1
	s_barrier
	s_waitcnt lgkmcnt(0)
	v_mfma_f32_16x16x32_bf16 v[36:39], v[166:169], v[8:11], v[56:59]
	v_mfma_f32_16x16x32_bf16 v[40:43], v[174:177], v[8:11], v[216:219]
	v_mfma_f32_16x16x32_bf16 v[32:35], v[166:169], v[0:3], v[60:63]
	v_mfma_f32_16x16x32_bf16 v[48:51], v[170:173], v[16:19], v[36:39]
	v_mfma_f32_16x16x32_bf16 v[36:39], v[174:177], v[0:3], v[52:55]
	v_mfma_f32_16x16x32_bf16 v[52:55], v[178:181], v[16:19], v[40:43]
	v_mfma_f32_16x16x32_bf16 v[40:43], v[190:193], v[0:3], v[44:47]
	v_mfma_f32_16x16x32_bf16 v[44:47], v[190:193], v[8:11], v[220:223]
	v_mfma_f32_16x16x32_bf16 v[0:3], v[196:199], v[0:3], v[138:141]
	v_mfma_f32_16x16x32_bf16 v[56:59], v[134:137], v[16:19], v[44:47]
	v_mfma_f32_16x16x32_bf16 v[44:47], v[130:133], v[4:7], v[0:3]
	v_mfma_f32_16x16x32_bf16 v[0:3], v[196:199], v[8:11], v[146:149]
	v_mfma_f32_16x16x32_bf16 v[32:35], v[170:173], v[4:7], v[32:35]
	v_mfma_f32_16x16x32_bf16 v[36:39], v[178:181], v[4:7], v[36:39]
	v_mfma_f32_16x16x32_bf16 v[40:43], v[134:137], v[4:7], v[40:43]
	v_mfma_f32_16x16x32_bf16 v[60:63], v[130:133], v[16:19], v[0:3]
	s_setprio 0
	s_setprio 1
	v_mfma_f32_16x16x32_bf16 v[4:7], v[166:169], v[208:211], v[24:27]
	v_mfma_f32_16x16x32_bf16 v[8:11], v[174:177], v[208:211], v[158:161]
	v_mfma_f32_16x16x32_bf16 v[16:19], v[170:173], v[142:145], v[4:7]
	v_mfma_f32_16x16x32_bf16 v[4:7], v[174:177], v[150:153], v[20:23]
	v_mfma_f32_16x16x32_bf16 v[20:23], v[178:181], v[142:145], v[8:11]
	v_mfma_f32_16x16x32_bf16 v[8:11], v[190:193], v[150:153], v[12:15]
	v_mfma_f32_16x16x32_bf16 v[12:15], v[190:193], v[208:211], v[162:165]
	v_mfma_f32_16x16x32_bf16 v[0:3], v[166:169], v[150:153], v[28:31]
	v_mfma_f32_16x16x32_bf16 v[24:27], v[134:137], v[142:145], v[12:15]
	v_mfma_f32_16x16x32_bf16 v[12:15], v[196:199], v[150:153], v[182:185]
	v_mfma_f32_16x16x32_bf16 v[28:31], v[196:199], v[208:211], v[186:189]
	v_mfma_f32_16x16x32_bf16 v[0:3], v[170:173], v[200:203], v[0:3]
	v_mfma_f32_16x16x32_bf16 v[4:7], v[178:181], v[200:203], v[4:7]
	v_mfma_f32_16x16x32_bf16 v[8:11], v[134:137], v[200:203], v[8:11]
	v_mfma_f32_16x16x32_bf16 v[12:15], v[130:133], v[200:203], v[12:15]
	v_mfma_f32_16x16x32_bf16 v[28:31], v[130:133], v[142:145], v[28:31]
	s_barrier
	s_setprio 0
	s_cmpk_gt_u32 s77, 0xff
	s_cbranch_scc1 .LBB0_1696
	s_barrier
	s_branch .LBB0_1696

; __global__ void __launch_bounds__(512, 2) fwd_megakernel(Params p) {
;   if (p.use_cg) cg::this_grid().sync();
;     ...
;   phase_prep(p);
;   xcd_barrier(xb);
;   if (blockIdx.x >= 24 && (blockIdx.x & 1)) convert_w_o_gu(p, 24, gridDim.x - 24);
;   if (blockIdx.x < 24) gemm_tile<EPI_PROJ>(p, P_HBUF(p), P_WINT(p), DM, DM / BK, SEQ, blockIdx.x * BM, 64, blockIdx.x);
;   gemm_phase<EPI_PROJ>(p, P_HBUF(p), P_WINT(p), DM, 64, 24);
;   if (blockIdx.x >= 24 && !(blockIdx.x & 1)) convert_w_o_gu(p, 24, gridDim.x - 24);
;   xcd_barrier(xb);
;   phase_mixer(p);
;   xcd_barrier(xb);
;   gemm_phase<EPI_WO>(p, P_MIX(p), P_WOT(p), DM, 65, 8);
;   if (blockIdx.x >= 8) convert_w_down(p, 8, gridDim.x - 8);
;   xcd_barrier(xb);
;   gemm_phase<EPI_GU>(p, P_HBUF(p), P_WGUT(p), DM, 66, 44);
;   xcd_barrier(xb);
;   if (blockIdx.x < 8 * DSK) {
;     const int pn = blockIdx.x / DSK, ks = blockIdx.x % DSK;
;     gemm_tile<EPI_DOWN_ATOMIC>(p, P_ACT(p) + ks * 512, P_WDT(p) + ks * 512, DFF, 512 / BK, SEQ, pn * BM, 64 + ks, pn);
;   }
;   gemm_phase<EPI_DOWN>(p, P_ACT(p), P_WDT(p), DFF, 64, 8);
;   xcd_barrier(xb);
;   phase_final(p);
; }
	.amdhsa_kernel _Z14fwd_megakernel6Params
		.amdhsa_group_segment_fixed_size 16
		.amdhsa_private_segment_fixed_size 0
		.amdhsa_kernarg_size 416
		.amdhsa_user_sgpr_count 2
		.amdhsa_user_sgpr_dispatch_ptr 0
		.amdhsa_user_sgpr_queue_ptr 0
		.amdhsa_user_sgpr_kernarg_segment_ptr 1
		.amdhsa_user_sgpr_dispatch_id 0
		.amdhsa_user_sgpr_kernarg_preload_length 0
		.amdhsa_user_sgpr_kernarg_preload_offset 0
		.amdhsa_user_sgpr_private_segment_size 0
		.amdhsa_uses_dynamic_stack 0
		.amdhsa_enable_private_segment 0
		.amdhsa_system_sgpr_workgroup_id_x 1
		.amdhsa_system_sgpr_workgroup_id_y 0
		.amdhsa_system_sgpr_workgroup_id_z 0
		.amdhsa_system_sgpr_workgroup_info 0
		.amdhsa_system_vgpr_workitem_id 2
		.amdhsa_next_free_vgpr 256
		.amdhsa_next_free_sgpr 102
		.amdhsa_accum_offset 256
		.amdhsa_reserve_vcc 1
		.amdhsa_float_round_mode_32 0
		.amdhsa_float_round_mode_16_64 0
		.amdhsa_float_denorm_mode_32 3
		.amdhsa_float_denorm_mode_16_64 3
		.amdhsa_dx10_clamp 1
		.amdhsa_ieee_mode 1
		.amdhsa_fp16_overflow 0
		.amdhsa_tg_split 0
		.amdhsa_exception_fp_ieee_invalid_op 0
		.amdhsa_exception_fp_denorm_src 0
		.amdhsa_exception_fp_ieee_div_zero 0
		.amdhsa_exception_fp_ieee_overflow 0
		.amdhsa_exception_fp_ieee_underflow 0
		.amdhsa_exception_fp_ieee_inexact 0
		.amdhsa_exception_int_div_zero 0
	.end_amdhsa_kernel

; __global__ void __launch_bounds__(512, 2) fwd_megakernel(Params p) {
amdhsa.kernels:
  - .agpr_count:     0
    .args:
      - .offset:         0
        .size:           160
        .value_kind:     by_value
      - .offset:         160
        .size:           4
        .value_kind:     hidden_block_count_x
      - .offset:         164
        .size:           4
        .value_kind:     hidden_block_count_y
      - .offset:         168
        .size:           4
        .value_kind:     hidden_block_count_z
      - .offset:         172
        .size:           2
        .value_kind:     hidden_group_size_x
      - .offset:         174
        .size:           2
        .value_kind:     hidden_group_size_y
      - .offset:         176
        .size:           2
        .value_kind:     hidden_group_size_z
      - .offset:         178
        .size:           2
        .value_kind:     hidden_remainder_x
      - .offset:         180
        .size:           2
        .value_kind:     hidden_remainder_y
      - .offset:         182
        .size:           2
        .value_kind:     hidden_remainder_z
      - .offset:         200
        .size:           8
        .value_kind:     hidden_global_offset_x
      - .offset:         208
        .size:           8
        .value_kind:     hidden_global_offset_y
      - .offset:         216
        .size:           8
        .value_kind:     hidden_global_offset_z
      - .offset:         224
        .size:           2
        .value_kind:     hidden_grid_dims
      - .offset:         248
        .size:           8
        .value_kind:     hidden_multigrid_sync_arg
      - .offset:         280
        .size:           4
        .value_kind:     hidden_dynamic_lds_size
    .group_segment_fixed_size: 16
    .kernarg_segment_align: 8
    .kernarg_segment_size: 416
    .language:       OpenCL C
    .language_version:
      - 2
      - 0
    .max_flat_workgroup_size: 512
    .name:           _Z14fwd_megakernel6Params
    .private_segment_fixed_size: 0
    .sgpr_count:     108
    .sgpr_spill_count: 8
    .symbol:         _Z14fwd_megakernel6Params.kd
    .uniform_work_group_size: 1
    .uses_dynamic_stack: false
    .vgpr_count:     256
    .vgpr_spill_count: 0
    .wavefront_size: 64
